# dn_chunk_prep triangular solve: A[i][j] broadcast via LDS ds_read_b128 (4 columns per read, prefetched 8 groups ahead) instead of per-element v_readlane to SGPR; same FMA order
# speedup vs baseline: 1.0117x; 1.0117x over previous
.LBB0_654:
	s_andn2_saveexec_b64 s[0:1], s[2:3]
	s_cbranch_execz .LBB0_660
	v_cmp_lt_i32_e64 s[40:41], 63, v74
	ds_read2st64_b32 v[72:73], v77 offset0:109 offset1:110
	ds_read2st64_b32 v[70:71], v77 offset0:111 offset1:112
	ds_read2st64_b32 v[68:69], v77 offset0:113 offset1:114
	ds_read2st64_b32 v[66:67], v77 offset0:115 offset1:116
	ds_read2st64_b32 v[64:65], v77 offset0:117 offset1:118
	ds_read2st64_b32 v[62:63], v77 offset0:119 offset1:120
	ds_read2st64_b32 v[60:61], v77 offset0:121 offset1:122
	ds_read2st64_b32 v[58:59], v77 offset0:123 offset1:124
	ds_read2st64_b32 v[56:57], v77 offset0:125 offset1:126
	ds_read2st64_b32 v[54:55], v77 offset0:127 offset1:128
	ds_read2st64_b32 v[52:53], v77 offset0:129 offset1:130
	ds_read2st64_b32 v[50:51], v77 offset0:131 offset1:132
	ds_read2st64_b32 v[48:49], v77 offset0:133 offset1:134
	ds_read2st64_b32 v[46:47], v77 offset0:135 offset1:136
	ds_read2st64_b32 v[44:45], v77 offset0:137 offset1:138
	ds_read2st64_b32 v[42:43], v77 offset0:139 offset1:140
	ds_read2st64_b32 v[40:41], v77 offset0:141 offset1:142
	ds_read2st64_b32 v[38:39], v77 offset0:143 offset1:144
	ds_read2st64_b32 v[36:37], v77 offset0:145 offset1:146
	ds_read2st64_b32 v[34:35], v77 offset0:147 offset1:148
	ds_read2st64_b32 v[32:33], v77 offset0:149 offset1:150
	ds_read2st64_b32 v[30:31], v77 offset0:151 offset1:152
	ds_read2st64_b32 v[28:29], v77 offset0:153 offset1:154
	ds_read2st64_b32 v[26:27], v77 offset0:155 offset1:156
	ds_read2st64_b32 v[24:25], v77 offset0:157 offset1:158
	ds_read2st64_b32 v[22:23], v77 offset0:159 offset1:160
	ds_read2st64_b32 v[20:21], v77 offset0:161 offset1:162
	ds_read2st64_b32 v[18:19], v77 offset0:163 offset1:164
	ds_read2st64_b32 v[16:17], v77 offset0:165 offset1:166
	ds_read2st64_b32 v[14:15], v77 offset0:167 offset1:168
	ds_read2st64_b32 v[12:13], v77 offset0:169 offset1:170
	ds_read_b32 v80, v77 offset:43776
	ds_read_b128 v[202:205], v137 offset:27904
	ds_read_b128 v[206:209], v137 offset:28160
	ds_read_b128 v[210:213], v137 offset:28416
	ds_read_b128 v[214:217], v137 offset:28672
	ds_read_b128 v[218:221], v137 offset:28928
	ds_read_b128 v[222:225], v137 offset:28944
	ds_read_b128 v[226:229], v137 offset:29184
	ds_read_b128 v[230:233], v137 offset:29200
	v_cndmask_b32_e64 v0, v194, v192, s[40:41]
	v_lshlrev_b32_e32 v77, 1, v75
	v_or_b32_e32 v82, v0, v77
	ds_read_u16 v0, v82
	ds_read_b128 v[84:87], v137 offset:60672
	s_waitcnt lgkmcnt(14)
	v_cmp_gt_i32_e64 s[38:39], 64, v74
	s_waitcnt lgkmcnt(1)
	v_lshlrev_b32_e32 v0, 16, v0
	s_waitcnt lgkmcnt(0)
	v_mul_f32_e32 v79, v84, v0
	ds_read_b128 v[88:91], v137 offset:60416
	ds_read_b128 v[8:11], v137 offset:60432
	ds_read_b128 v[4:7], v137 offset:60448
	ds_read_b128 v[0:3], v137 offset:60464
	ds_read_u16 v83, v82 offset:144
	s_waitcnt lgkmcnt(4)
	v_mul_f32_e32 v84, 0x3fb8aa3b, v89
	v_exp_f32_e32 v84, v84
	s_waitcnt lgkmcnt(3)
	v_mul_f32_e32 v8, 0x3fb8aa3b, v8
	v_exp_f32_e32 v8, v8
	s_waitcnt lgkmcnt(0)
	v_lshlrev_b32_e32 v83, 16, v83
	v_mul_f32_e32 v83, v85, v83
	v_mul_f32_e32 v84, v83, v84
	v_cndmask_b32_e64 v105, v83, v84, s[40:41]
	ds_read_u16 v83, v82 offset:288
	v_mul_f32_e32 v84, 0x3fb8aa3b, v90
	v_exp_f32_e32 v84, v84
	v_mul_f32_e32 v9, 0x3fb8aa3b, v9
	v_exp_f32_e32 v9, v9
	s_waitcnt lgkmcnt(0)
	v_lshlrev_b32_e32 v83, 16, v83
	v_mul_f32_e32 v83, v86, v83
	v_mul_f32_e32 v84, v83, v84
	v_cndmask_b32_e64 v106, v83, v84, s[40:41]
	ds_read_u16 v83, v82 offset:432
	v_mul_f32_e32 v84, 0x3fb8aa3b, v91
	v_exp_f32_e32 v84, v84
	v_mul_f32_e32 v10, 0x3fb8aa3b, v10
	v_exp_f32_e32 v10, v10
	s_waitcnt lgkmcnt(0)
	v_lshlrev_b32_e32 v83, 16, v83
	v_mul_f32_e32 v83, v87, v83
	v_mul_f32_e32 v84, v83, v84
	v_cndmask_b32_e64 v109, v83, v84, s[40:41]
	ds_read_u16 v83, v82 offset:576
	ds_read_b128 v[84:87], v137 offset:60688
	v_mul_f32_e32 v11, 0x3fb8aa3b, v11
	v_exp_f32_e32 v11, v11
	v_mul_f32_e32 v4, 0x3fb8aa3b, v4
	s_waitcnt lgkmcnt(1)
	v_lshlrev_b32_e32 v83, 16, v83
	s_waitcnt lgkmcnt(0)
	v_mul_f32_e32 v83, v84, v83
	v_mul_f32_e32 v8, v83, v8
	v_cndmask_b32_e64 v8, v83, v8, s[40:41]
	ds_read_u16 v83, v82 offset:720
	v_exp_f32_e32 v4, v4
	v_mul_f32_e32 v5, 0x3fb8aa3b, v5
	v_exp_f32_e32 v5, v5
	v_mul_f32_e32 v0, 0x3fb8aa3b, v0
	s_waitcnt lgkmcnt(0)
	v_lshlrev_b32_e32 v83, 16, v83
	v_mul_f32_e32 v83, v85, v83
	v_mul_f32_e32 v9, v83, v9
	v_cndmask_b32_e64 v9, v83, v9, s[40:41]
	ds_read_u16 v83, v82 offset:864
	v_exp_f32_e32 v0, v0
	v_mul_f32_e32 v1, 0x3fb8aa3b, v1
	v_exp_f32_e32 v1, v1
	v_mul_f32_e32 v78, 0x3fb8aa3b, v88
	s_waitcnt lgkmcnt(0)
	v_lshlrev_b32_e32 v83, 16, v83
	v_mul_f32_e32 v83, v86, v83
	v_mul_f32_e32 v10, v83, v10
	v_cndmask_b32_e64 v10, v83, v10, s[40:41]
	ds_read_u16 v83, v82 offset:1008
	v_exp_f32_e32 v78, v78
	s_waitcnt lgkmcnt(0)
	v_lshlrev_b32_e32 v83, 16, v83
	v_mul_f32_e32 v83, v87, v83
	v_mul_f32_e32 v11, v83, v11
	v_cndmask_b32_e64 v11, v83, v11, s[40:41]
	ds_read_u16 v83, v82 offset:1152
	ds_read_b128 v[84:87], v137 offset:60704
	v_mul_f32_e32 v78, v79, v78
	v_cndmask_b32_e64 v81, v79, v78, s[40:41]
	s_waitcnt lgkmcnt(1)
	v_lshlrev_b32_e32 v83, 16, v83
	s_waitcnt lgkmcnt(0)
	v_mul_f32_e32 v83, v84, v83
	v_mul_f32_e32 v4, v83, v4
	v_cndmask_b32_e64 v116, v83, v4, s[40:41]
	ds_read_u16 v4, v82 offset:1296
	s_waitcnt lgkmcnt(0)
	v_lshlrev_b32_e32 v4, 16, v4
	v_mul_f32_e32 v4, v85, v4
	v_mul_f32_e32 v5, v4, v5
	v_cndmask_b32_e64 v117, v4, v5, s[40:41]
	ds_read_u16 v4, v82 offset:1440
	v_mul_f32_e32 v5, 0x3fb8aa3b, v6
	v_exp_f32_e32 v5, v5
	s_waitcnt lgkmcnt(0)
	v_lshlrev_b32_e32 v4, 16, v4
	v_mul_f32_e32 v4, v86, v4
	v_mul_f32_e32 v5, v4, v5
	v_cndmask_b32_e64 v120, v4, v5, s[40:41]
	ds_read_u16 v4, v82 offset:1584
	v_mul_f32_e32 v5, 0x3fb8aa3b, v7
	v_exp_f32_e32 v5, v5
	s_waitcnt lgkmcnt(0)
	v_lshlrev_b32_e32 v4, 16, v4
	v_mul_f32_e32 v4, v87, v4
	v_mul_f32_e32 v5, v4, v5
	v_cndmask_b32_e64 v121, v4, v5, s[40:41]
	ds_read_u16 v4, v82 offset:1728
	s_waitcnt lgkmcnt(0)
	v_lshlrev_b32_e32 v83, 16, v4
	ds_read_b128 v[4:7], v137 offset:60720
	s_waitcnt lgkmcnt(0)
	v_mul_f32_e32 v4, v4, v83
	v_mul_f32_e32 v0, v4, v0
	v_cndmask_b32_e64 v122, v4, v0, s[40:41]
	ds_read_u16 v0, v82 offset:1872
	s_waitcnt lgkmcnt(0)
	v_lshlrev_b32_e32 v0, 16, v0
	v_mul_f32_e32 v0, v5, v0
	v_mul_f32_e32 v1, v0, v1
	v_cndmask_b32_e64 v123, v0, v1, s[40:41]
	ds_read_u16 v0, v82 offset:2016
	v_mul_f32_e32 v1, 0x3fb8aa3b, v2
	v_exp_f32_e32 v1, v1
	s_waitcnt lgkmcnt(0)
	v_lshlrev_b32_e32 v0, 16, v0
	v_mul_f32_e32 v0, v6, v0
	v_mul_f32_e32 v1, v0, v1
	v_cndmask_b32_e64 v124, v0, v1, s[40:41]
	ds_read_u16 v0, v82 offset:2160
	v_mul_f32_e32 v1, 0x3fb8aa3b, v3
	v_exp_f32_e32 v1, v1
	s_waitcnt lgkmcnt(0)
	v_lshlrev_b32_e32 v0, 16, v0
	v_mul_f32_e32 v0, v7, v0
	v_mul_f32_e32 v1, v0, v1
	v_cndmask_b32_e64 v143, v0, v1, s[40:41]
	ds_read_u16 v0, v82 offset:2304
	s_waitcnt lgkmcnt(0)
	v_lshlrev_b32_e32 v4, 16, v0
	ds_read_b128 v[0:3], v137 offset:60736
	s_waitcnt lgkmcnt(0)
	v_mul_f32_e32 v0, v0, v4
	ds_read_b128 v[4:7], v137 offset:60480
	s_waitcnt lgkmcnt(0)
	v_mul_f32_e32 v4, 0x3fb8aa3b, v4
	v_exp_f32_e32 v4, v4
	s_nop 0
	v_mul_f32_e32 v4, v0, v4
	v_cndmask_b32_e64 v145, v0, v4, s[40:41]
	ds_read_u16 v0, v82 offset:2448
	s_waitcnt lgkmcnt(0)
	v_lshlrev_b32_e32 v0, 16, v0
	v_mul_f32_e32 v0, v1, v0
	v_mul_f32_e32 v1, 0x3fb8aa3b, v5
	v_exp_f32_e32 v1, v1
	s_nop 0
	v_mul_f32_e32 v1, v0, v1
	v_cndmask_b32_e64 v133, v0, v1, s[40:41]
	ds_read_u16 v0, v82 offset:2592
	v_mul_f32_e32 v1, 0x3fb8aa3b, v6
	v_exp_f32_e32 v1, v1
	s_waitcnt lgkmcnt(0)
	v_lshlrev_b32_e32 v0, 16, v0
	v_mul_f32_e32 v0, v2, v0
	v_mul_f32_e32 v1, v0, v1
	v_cndmask_b32_e64 v129, v0, v1, s[40:41]
	ds_read_u16 v0, v82 offset:2736
	v_mul_f32_e32 v1, 0x3fb8aa3b, v7
	v_exp_f32_e32 v1, v1
	s_waitcnt lgkmcnt(0)
	v_lshlrev_b32_e32 v0, 16, v0
	v_mul_f32_e32 v0, v3, v0
	v_mul_f32_e32 v1, v0, v1
	v_cndmask_b32_e64 v125, v0, v1, s[40:41]
	ds_read_u16 v0, v82 offset:2880
	s_waitcnt lgkmcnt(0)
	v_lshlrev_b32_e32 v4, 16, v0
	ds_read_b128 v[0:3], v137 offset:60752
	s_waitcnt lgkmcnt(0)
	v_mul_f32_e32 v0, v0, v4
	ds_read_b128 v[4:7], v137 offset:60496
	s_waitcnt lgkmcnt(0)
	v_mul_f32_e32 v4, 0x3fb8aa3b, v4
	v_exp_f32_e32 v4, v4
	s_nop 0
	v_mul_f32_e32 v4, v0, v4
	v_cndmask_b32_e64 v136, v0, v4, s[40:41]
	ds_read_u16 v0, v82 offset:3024
	s_waitcnt lgkmcnt(0)
	v_lshlrev_b32_e32 v0, 16, v0
	v_mul_f32_e32 v0, v1, v0
	v_mul_f32_e32 v1, 0x3fb8aa3b, v5
	v_exp_f32_e32 v1, v1
	s_nop 0
	v_mul_f32_e32 v1, v0, v1
	v_cndmask_b32_e64 v134, v0, v1, s[40:41]
	ds_read_u16 v0, v82 offset:3168
	v_mul_f32_e32 v1, 0x3fb8aa3b, v6
	v_exp_f32_e32 v1, v1
	s_waitcnt lgkmcnt(0)
	v_lshlrev_b32_e32 v0, 16, v0
	v_mul_f32_e32 v0, v2, v0
	v_mul_f32_e32 v1, v0, v1
	v_cndmask_b32_e64 v132, v0, v1, s[40:41]
	ds_read_u16 v0, v82 offset:3312
	v_mul_f32_e32 v1, 0x3fb8aa3b, v7
	v_exp_f32_e32 v1, v1
	s_waitcnt lgkmcnt(0)
	v_lshlrev_b32_e32 v0, 16, v0
	v_mul_f32_e32 v0, v3, v0
	v_mul_f32_e32 v1, v0, v1
	v_cndmask_b32_e64 v147, v0, v1, s[40:41]
	ds_read_u16 v0, v82 offset:3456
	s_waitcnt lgkmcnt(0)
	v_lshlrev_b32_e32 v4, 16, v0
	ds_read_b128 v[0:3], v137 offset:60768
	s_waitcnt lgkmcnt(0)
	v_mul_f32_e32 v0, v0, v4
	ds_read_b128 v[4:7], v137 offset:60512
	s_waitcnt lgkmcnt(0)
	v_mul_f32_e32 v4, 0x3fb8aa3b, v4
	v_exp_f32_e32 v4, v4
	s_nop 0
	v_mul_f32_e32 v4, v0, v4
	v_cndmask_b32_e64 v146, v0, v4, s[40:41]
	ds_read_u16 v0, v82 offset:3600
	s_waitcnt lgkmcnt(0)
	v_lshlrev_b32_e32 v0, 16, v0
	v_mul_f32_e32 v0, v1, v0
	v_mul_f32_e32 v1, 0x3fb8aa3b, v5
	v_exp_f32_e32 v1, v1
	s_nop 0
	v_mul_f32_e32 v1, v0, v1
	v_cndmask_b32_e64 v135, v0, v1, s[40:41]
	ds_read_u16 v0, v82 offset:3744
	v_mul_f32_e32 v1, 0x3fb8aa3b, v6
	v_exp_f32_e32 v1, v1
	s_waitcnt lgkmcnt(0)
	v_lshlrev_b32_e32 v0, 16, v0
	v_mul_f32_e32 v0, v2, v0
	v_mul_f32_e32 v1, v0, v1
	v_cndmask_b32_e64 v128, v0, v1, s[40:41]
	ds_read_u16 v0, v82 offset:3888
	v_mul_f32_e32 v1, 0x3fb8aa3b, v7
	v_exp_f32_e32 v1, v1
	s_waitcnt lgkmcnt(0)
	v_lshlrev_b32_e32 v0, 16, v0
	v_mul_f32_e32 v0, v3, v0
	v_mul_f32_e32 v1, v0, v1
	v_cndmask_b32_e64 v118, v0, v1, s[40:41]
	ds_read_u16 v0, v82 offset:4032
	s_waitcnt lgkmcnt(0)
	v_lshlrev_b32_e32 v4, 16, v0
	ds_read_b128 v[0:3], v137 offset:60784
	s_waitcnt lgkmcnt(0)
	v_mul_f32_e32 v0, v0, v4
	ds_read_b128 v[4:7], v137 offset:60528
	s_waitcnt lgkmcnt(0)
	v_mul_f32_e32 v4, 0x3fb8aa3b, v4
	v_exp_f32_e32 v4, v4
	s_nop 0
	v_mul_f32_e32 v4, v0, v4
	v_cndmask_b32_e64 v130, v0, v4, s[40:41]
	ds_read_u16 v0, v82 offset:4176
	s_waitcnt lgkmcnt(0)
	v_lshlrev_b32_e32 v0, 16, v0
	v_mul_f32_e32 v0, v1, v0
	v_mul_f32_e32 v1, 0x3fb8aa3b, v5
	v_exp_f32_e32 v1, v1
	s_nop 0
	v_mul_f32_e32 v1, v0, v1
	v_cndmask_b32_e64 v127, v0, v1, s[40:41]
	ds_read_u16 v0, v82 offset:4320
	v_mul_f32_e32 v1, 0x3fb8aa3b, v6
	v_exp_f32_e32 v1, v1
	s_waitcnt lgkmcnt(0)
	v_lshlrev_b32_e32 v0, 16, v0
	v_mul_f32_e32 v0, v2, v0
	v_mul_f32_e32 v1, v0, v1
	v_cndmask_b32_e64 v119, v0, v1, s[40:41]
	ds_read_u16 v0, v82 offset:4464
	v_mul_f32_e32 v1, 0x3fb8aa3b, v7
	v_exp_f32_e32 v1, v1
	s_waitcnt lgkmcnt(0)
	v_lshlrev_b32_e32 v0, 16, v0
	v_mul_f32_e32 v0, v3, v0
	v_mul_f32_e32 v1, v0, v1
	v_cndmask_b32_e64 v131, v0, v1, s[40:41]
	ds_read_u16 v0, v82 offset:4608
	s_waitcnt lgkmcnt(0)
	v_lshlrev_b32_e32 v4, 16, v0
	ds_read_b128 v[0:3], v137 offset:60800
	s_waitcnt lgkmcnt(0)
	v_mul_f32_e32 v0, v0, v4
	ds_read_b128 v[4:7], v137 offset:60544
	s_waitcnt lgkmcnt(0)
	v_mul_f32_e32 v4, 0x3fb8aa3b, v4
	v_exp_f32_e32 v4, v4
	s_nop 0
	v_mul_f32_e32 v4, v0, v4
	v_cndmask_b32_e64 v126, v0, v4, s[40:41]
	ds_read_u16 v0, v82 offset:4752
	s_waitcnt lgkmcnt(0)
	v_lshlrev_b32_e32 v0, 16, v0
	v_mul_f32_e32 v0, v1, v0
	v_mul_f32_e32 v1, 0x3fb8aa3b, v5
	v_exp_f32_e32 v1, v1
	s_nop 0
	v_mul_f32_e32 v1, v0, v1
	v_cndmask_b32_e64 v115, v0, v1, s[40:41]
	ds_read_u16 v0, v82 offset:4896
	v_mul_f32_e32 v1, 0x3fb8aa3b, v6
	v_exp_f32_e32 v1, v1
	s_waitcnt lgkmcnt(0)
	v_lshlrev_b32_e32 v0, 16, v0
	v_mul_f32_e32 v0, v2, v0
	v_mul_f32_e32 v1, v0, v1
	v_cndmask_b32_e64 v114, v0, v1, s[40:41]
	ds_read_u16 v0, v82 offset:5040
	v_mul_f32_e32 v1, 0x3fb8aa3b, v7
	v_exp_f32_e32 v1, v1
	s_waitcnt lgkmcnt(0)
	v_lshlrev_b32_e32 v0, 16, v0
	v_mul_f32_e32 v0, v3, v0
	v_mul_f32_e32 v1, v0, v1
	v_cndmask_b32_e64 v111, v0, v1, s[40:41]
	ds_read_u16 v0, v82 offset:5184
	s_waitcnt lgkmcnt(0)
	v_lshlrev_b32_e32 v4, 16, v0
	ds_read_b128 v[0:3], v137 offset:60816
	s_waitcnt lgkmcnt(0)
	v_mul_f32_e32 v0, v0, v4
	ds_read_b128 v[4:7], v137 offset:60560
	s_waitcnt lgkmcnt(0)
	v_mul_f32_e32 v4, 0x3fb8aa3b, v4
	v_exp_f32_e32 v4, v4
	s_nop 0
	v_mul_f32_e32 v4, v0, v4
	v_cndmask_b32_e64 v113, v0, v4, s[40:41]
	ds_read_u16 v0, v82 offset:5328
	s_waitcnt lgkmcnt(0)
	v_lshlrev_b32_e32 v0, 16, v0
	v_mul_f32_e32 v0, v1, v0
	v_mul_f32_e32 v1, 0x3fb8aa3b, v5
	v_exp_f32_e32 v1, v1
	s_nop 0
	v_mul_f32_e32 v1, v0, v1
	v_cndmask_b32_e64 v112, v0, v1, s[40:41]
	ds_read_u16 v0, v82 offset:5472
	v_mul_f32_e32 v1, 0x3fb8aa3b, v6
	v_exp_f32_e32 v1, v1
	s_waitcnt lgkmcnt(0)
	v_lshlrev_b32_e32 v0, 16, v0
	v_mul_f32_e32 v0, v2, v0
	v_mul_f32_e32 v1, v0, v1
	v_cndmask_b32_e64 v108, v0, v1, s[40:41]
	ds_read_u16 v0, v82 offset:5616
	v_mul_f32_e32 v1, 0x3fb8aa3b, v7
	v_exp_f32_e32 v1, v1
	s_waitcnt lgkmcnt(0)
	v_lshlrev_b32_e32 v0, 16, v0
	v_mul_f32_e32 v0, v3, v0
	v_mul_f32_e32 v1, v0, v1
	v_cndmask_b32_e64 v110, v0, v1, s[40:41]
	ds_read_u16 v0, v82 offset:5760
	s_waitcnt lgkmcnt(0)
	v_lshlrev_b32_e32 v4, 16, v0
	ds_read_b128 v[0:3], v137 offset:60832
	s_waitcnt lgkmcnt(0)
	v_mul_f32_e32 v0, v0, v4
	ds_read_b128 v[4:7], v137 offset:60576
	s_waitcnt lgkmcnt(0)
	v_mul_f32_e32 v4, 0x3fb8aa3b, v4
	v_exp_f32_e32 v4, v4
	s_nop 0
	v_mul_f32_e32 v4, v0, v4
	v_cndmask_b32_e64 v107, v0, v4, s[40:41]
	ds_read_u16 v0, v82 offset:5904
	s_waitcnt lgkmcnt(0)
	v_lshlrev_b32_e32 v0, 16, v0
	v_mul_f32_e32 v0, v1, v0
	v_mul_f32_e32 v1, 0x3fb8aa3b, v5
	v_exp_f32_e32 v1, v1
	s_nop 0
	v_mul_f32_e32 v1, v0, v1
	v_cndmask_b32_e64 v104, v0, v1, s[40:41]
	ds_read_u16 v0, v82 offset:6048
	v_mul_f32_e32 v1, 0x3fb8aa3b, v6
	v_exp_f32_e32 v1, v1
	s_waitcnt lgkmcnt(0)
	v_lshlrev_b32_e32 v0, 16, v0
	v_mul_f32_e32 v0, v2, v0
	v_mul_f32_e32 v1, v0, v1
	v_cndmask_b32_e64 v103, v0, v1, s[40:41]
	ds_read_u16 v0, v82 offset:6192
	v_mul_f32_e32 v1, 0x3fb8aa3b, v7
	v_exp_f32_e32 v1, v1
	s_waitcnt lgkmcnt(0)
	v_lshlrev_b32_e32 v0, 16, v0
	v_mul_f32_e32 v0, v3, v0
	v_mul_f32_e32 v1, v0, v1
	v_cndmask_b32_e64 v101, v0, v1, s[40:41]
	ds_read_u16 v0, v82 offset:6336
	s_waitcnt lgkmcnt(0)
	v_lshlrev_b32_e32 v4, 16, v0
	ds_read_b128 v[0:3], v137 offset:60848
	s_waitcnt lgkmcnt(0)
	v_mul_f32_e32 v0, v0, v4
	ds_read_b128 v[4:7], v137 offset:60592
	s_waitcnt lgkmcnt(0)
	v_mul_f32_e32 v4, 0x3fb8aa3b, v4
	v_exp_f32_e32 v4, v4
	s_nop 0
	v_mul_f32_e32 v4, v0, v4
	v_cndmask_b32_e64 v102, v0, v4, s[40:41]
	ds_read_u16 v0, v82 offset:6480
	s_waitcnt lgkmcnt(0)
	v_lshlrev_b32_e32 v0, 16, v0
	v_mul_f32_e32 v0, v1, v0
	v_mul_f32_e32 v1, 0x3fb8aa3b, v5
	v_exp_f32_e32 v1, v1
	s_nop 0
	v_mul_f32_e32 v1, v0, v1
	v_cndmask_b32_e64 v100, v0, v1, s[40:41]
	ds_read_u16 v0, v82 offset:6624
	v_mul_f32_e32 v1, 0x3fb8aa3b, v6
	v_exp_f32_e32 v1, v1
	s_waitcnt lgkmcnt(0)
	v_lshlrev_b32_e32 v0, 16, v0
	v_mul_f32_e32 v0, v2, v0
	v_mul_f32_e32 v1, v0, v1
	v_cndmask_b32_e64 v98, v0, v1, s[40:41]
	ds_read_u16 v0, v82 offset:6768
	v_mul_f32_e32 v1, 0x3fb8aa3b, v7
	v_exp_f32_e32 v1, v1
	s_waitcnt lgkmcnt(0)
	v_lshlrev_b32_e32 v0, 16, v0
	v_mul_f32_e32 v0, v3, v0
	v_mul_f32_e32 v1, v0, v1
	v_cndmask_b32_e64 v99, v0, v1, s[40:41]
	ds_read_u16 v0, v82 offset:6912
	s_waitcnt lgkmcnt(0)
	v_lshlrev_b32_e32 v4, 16, v0
	ds_read_b128 v[0:3], v137 offset:60864
	s_waitcnt lgkmcnt(0)
	v_mul_f32_e32 v0, v0, v4
	ds_read_b128 v[4:7], v137 offset:60608
	s_waitcnt lgkmcnt(0)
	v_mul_f32_e32 v4, 0x3fb8aa3b, v4
	v_exp_f32_e32 v4, v4
	s_nop 0
	v_mul_f32_e32 v4, v0, v4
	v_cndmask_b32_e64 v97, v0, v4, s[40:41]
	ds_read_u16 v0, v82 offset:7056
	s_waitcnt lgkmcnt(0)
	v_lshlrev_b32_e32 v0, 16, v0
	v_mul_f32_e32 v0, v1, v0
	v_mul_f32_e32 v1, 0x3fb8aa3b, v5
	v_exp_f32_e32 v1, v1
	s_nop 0
	v_mul_f32_e32 v1, v0, v1
	v_cndmask_b32_e64 v96, v0, v1, s[40:41]
	ds_read_u16 v0, v82 offset:7200
	v_mul_f32_e32 v1, 0x3fb8aa3b, v6
	v_exp_f32_e32 v1, v1
	s_waitcnt lgkmcnt(0)
	v_lshlrev_b32_e32 v0, 16, v0
	v_mul_f32_e32 v0, v2, v0
	v_mul_f32_e32 v1, v0, v1
	v_cndmask_b32_e64 v95, v0, v1, s[40:41]
	ds_read_u16 v0, v82 offset:7344
	v_mul_f32_e32 v1, 0x3fb8aa3b, v7
	v_exp_f32_e32 v1, v1
	s_waitcnt lgkmcnt(0)
	v_lshlrev_b32_e32 v0, 16, v0
	v_mul_f32_e32 v0, v3, v0
	v_mul_f32_e32 v1, v0, v1
	v_cndmask_b32_e64 v93, v0, v1, s[40:41]
	ds_read_u16 v0, v82 offset:7488
	s_waitcnt lgkmcnt(0)
	v_lshlrev_b32_e32 v4, 16, v0
	ds_read_b128 v[0:3], v137 offset:60880
	s_waitcnt lgkmcnt(0)
	v_mul_f32_e32 v0, v0, v4
	ds_read_b128 v[4:7], v137 offset:60624
	s_waitcnt lgkmcnt(0)
	v_mul_f32_e32 v4, 0x3fb8aa3b, v4
	v_exp_f32_e32 v4, v4
	s_nop 0
	v_mul_f32_e32 v4, v0, v4
	v_cndmask_b32_e64 v94, v0, v4, s[40:41]
	ds_read_u16 v0, v82 offset:7632
	s_waitcnt lgkmcnt(0)
	v_lshlrev_b32_e32 v0, 16, v0
	v_mul_f32_e32 v0, v1, v0
	v_mul_f32_e32 v1, 0x3fb8aa3b, v5
	v_exp_f32_e32 v1, v1
	s_nop 0
	v_mul_f32_e32 v1, v0, v1
	v_cndmask_b32_e64 v92, v0, v1, s[40:41]
	ds_read_u16 v0, v82 offset:7776
	v_mul_f32_e32 v1, 0x3fb8aa3b, v6
	v_exp_f32_e32 v1, v1
	s_waitcnt lgkmcnt(0)
	v_lshlrev_b32_e32 v0, 16, v0
	v_mul_f32_e32 v0, v2, v0
	v_mul_f32_e32 v1, v0, v1
	v_cndmask_b32_e64 v90, v0, v1, s[40:41]
	ds_read_u16 v0, v82 offset:7920
	v_mul_f32_e32 v1, 0x3fb8aa3b, v7
	v_exp_f32_e32 v1, v1
	s_waitcnt lgkmcnt(0)
	v_lshlrev_b32_e32 v0, 16, v0
	v_mul_f32_e32 v0, v3, v0
	v_mul_f32_e32 v1, v0, v1
	v_cndmask_b32_e64 v91, v0, v1, s[40:41]
	ds_read_u16 v0, v82 offset:8064
	s_waitcnt lgkmcnt(0)
	v_lshlrev_b32_e32 v4, 16, v0
	ds_read_b128 v[0:3], v137 offset:60896
	s_waitcnt lgkmcnt(0)
	v_mul_f32_e32 v0, v0, v4
	ds_read_b128 v[4:7], v137 offset:60640
	s_waitcnt lgkmcnt(0)
	v_mul_f32_e32 v4, 0x3fb8aa3b, v4
	v_exp_f32_e32 v4, v4
	s_nop 0
	v_mul_f32_e32 v4, v0, v4
	v_cndmask_b32_e64 v89, v0, v4, s[40:41]
	ds_read_u16 v0, v82 offset:8208
	s_waitcnt lgkmcnt(0)
	v_lshlrev_b32_e32 v0, 16, v0
	v_mul_f32_e32 v0, v1, v0
	v_mul_f32_e32 v1, 0x3fb8aa3b, v5
	v_exp_f32_e32 v1, v1
	s_nop 0
	v_mul_f32_e32 v1, v0, v1
	v_cndmask_b32_e64 v88, v0, v1, s[40:41]
	ds_read_u16 v0, v82 offset:8352
	v_mul_f32_e32 v1, 0x3fb8aa3b, v6
	v_exp_f32_e32 v1, v1
	s_waitcnt lgkmcnt(0)
	v_lshlrev_b32_e32 v0, 16, v0
	v_mul_f32_e32 v0, v2, v0
	v_mul_f32_e32 v1, v0, v1
	v_cndmask_b32_e64 v87, v0, v1, s[40:41]
	ds_read_u16 v0, v82 offset:8496
	v_mul_f32_e32 v1, 0x3fb8aa3b, v7
	v_exp_f32_e32 v1, v1
	s_waitcnt lgkmcnt(0)
	v_lshlrev_b32_e32 v0, 16, v0
	v_mul_f32_e32 v0, v3, v0
	v_mul_f32_e32 v1, v0, v1
	v_cndmask_b32_e64 v86, v0, v1, s[40:41]
	ds_read_u16 v0, v82 offset:8640
	s_waitcnt lgkmcnt(0)
	v_lshlrev_b32_e32 v4, 16, v0
	ds_read_b128 v[0:3], v137 offset:60912
	s_waitcnt lgkmcnt(0)
	v_mul_f32_e32 v0, v0, v4
	ds_read_b128 v[4:7], v137 offset:60656
	s_waitcnt lgkmcnt(0)
	v_mul_f32_e32 v4, 0x3fb8aa3b, v4
	v_exp_f32_e32 v4, v4
	s_nop 0
	v_mul_f32_e32 v4, v0, v4
	v_cndmask_b32_e64 v85, v0, v4, s[40:41]
	ds_read_u16 v0, v82 offset:8784
	s_waitcnt lgkmcnt(0)
	v_lshlrev_b32_e32 v0, 16, v0
	v_mul_f32_e32 v0, v1, v0
	v_mul_f32_e32 v1, 0x3fb8aa3b, v5
	v_exp_f32_e32 v1, v1
	s_nop 0
	v_mul_f32_e32 v1, v0, v1
	v_cndmask_b32_e64 v84, v0, v1, s[40:41]
	ds_read_u16 v0, v82 offset:8928
	v_mul_f32_e32 v1, 0x3fb8aa3b, v6
	v_exp_f32_e32 v1, v1
	s_waitcnt lgkmcnt(0)
	v_lshlrev_b32_e32 v0, 16, v0
	v_mul_f32_e32 v0, v2, v0
	v_mul_f32_e32 v1, v0, v1
	v_cndmask_b32_e64 v83, v0, v1, s[40:41]
	ds_read_u16 v0, v82 offset:9072
	v_mul_f32_e32 v1, 0x3fb8aa3b, v7
	v_exp_f32_e32 v1, v1
	s_waitcnt lgkmcnt(0)
	v_lshlrev_b32_e32 v0, 16, v0
	v_mul_f32_e32 v0, v3, v0
	v_mul_f32_e32 v1, v0, v1
	v_cndmask_b32_e64 v82, v0, v1, s[40:41]
	ds_read_b128 v[234:237], v137 offset:29440
	s_waitcnt lgkmcnt(15)
	v_fma_f32 v0, -v81, v202, v105
	v_add_f32_e32 v0, 0, v0
	s_nop 0
	ds_read_b128 v[238:241], v137 offset:29456
	s_waitcnt lgkmcnt(15)
	v_fma_f32 v1, -v81, v206, v106
	v_fma_f32 v2, -v0, v207, 0
	v_add_f32_e32 v1, v1, v2
	s_nop 0
	ds_read_b128 v[248:251], v137 offset:29696
	s_waitcnt lgkmcnt(15)
	v_fma_f32 v2, -v81, v210, v109
	v_fma_f32 v3, -v0, v211, 0
	v_fma_f32 v2, -v1, v212, v2
	v_add_f32_e32 v2, v3, v2
	s_nop 0
	ds_read_b128 v[252:255], v137 offset:29712
	s_waitcnt lgkmcnt(15)
	v_fma_f32 v3, -v81, v214, v8
	v_fma_f32 v4, -v0, v215, 0
	v_fma_f32 v3, -v1, v216, v3
	v_fma_f32 v4, -v2, v217, v4
	v_add_f32_e32 v3, v3, v4
	s_nop 0
	ds_read_b128 v[202:205], v137 offset:29952
	s_waitcnt lgkmcnt(15)
	v_fma_f32 v4, -v81, v218, v9
	v_fma_f32 v5, -v0, v219, 0
	v_fma_f32 v4, -v1, v220, v4
	v_fma_f32 v5, -v2, v221, v5
	ds_read_b128 v[206:209], v137 offset:29968
	s_waitcnt lgkmcnt(15)
	v_fma_f32 v4, -v3, v222, v4
	v_add_f32_e32 v4, v5, v4
	s_nop 0
	ds_read_b128 v[210:213], v137 offset:29984
	s_waitcnt lgkmcnt(15)
	v_fma_f32 v5, -v81, v226, v10
	v_fma_f32 v6, -v0, v227, 0
	v_fma_f32 v5, -v1, v228, v5
	v_fma_f32 v6, -v2, v229, v6
	ds_read_b128 v[214:217], v137 offset:30208
	s_waitcnt lgkmcnt(15)
	v_fma_f32 v5, -v3, v230, v5
	v_fma_f32 v6, -v4, v231, v6
	v_add_f32_e32 v5, v5, v6
	s_nop 0
	ds_read_b128 v[218:221], v137 offset:30224
	s_waitcnt lgkmcnt(8)
	v_fma_f32 v6, -v81, v234, v11
	v_fma_f32 v7, -v0, v235, 0
	v_fma_f32 v6, -v1, v236, v6
	v_fma_f32 v7, -v2, v237, v7
	ds_read_b128 v[222:225], v137 offset:30240
	s_waitcnt lgkmcnt(8)
	v_fma_f32 v6, -v3, v238, v6
	v_fma_f32 v7, -v4, v239, v7
	v_fma_f32 v6, -v5, v240, v6
	v_add_f32_e32 v7, v7, v6
	s_nop 0
	ds_read_b128 v[226:229], v137 offset:30464
	s_waitcnt lgkmcnt(8)
	v_fma_f32 v6, -v81, v248, v116
	v_fma_f32 v8, -v0, v249, 0
	v_fma_f32 v6, -v1, v250, v6
	v_fma_f32 v8, -v2, v251, v8
	ds_read_b128 v[230:233], v137 offset:30480
	s_waitcnt lgkmcnt(8)
	v_fma_f32 v6, -v3, v252, v6
	v_fma_f32 v8, -v4, v253, v8
	v_fma_f32 v6, -v5, v254, v6
	v_fma_f32 v8, -v7, v255, v8
	v_add_f32_e32 v6, v6, v8
	s_nop 0
	ds_read_b128 v[234:237], v137 offset:30496
	s_waitcnt lgkmcnt(8)
	v_fma_f32 v8, -v81, v202, v117
	v_fma_f32 v9, -v0, v203, 0
	v_fma_f32 v8, -v1, v204, v8
	v_fma_f32 v9, -v2, v205, v9
	ds_read_b128 v[238:241], v137 offset:30720
	s_waitcnt lgkmcnt(8)
	v_fma_f32 v8, -v3, v206, v8
	v_fma_f32 v9, -v4, v207, v9
	v_fma_f32 v8, -v5, v208, v8
	v_fma_f32 v9, -v7, v209, v9
	ds_read_b128 v[248:251], v137 offset:30736
	s_waitcnt lgkmcnt(8)
	v_fma_f32 v8, -v6, v210, v8
	v_add_f32_e32 v8, v9, v8
	s_nop 0
	ds_read_b128 v[252:255], v137 offset:30752
	s_waitcnt lgkmcnt(8)
	v_fma_f32 v9, -v81, v214, v120
	v_fma_f32 v10, -v0, v215, 0
	v_fma_f32 v9, -v1, v216, v9
	v_fma_f32 v10, -v2, v217, v10
	ds_read_b128 v[202:205], v137 offset:30976
	s_waitcnt lgkmcnt(8)
	v_fma_f32 v9, -v3, v218, v9
	v_fma_f32 v10, -v4, v219, v10
	v_fma_f32 v9, -v5, v220, v9
	v_fma_f32 v10, -v7, v221, v10
	ds_read_b128 v[206:209], v137 offset:30992
	s_waitcnt lgkmcnt(8)
	v_fma_f32 v9, -v6, v222, v9
	v_fma_f32 v10, -v8, v223, v10
	v_add_f32_e32 v9, v9, v10
	s_nop 0
	ds_read_b128 v[210:213], v137 offset:31008
	s_waitcnt lgkmcnt(8)
	v_fma_f32 v10, -v81, v226, v121
	v_fma_f32 v11, -v0, v227, 0
	v_fma_f32 v10, -v1, v228, v10
	v_fma_f32 v11, -v2, v229, v11
	ds_read_b128 v[214:217], v137 offset:31024
	s_waitcnt lgkmcnt(8)
	v_fma_f32 v10, -v3, v230, v10
	v_fma_f32 v11, -v4, v231, v11
	v_fma_f32 v10, -v5, v232, v10
	v_fma_f32 v11, -v7, v233, v11
	ds_read_b128 v[218:221], v137 offset:31232
	s_waitcnt lgkmcnt(8)
	v_fma_f32 v10, -v6, v234, v10
	v_fma_f32 v11, -v8, v235, v11
	v_fma_f32 v10, -v9, v236, v10
	v_add_f32_e32 v10, v11, v10
	s_nop 0
	ds_read_b128 v[222:225], v137 offset:31248
	s_waitcnt lgkmcnt(8)
	v_fma_f32 v11, -v81, v238, v122
	v_fma_f32 v62, -v0, v239, 0
	v_fma_f32 v11, -v1, v240, v11
	v_fma_f32 v62, -v2, v241, v62
	ds_read_b128 v[226:229], v137 offset:31264
	s_waitcnt lgkmcnt(8)
	v_fma_f32 v11, -v3, v248, v11
	v_fma_f32 v62, -v4, v249, v62
	v_fma_f32 v11, -v5, v250, v11
	v_fma_f32 v62, -v7, v251, v62
	ds_read_b128 v[230:233], v137 offset:31280
	s_waitcnt lgkmcnt(8)
	v_fma_f32 v11, -v6, v252, v11
	v_fma_f32 v62, -v8, v253, v62
	v_fma_f32 v11, -v9, v254, v11
	v_fma_f32 v62, -v10, v255, v62
	v_add_f32_e32 v11, v11, v62
	s_nop 0
	ds_read_b128 v[234:237], v137 offset:31488
	s_waitcnt lgkmcnt(8)
	v_fma_f32 v62, -v81, v202, v123
	v_fma_f32 v63, -v0, v203, 0
	v_fma_f32 v62, -v1, v204, v62
	v_fma_f32 v63, -v2, v205, v63
	ds_read_b128 v[238:241], v137 offset:31504
	s_waitcnt lgkmcnt(8)
	v_fma_f32 v62, -v3, v206, v62
	v_fma_f32 v63, -v4, v207, v63
	v_fma_f32 v62, -v5, v208, v62
	v_fma_f32 v63, -v7, v209, v63
	ds_read_b128 v[248:251], v137 offset:31520
	s_waitcnt lgkmcnt(8)
	v_fma_f32 v62, -v6, v210, v62
	v_fma_f32 v63, -v8, v211, v63
	v_fma_f32 v62, -v9, v212, v62
	v_fma_f32 v63, -v10, v213, v63
	ds_read_b128 v[252:255], v137 offset:31536
	s_waitcnt lgkmcnt(8)
	v_fma_f32 v60, -v11, v214, v62
	v_add_f32_e32 v60, v63, v60
	s_nop 0
	ds_read_b128 v[202:205], v137 offset:31744
	s_waitcnt lgkmcnt(8)
	v_fma_f32 v62, -v81, v218, v124
	v_fma_f32 v63, -v0, v219, 0
	v_fma_f32 v62, -v1, v220, v62
	v_fma_f32 v63, -v2, v221, v63
	ds_read_b128 v[206:209], v137 offset:31760
	s_waitcnt lgkmcnt(8)
	v_fma_f32 v62, -v3, v222, v62
	v_fma_f32 v63, -v4, v223, v63
	v_fma_f32 v62, -v5, v224, v62
	v_fma_f32 v63, -v7, v225, v63
	ds_read_b128 v[210:213], v137 offset:31776
	s_waitcnt lgkmcnt(8)
	v_fma_f32 v62, -v6, v226, v62
	v_fma_f32 v63, -v8, v227, v63
	v_fma_f32 v62, -v9, v228, v62
	v_fma_f32 v63, -v10, v229, v63
	ds_read_b128 v[214:217], v137 offset:31792
	s_waitcnt lgkmcnt(8)
	v_fma_f32 v62, -v11, v230, v62
	v_fma_f32 v61, -v60, v231, v63
	v_add_f32_e32 v61, v62, v61
	s_nop 0
	ds_read_b128 v[218:221], v137 offset:32000
	s_waitcnt lgkmcnt(8)
	v_fma_f32 v62, -v81, v234, v143
	v_fma_f32 v63, -v0, v235, 0
	v_fma_f32 v62, -v1, v236, v62
	v_fma_f32 v63, -v2, v237, v63
	ds_read_b128 v[222:225], v137 offset:32016
	s_waitcnt lgkmcnt(8)
	v_fma_f32 v62, -v3, v238, v62
	v_fma_f32 v63, -v4, v239, v63
	v_fma_f32 v62, -v5, v240, v62
	v_fma_f32 v63, -v7, v241, v63
	ds_read_b128 v[226:229], v137 offset:32032
	s_waitcnt lgkmcnt(8)
	v_fma_f32 v62, -v6, v248, v62
	v_fma_f32 v63, -v8, v249, v63
	v_fma_f32 v62, -v9, v250, v62
	v_fma_f32 v63, -v10, v251, v63
	ds_read_b128 v[230:233], v137 offset:32048
	s_waitcnt lgkmcnt(8)
	v_fma_f32 v62, -v11, v252, v62
	v_fma_f32 v63, -v60, v253, v63
	v_fma_f32 v58, -v61, v254, v62
	v_add_f32_e32 v58, v63, v58
	s_nop 0
	ds_read_b128 v[234:237], v137 offset:32064
	s_waitcnt lgkmcnt(8)
	v_fma_f32 v62, -v81, v202, v145
	v_fma_f32 v63, -v0, v203, 0
	v_fma_f32 v62, -v1, v204, v62
	v_fma_f32 v63, -v2, v205, v63
	ds_read_b128 v[238:241], v137 offset:32256
	s_waitcnt lgkmcnt(8)
	v_fma_f32 v62, -v3, v206, v62
	v_fma_f32 v63, -v4, v207, v63
	v_fma_f32 v62, -v5, v208, v62
	v_fma_f32 v63, -v7, v209, v63
	ds_read_b128 v[248:251], v137 offset:32272
	s_waitcnt lgkmcnt(8)
	v_fma_f32 v62, -v6, v210, v62
	v_fma_f32 v63, -v8, v211, v63
	v_fma_f32 v62, -v9, v212, v62
	v_fma_f32 v63, -v10, v213, v63
	ds_read_b128 v[252:255], v137 offset:32288
	s_waitcnt lgkmcnt(8)
	v_fma_f32 v62, -v11, v214, v62
	v_fma_f32 v63, -v60, v215, v63
	v_fma_f32 v62, -v61, v216, v62
	v_fma_f32 v59, -v58, v217, v63
	v_add_f32_e32 v59, v62, v59
	s_nop 0
	ds_read_b128 v[202:205], v137 offset:32304
	s_waitcnt lgkmcnt(8)
	v_fma_f32 v62, -v81, v218, v133
	v_fma_f32 v63, -v0, v219, 0
	v_fma_f32 v62, -v1, v220, v62
	v_fma_f32 v63, -v2, v221, v63
	ds_read_b128 v[206:209], v137 offset:32320
	s_waitcnt lgkmcnt(8)
	v_fma_f32 v62, -v3, v222, v62
	v_fma_f32 v63, -v4, v223, v63
	v_fma_f32 v62, -v5, v224, v62
	v_fma_f32 v63, -v7, v225, v63
	ds_read_b128 v[210:213], v137 offset:32512
	s_waitcnt lgkmcnt(8)
	v_fma_f32 v62, -v6, v226, v62
	v_fma_f32 v63, -v8, v227, v63
	v_fma_f32 v62, -v9, v228, v62
	v_fma_f32 v63, -v10, v229, v63
	ds_read_b128 v[214:217], v137 offset:32528
	s_waitcnt lgkmcnt(8)
	v_fma_f32 v62, -v11, v230, v62
	v_fma_f32 v63, -v60, v231, v63
	v_fma_f32 v62, -v61, v232, v62
	v_fma_f32 v63, -v58, v233, v63
	ds_read_b128 v[218:221], v137 offset:32544
	s_waitcnt lgkmcnt(8)
	v_fma_f32 v56, -v59, v234, v62
	v_add_f32_e32 v56, v63, v56
	s_nop 0
	ds_read_b128 v[222:225], v137 offset:32560
	s_waitcnt lgkmcnt(8)
	v_fma_f32 v62, -v81, v238, v129
	v_fma_f32 v63, -v0, v239, 0
	v_fma_f32 v62, -v1, v240, v62
	v_fma_f32 v63, -v2, v241, v63
	ds_read_b128 v[226:229], v137 offset:32576
	s_waitcnt lgkmcnt(8)
	v_fma_f32 v62, -v3, v248, v62
	v_fma_f32 v63, -v4, v249, v63
	v_fma_f32 v62, -v5, v250, v62
	v_fma_f32 v63, -v7, v251, v63
	ds_read_b128 v[230:233], v137 offset:32768
	s_waitcnt lgkmcnt(8)
	v_fma_f32 v62, -v6, v252, v62
	v_fma_f32 v63, -v8, v253, v63
	v_fma_f32 v62, -v9, v254, v62
	v_fma_f32 v63, -v10, v255, v63
	ds_read_b128 v[234:237], v137 offset:32784
	s_waitcnt lgkmcnt(8)
	v_fma_f32 v62, -v11, v202, v62
	v_fma_f32 v63, -v60, v203, v63
	v_fma_f32 v62, -v61, v204, v62
	v_fma_f32 v63, -v58, v205, v63
	ds_read_b128 v[238:241], v137 offset:32800
	s_waitcnt lgkmcnt(8)
	v_fma_f32 v62, -v59, v206, v62
	v_fma_f32 v57, -v56, v207, v63
	v_add_f32_e32 v57, v62, v57
	s_nop 0
	ds_read_b128 v[248:251], v137 offset:32816
	s_waitcnt lgkmcnt(8)
	v_fma_f32 v62, -v81, v210, v125
	v_fma_f32 v63, -v0, v211, 0
	v_fma_f32 v62, -v1, v212, v62
	v_fma_f32 v63, -v2, v213, v63
	ds_read_b128 v[252:255], v137 offset:32832
	s_waitcnt lgkmcnt(8)
	v_fma_f32 v62, -v3, v214, v62
	v_fma_f32 v63, -v4, v215, v63
	v_fma_f32 v62, -v5, v216, v62
	v_fma_f32 v63, -v7, v217, v63
	ds_read_b128 v[202:205], v137 offset:33024
	s_waitcnt lgkmcnt(8)
	v_fma_f32 v62, -v6, v218, v62
	v_fma_f32 v63, -v8, v219, v63
	v_fma_f32 v62, -v9, v220, v62
	v_fma_f32 v63, -v10, v221, v63
	ds_read_b128 v[206:209], v137 offset:33040
	s_waitcnt lgkmcnt(8)
	v_fma_f32 v62, -v11, v222, v62
	v_fma_f32 v63, -v60, v223, v63
	v_fma_f32 v62, -v61, v224, v62
	v_fma_f32 v63, -v58, v225, v63
	ds_read_b128 v[210:213], v137 offset:33056
	s_waitcnt lgkmcnt(8)
	v_fma_f32 v62, -v59, v226, v62
	v_fma_f32 v63, -v56, v227, v63
	v_fma_f32 v54, -v57, v228, v62
	v_add_f32_e32 v54, v63, v54
	s_nop 0
	ds_read_b128 v[214:217], v137 offset:33072
	s_waitcnt lgkmcnt(8)
	v_fma_f32 v62, -v81, v230, v136
	v_fma_f32 v63, -v0, v231, 0
	v_fma_f32 v62, -v1, v232, v62
	v_fma_f32 v63, -v2, v233, v63
	ds_read_b128 v[218:221], v137 offset:33088
	s_waitcnt lgkmcnt(8)
	v_fma_f32 v62, -v3, v234, v62
	v_fma_f32 v63, -v4, v235, v63
	v_fma_f32 v62, -v5, v236, v62
	v_fma_f32 v63, -v7, v237, v63
	ds_read_b128 v[222:225], v137 offset:33104
	s_waitcnt lgkmcnt(8)
	v_fma_f32 v62, -v6, v238, v62
	v_fma_f32 v63, -v8, v239, v63
	v_fma_f32 v62, -v9, v240, v62
	v_fma_f32 v63, -v10, v241, v63
	ds_read_b128 v[226:229], v137 offset:33280
	s_waitcnt lgkmcnt(8)
	v_fma_f32 v62, -v11, v248, v62
	v_fma_f32 v63, -v60, v249, v63
	v_fma_f32 v62, -v61, v250, v62
	v_fma_f32 v63, -v58, v251, v63
	ds_read_b128 v[230:233], v137 offset:33296
	s_waitcnt lgkmcnt(8)
	v_fma_f32 v62, -v59, v252, v62
	v_fma_f32 v63, -v56, v253, v63
	v_fma_f32 v62, -v57, v254, v62
	v_fma_f32 v55, -v54, v255, v63
	v_add_f32_e32 v55, v62, v55
	s_nop 0
	ds_read_b128 v[234:237], v137 offset:33312
	s_waitcnt lgkmcnt(8)
	v_fma_f32 v62, -v81, v202, v134
	v_fma_f32 v63, -v0, v203, 0
	v_fma_f32 v62, -v1, v204, v62
	v_fma_f32 v63, -v2, v205, v63
	ds_read_b128 v[238:241], v137 offset:33328
	s_waitcnt lgkmcnt(8)
	v_fma_f32 v62, -v3, v206, v62
	v_fma_f32 v63, -v4, v207, v63
	v_fma_f32 v62, -v5, v208, v62
	v_fma_f32 v63, -v7, v209, v63
	ds_read_b128 v[248:251], v137 offset:33344
	s_waitcnt lgkmcnt(8)
	v_fma_f32 v62, -v6, v210, v62
	v_fma_f32 v63, -v8, v211, v63
	v_fma_f32 v62, -v9, v212, v62
	v_fma_f32 v63, -v10, v213, v63
	ds_read_b128 v[252:255], v137 offset:33360
	s_waitcnt lgkmcnt(8)
	v_fma_f32 v62, -v11, v214, v62
	v_fma_f32 v63, -v60, v215, v63
	v_fma_f32 v62, -v61, v216, v62
	v_fma_f32 v63, -v58, v217, v63
	ds_read_b128 v[202:205], v137 offset:33536
	s_waitcnt lgkmcnt(8)
	v_fma_f32 v62, -v59, v218, v62
	v_fma_f32 v63, -v56, v219, v63
	v_fma_f32 v62, -v57, v220, v62
	v_fma_f32 v63, -v54, v221, v63
	ds_read_b128 v[206:209], v137 offset:33552
	s_waitcnt lgkmcnt(8)
	v_fma_f32 v52, -v55, v222, v62
	v_add_f32_e32 v52, v63, v52
	s_nop 0
	ds_read_b128 v[210:213], v137 offset:33568
	s_waitcnt lgkmcnt(8)
	v_fma_f32 v62, -v81, v226, v132
	v_fma_f32 v63, -v0, v227, 0
	v_fma_f32 v62, -v1, v228, v62
	v_fma_f32 v63, -v2, v229, v63
	ds_read_b128 v[214:217], v137 offset:33584
	s_waitcnt lgkmcnt(8)
	v_fma_f32 v62, -v3, v230, v62
	v_fma_f32 v63, -v4, v231, v63
	v_fma_f32 v62, -v5, v232, v62
	v_fma_f32 v63, -v7, v233, v63
	ds_read_b128 v[218:221], v137 offset:33600
	s_waitcnt lgkmcnt(8)
	v_fma_f32 v62, -v6, v234, v62
	v_fma_f32 v63, -v8, v235, v63
	v_fma_f32 v62, -v9, v236, v62
	v_fma_f32 v63, -v10, v237, v63
	ds_read_b128 v[222:225], v137 offset:33616
	s_waitcnt lgkmcnt(8)
	v_fma_f32 v62, -v11, v238, v62
	v_fma_f32 v63, -v60, v239, v63
	v_fma_f32 v62, -v61, v240, v62
	v_fma_f32 v63, -v58, v241, v63
	ds_read_b128 v[226:229], v137 offset:33792
	s_waitcnt lgkmcnt(8)
	v_fma_f32 v62, -v59, v248, v62
	v_fma_f32 v63, -v56, v249, v63
	v_fma_f32 v62, -v57, v250, v62
	v_fma_f32 v63, -v54, v251, v63
	ds_read_b128 v[230:233], v137 offset:33808
	s_waitcnt lgkmcnt(8)
	v_fma_f32 v62, -v55, v252, v62
	v_fma_f32 v53, -v52, v253, v63
	v_add_f32_e32 v53, v62, v53
	s_nop 0
	ds_read_b128 v[234:237], v137 offset:33824
	s_waitcnt lgkmcnt(8)
	v_fma_f32 v62, -v81, v202, v147
	v_fma_f32 v63, -v0, v203, 0
	v_fma_f32 v62, -v1, v204, v62
	v_fma_f32 v63, -v2, v205, v63
	ds_read_b128 v[238:241], v137 offset:33840
	s_waitcnt lgkmcnt(8)
	v_fma_f32 v62, -v3, v206, v62
	v_fma_f32 v63, -v4, v207, v63
	v_fma_f32 v62, -v5, v208, v62
	v_fma_f32 v63, -v7, v209, v63
	ds_read_b128 v[248:251], v137 offset:33856
	s_waitcnt lgkmcnt(8)
	v_fma_f32 v62, -v6, v210, v62
	v_fma_f32 v63, -v8, v211, v63
	v_fma_f32 v62, -v9, v212, v62
	v_fma_f32 v63, -v10, v213, v63
	ds_read_b128 v[252:255], v137 offset:33872
	s_waitcnt lgkmcnt(8)
	v_fma_f32 v62, -v11, v214, v62
	v_fma_f32 v63, -v60, v215, v63
	v_fma_f32 v62, -v61, v216, v62
	v_fma_f32 v63, -v58, v217, v63
	ds_read_b128 v[202:205], v137 offset:34048
	s_waitcnt lgkmcnt(8)
	v_fma_f32 v62, -v59, v218, v62
	v_fma_f32 v63, -v56, v219, v63
	v_fma_f32 v62, -v57, v220, v62
	v_fma_f32 v63, -v54, v221, v63
	ds_read_b128 v[206:209], v137 offset:34064
	s_waitcnt lgkmcnt(8)
	v_fma_f32 v62, -v55, v222, v62
	v_fma_f32 v63, -v52, v223, v63
	v_fma_f32 v50, -v53, v224, v62
	v_add_f32_e32 v50, v63, v50
	s_nop 0
	ds_read_b128 v[210:213], v137 offset:34080
	s_waitcnt lgkmcnt(8)
	v_fma_f32 v62, -v81, v226, v146
	v_fma_f32 v63, -v0, v227, 0
	v_fma_f32 v62, -v1, v228, v62
	v_fma_f32 v63, -v2, v229, v63
	ds_read_b128 v[214:217], v137 offset:34096
	s_waitcnt lgkmcnt(8)
	v_fma_f32 v62, -v3, v230, v62
	v_fma_f32 v63, -v4, v231, v63
	v_fma_f32 v62, -v5, v232, v62
	v_fma_f32 v63, -v7, v233, v63
	ds_read_b128 v[218:221], v137 offset:34112
	s_waitcnt lgkmcnt(8)
	v_fma_f32 v62, -v6, v234, v62
	v_fma_f32 v63, -v8, v235, v63
	v_fma_f32 v62, -v9, v236, v62
	v_fma_f32 v63, -v10, v237, v63
	ds_read_b128 v[222:225], v137 offset:34128
	s_waitcnt lgkmcnt(8)
	v_fma_f32 v62, -v11, v238, v62
	v_fma_f32 v63, -v60, v239, v63
	v_fma_f32 v62, -v61, v240, v62
	v_fma_f32 v63, -v58, v241, v63
	ds_read_b128 v[226:229], v137 offset:34144
	s_waitcnt lgkmcnt(8)
	v_fma_f32 v62, -v59, v248, v62
	v_fma_f32 v63, -v56, v249, v63
	v_fma_f32 v62, -v57, v250, v62
	v_fma_f32 v63, -v54, v251, v63
	ds_read_b128 v[230:233], v137 offset:34304
	s_waitcnt lgkmcnt(8)
	v_fma_f32 v62, -v55, v252, v62
	v_fma_f32 v63, -v52, v253, v63
	v_fma_f32 v62, -v53, v254, v62
	v_fma_f32 v51, -v50, v255, v63
	v_add_f32_e32 v51, v62, v51
	s_nop 0
	ds_read_b128 v[234:237], v137 offset:34320
	s_waitcnt lgkmcnt(8)
	v_fma_f32 v62, -v81, v202, v135
	v_fma_f32 v63, -v0, v203, 0
	v_fma_f32 v62, -v1, v204, v62
	v_fma_f32 v63, -v2, v205, v63
	ds_read_b128 v[238:241], v137 offset:34336
	s_waitcnt lgkmcnt(8)
	v_fma_f32 v62, -v3, v206, v62
	v_fma_f32 v63, -v4, v207, v63
	v_fma_f32 v62, -v5, v208, v62
	v_fma_f32 v63, -v7, v209, v63
	ds_read_b128 v[248:251], v137 offset:34352
	s_waitcnt lgkmcnt(8)
	v_fma_f32 v62, -v6, v210, v62
	v_fma_f32 v63, -v8, v211, v63
	v_fma_f32 v62, -v9, v212, v62
	v_fma_f32 v63, -v10, v213, v63
	ds_read_b128 v[252:255], v137 offset:34368
	s_waitcnt lgkmcnt(8)
	v_fma_f32 v62, -v11, v214, v62
	v_fma_f32 v63, -v60, v215, v63
	v_fma_f32 v62, -v61, v216, v62
	v_fma_f32 v63, -v58, v217, v63
	ds_read_b128 v[202:205], v137 offset:34384
	s_waitcnt lgkmcnt(8)
	v_fma_f32 v62, -v59, v218, v62
	v_fma_f32 v63, -v56, v219, v63
	v_fma_f32 v62, -v57, v220, v62
	v_fma_f32 v63, -v54, v221, v63
	ds_read_b128 v[206:209], v137 offset:34400
	s_waitcnt lgkmcnt(8)
	v_fma_f32 v62, -v55, v222, v62
	v_fma_f32 v63, -v52, v223, v63
	v_fma_f32 v62, -v53, v224, v62
	v_fma_f32 v63, -v50, v225, v63
	ds_read_b128 v[210:213], v137 offset:34560
	s_waitcnt lgkmcnt(8)
	v_fma_f32 v48, -v51, v226, v62
	v_add_f32_e32 v48, v63, v48
	s_nop 0
	ds_read_b128 v[214:217], v137 offset:34576
	s_waitcnt lgkmcnt(8)
	v_fma_f32 v62, -v81, v230, v128
	v_fma_f32 v63, -v0, v231, 0
	v_fma_f32 v62, -v1, v232, v62
	v_fma_f32 v63, -v2, v233, v63
	ds_read_b128 v[218:221], v137 offset:34592
	s_waitcnt lgkmcnt(8)
	v_fma_f32 v62, -v3, v234, v62
	v_fma_f32 v63, -v4, v235, v63
	v_fma_f32 v62, -v5, v236, v62
	v_fma_f32 v63, -v7, v237, v63
	ds_read_b128 v[222:225], v137 offset:34608
	s_waitcnt lgkmcnt(8)
	v_fma_f32 v62, -v6, v238, v62
	v_fma_f32 v63, -v8, v239, v63
	v_fma_f32 v62, -v9, v240, v62
	v_fma_f32 v63, -v10, v241, v63
	ds_read_b128 v[226:229], v137 offset:34624
	s_waitcnt lgkmcnt(8)
	v_fma_f32 v62, -v11, v248, v62
	v_fma_f32 v63, -v60, v249, v63
	v_fma_f32 v62, -v61, v250, v62
	v_fma_f32 v63, -v58, v251, v63
	ds_read_b128 v[230:233], v137 offset:34640
	s_waitcnt lgkmcnt(8)
	v_fma_f32 v62, -v59, v252, v62
	v_fma_f32 v63, -v56, v253, v63
	v_fma_f32 v62, -v57, v254, v62
	v_fma_f32 v63, -v54, v255, v63
	ds_read_b128 v[234:237], v137 offset:34656
	s_waitcnt lgkmcnt(8)
	v_fma_f32 v62, -v55, v202, v62
	v_fma_f32 v63, -v52, v203, v63
	v_fma_f32 v62, -v53, v204, v62
	v_fma_f32 v63, -v50, v205, v63
	ds_read_b128 v[238:241], v137 offset:34816
	s_waitcnt lgkmcnt(8)
	v_fma_f32 v62, -v51, v206, v62
	v_fma_f32 v49, -v48, v207, v63
	v_add_f32_e32 v49, v62, v49
	s_nop 0
	ds_read_b128 v[248:251], v137 offset:34832
	s_waitcnt lgkmcnt(8)
	v_fma_f32 v62, -v81, v210, v118
	v_fma_f32 v63, -v0, v211, 0
	v_fma_f32 v62, -v1, v212, v62
	v_fma_f32 v63, -v2, v213, v63
	ds_read_b128 v[252:255], v137 offset:34848
	s_waitcnt lgkmcnt(8)
	v_fma_f32 v62, -v3, v214, v62
	v_fma_f32 v63, -v4, v215, v63
	v_fma_f32 v62, -v5, v216, v62
	v_fma_f32 v63, -v7, v217, v63
	ds_read_b128 v[202:205], v137 offset:34864
	s_waitcnt lgkmcnt(8)
	v_fma_f32 v62, -v6, v218, v62
	v_fma_f32 v63, -v8, v219, v63
	v_fma_f32 v62, -v9, v220, v62
	v_fma_f32 v63, -v10, v221, v63
	ds_read_b128 v[206:209], v137 offset:34880
	s_waitcnt lgkmcnt(8)
	v_fma_f32 v62, -v11, v222, v62
	v_fma_f32 v63, -v60, v223, v63
	v_fma_f32 v62, -v61, v224, v62
	v_fma_f32 v63, -v58, v225, v63
	ds_read_b128 v[210:213], v137 offset:34896
	s_waitcnt lgkmcnt(8)
	v_fma_f32 v62, -v59, v226, v62
	v_fma_f32 v63, -v56, v227, v63
	v_fma_f32 v62, -v57, v228, v62
	v_fma_f32 v63, -v54, v229, v63
	ds_read_b128 v[214:217], v137 offset:34912
	s_waitcnt lgkmcnt(8)
	v_fma_f32 v62, -v55, v230, v62
	v_fma_f32 v63, -v52, v231, v63
	v_fma_f32 v62, -v53, v232, v62
	v_fma_f32 v63, -v50, v233, v63
	ds_read_b128 v[218:221], v137 offset:35072
	s_waitcnt lgkmcnt(8)
	v_fma_f32 v62, -v51, v234, v62
	v_fma_f32 v63, -v48, v235, v63
	v_fma_f32 v46, -v49, v236, v62
	v_add_f32_e32 v46, v63, v46
	s_nop 0
	ds_read_b128 v[222:225], v137 offset:35088
	s_waitcnt lgkmcnt(8)
	v_fma_f32 v62, -v81, v238, v130
	v_fma_f32 v63, -v0, v239, 0
	v_fma_f32 v62, -v1, v240, v62
	v_fma_f32 v63, -v2, v241, v63
	ds_read_b128 v[226:229], v137 offset:35104
	s_waitcnt lgkmcnt(8)
	v_fma_f32 v62, -v3, v248, v62
	v_fma_f32 v63, -v4, v249, v63
	v_fma_f32 v62, -v5, v250, v62
	v_fma_f32 v63, -v7, v251, v63
	ds_read_b128 v[230:233], v137 offset:35120
	s_waitcnt lgkmcnt(8)
	v_fma_f32 v62, -v6, v252, v62
	v_fma_f32 v63, -v8, v253, v63
	v_fma_f32 v62, -v9, v254, v62
	v_fma_f32 v63, -v10, v255, v63
	ds_read_b128 v[234:237], v137 offset:35136
	s_waitcnt lgkmcnt(8)
	v_fma_f32 v62, -v11, v202, v62
	v_fma_f32 v63, -v60, v203, v63
	v_fma_f32 v62, -v61, v204, v62
	v_fma_f32 v63, -v58, v205, v63
	ds_read_b128 v[238:241], v137 offset:35152
	s_waitcnt lgkmcnt(8)
	v_fma_f32 v62, -v59, v206, v62
	v_fma_f32 v63, -v56, v207, v63
	v_fma_f32 v62, -v57, v208, v62
	v_fma_f32 v63, -v54, v209, v63
	ds_read_b128 v[248:251], v137 offset:35168
	s_waitcnt lgkmcnt(8)
	v_fma_f32 v62, -v55, v210, v62
	v_fma_f32 v63, -v52, v211, v63
	v_fma_f32 v62, -v53, v212, v62
	v_fma_f32 v63, -v50, v213, v63
	ds_read_b128 v[252:255], v137 offset:35184
	s_waitcnt lgkmcnt(8)
	v_fma_f32 v62, -v51, v214, v62
	v_fma_f32 v63, -v48, v215, v63
	v_fma_f32 v62, -v49, v216, v62
	v_fma_f32 v47, -v46, v217, v63
	v_add_f32_e32 v47, v62, v47
	s_nop 0
	ds_read_b128 v[202:205], v137 offset:35328
	s_waitcnt lgkmcnt(8)
	v_fma_f32 v62, -v81, v218, v127
	v_fma_f32 v63, -v0, v219, 0
	v_fma_f32 v62, -v1, v220, v62
	v_fma_f32 v63, -v2, v221, v63
	ds_read_b128 v[206:209], v137 offset:35344
	s_waitcnt lgkmcnt(8)
	v_fma_f32 v62, -v3, v222, v62
	v_fma_f32 v63, -v4, v223, v63
	v_fma_f32 v62, -v5, v224, v62
	v_fma_f32 v63, -v7, v225, v63
	ds_read_b128 v[210:213], v137 offset:35360
	s_waitcnt lgkmcnt(8)
	v_fma_f32 v62, -v6, v226, v62
	v_fma_f32 v63, -v8, v227, v63
	v_fma_f32 v62, -v9, v228, v62
	v_fma_f32 v63, -v10, v229, v63
	ds_read_b128 v[214:217], v137 offset:35376
	s_waitcnt lgkmcnt(8)
	v_fma_f32 v62, -v11, v230, v62
	v_fma_f32 v63, -v60, v231, v63
	v_fma_f32 v62, -v61, v232, v62
	v_fma_f32 v63, -v58, v233, v63
	ds_read_b128 v[218:221], v137 offset:35392
	s_waitcnt lgkmcnt(8)
	v_fma_f32 v62, -v59, v234, v62
	v_fma_f32 v63, -v56, v235, v63
	v_fma_f32 v62, -v57, v236, v62
	v_fma_f32 v63, -v54, v237, v63
	ds_read_b128 v[222:225], v137 offset:35408
	s_waitcnt lgkmcnt(8)
	v_fma_f32 v62, -v55, v238, v62
	v_fma_f32 v63, -v52, v239, v63
	v_fma_f32 v62, -v53, v240, v62
	v_fma_f32 v63, -v50, v241, v63
	ds_read_b128 v[226:229], v137 offset:35424
	s_waitcnt lgkmcnt(8)
	v_fma_f32 v62, -v51, v248, v62
	v_fma_f32 v63, -v48, v249, v63
	v_fma_f32 v62, -v49, v250, v62
	v_fma_f32 v63, -v46, v251, v63
	ds_read_b128 v[230:233], v137 offset:35440
	s_waitcnt lgkmcnt(8)
	v_fma_f32 v44, -v47, v252, v62
	v_add_f32_e32 v44, v63, v44
	s_nop 0
	ds_read_b128 v[234:237], v137 offset:35584
	s_waitcnt lgkmcnt(8)
	v_fma_f32 v62, -v81, v202, v119
	v_fma_f32 v63, -v0, v203, 0
	v_fma_f32 v62, -v1, v204, v62
	v_fma_f32 v63, -v2, v205, v63
	ds_read_b128 v[238:241], v137 offset:35600
	s_waitcnt lgkmcnt(8)
	v_fma_f32 v62, -v3, v206, v62
	v_fma_f32 v63, -v4, v207, v63
	v_fma_f32 v62, -v5, v208, v62
	v_fma_f32 v63, -v7, v209, v63
	ds_read_b128 v[248:251], v137 offset:35616
	s_waitcnt lgkmcnt(8)
	v_fma_f32 v62, -v6, v210, v62
	v_fma_f32 v63, -v8, v211, v63
	v_fma_f32 v62, -v9, v212, v62
	v_fma_f32 v63, -v10, v213, v63
	ds_read_b128 v[252:255], v137 offset:35632
	s_waitcnt lgkmcnt(8)
	v_fma_f32 v62, -v11, v214, v62
	v_fma_f32 v63, -v60, v215, v63
	v_fma_f32 v62, -v61, v216, v62
	v_fma_f32 v63, -v58, v217, v63
	ds_read_b128 v[202:205], v137 offset:35648
	s_waitcnt lgkmcnt(8)
	v_fma_f32 v62, -v59, v218, v62
	v_fma_f32 v63, -v56, v219, v63
	v_fma_f32 v62, -v57, v220, v62
	v_fma_f32 v63, -v54, v221, v63
	ds_read_b128 v[206:209], v137 offset:35664
	s_waitcnt lgkmcnt(8)
	v_fma_f32 v62, -v55, v222, v62
	v_fma_f32 v63, -v52, v223, v63
	v_fma_f32 v62, -v53, v224, v62
	v_fma_f32 v63, -v50, v225, v63
	ds_read_b128 v[210:213], v137 offset:35680
	s_waitcnt lgkmcnt(8)
	v_fma_f32 v62, -v51, v226, v62
	v_fma_f32 v63, -v48, v227, v63
	v_fma_f32 v62, -v49, v228, v62
	v_fma_f32 v63, -v46, v229, v63
	ds_read_b128 v[214:217], v137 offset:35696
	s_waitcnt lgkmcnt(8)
	v_fma_f32 v62, -v47, v230, v62
	v_fma_f32 v45, -v44, v231, v63
	v_add_f32_e32 v45, v62, v45
	s_nop 0
	ds_read_b128 v[218:221], v137 offset:35840
	s_waitcnt lgkmcnt(8)
	v_fma_f32 v62, -v81, v234, v131
	v_fma_f32 v63, -v0, v235, 0
	v_fma_f32 v62, -v1, v236, v62
	v_fma_f32 v63, -v2, v237, v63
	ds_read_b128 v[222:225], v137 offset:35856
	s_waitcnt lgkmcnt(8)
	v_fma_f32 v62, -v3, v238, v62
	v_fma_f32 v63, -v4, v239, v63
	v_fma_f32 v62, -v5, v240, v62
	v_fma_f32 v63, -v7, v241, v63
	ds_read_b128 v[226:229], v137 offset:35872
	s_waitcnt lgkmcnt(8)
	v_fma_f32 v62, -v6, v248, v62
	v_fma_f32 v63, -v8, v249, v63
	v_fma_f32 v62, -v9, v250, v62
	v_fma_f32 v63, -v10, v251, v63
	ds_read_b128 v[230:233], v137 offset:35888
	s_waitcnt lgkmcnt(8)
	v_fma_f32 v62, -v11, v252, v62
	v_fma_f32 v63, -v60, v253, v63
	v_fma_f32 v62, -v61, v254, v62
	v_fma_f32 v63, -v58, v255, v63
	ds_read_b128 v[234:237], v137 offset:35904
	s_waitcnt lgkmcnt(8)
	v_fma_f32 v62, -v59, v202, v62
	v_fma_f32 v63, -v56, v203, v63
	v_fma_f32 v62, -v57, v204, v62
	v_fma_f32 v63, -v54, v205, v63
	ds_read_b128 v[238:241], v137 offset:35920
	s_waitcnt lgkmcnt(8)
	v_fma_f32 v62, -v55, v206, v62
	v_fma_f32 v63, -v52, v207, v63
	v_fma_f32 v62, -v53, v208, v62
	v_fma_f32 v63, -v50, v209, v63
	ds_read_b128 v[248:251], v137 offset:35936
	s_waitcnt lgkmcnt(8)
	v_fma_f32 v62, -v51, v210, v62
	v_fma_f32 v63, -v48, v211, v63
	v_fma_f32 v62, -v49, v212, v62
	v_fma_f32 v63, -v46, v213, v63
	ds_read_b128 v[252:255], v137 offset:35952
	s_waitcnt lgkmcnt(8)
	v_fma_f32 v62, -v47, v214, v62
	v_fma_f32 v63, -v44, v215, v63
	v_fma_f32 v42, -v45, v216, v62
	v_add_f32_e32 v42, v63, v42
	s_nop 0
	ds_read_b128 v[202:205], v137 offset:36096
	s_waitcnt lgkmcnt(8)
	v_fma_f32 v62, -v81, v218, v126
	v_fma_f32 v63, -v0, v219, 0
	v_fma_f32 v62, -v1, v220, v62
	v_fma_f32 v63, -v2, v221, v63
	ds_read_b128 v[206:209], v137 offset:36112
	s_waitcnt lgkmcnt(8)
	v_fma_f32 v62, -v3, v222, v62
	v_fma_f32 v63, -v4, v223, v63
	v_fma_f32 v62, -v5, v224, v62
	v_fma_f32 v63, -v7, v225, v63
	ds_read_b128 v[210:213], v137 offset:36128
	s_waitcnt lgkmcnt(8)
	v_fma_f32 v62, -v6, v226, v62
	v_fma_f32 v63, -v8, v227, v63
	v_fma_f32 v62, -v9, v228, v62
	v_fma_f32 v63, -v10, v229, v63
	ds_read_b128 v[214:217], v137 offset:36144
	s_waitcnt lgkmcnt(8)
	v_fma_f32 v62, -v11, v230, v62
	v_fma_f32 v63, -v60, v231, v63
	v_fma_f32 v62, -v61, v232, v62
	v_fma_f32 v63, -v58, v233, v63
	ds_read_b128 v[218:221], v137 offset:36160
	s_waitcnt lgkmcnt(8)
	v_fma_f32 v62, -v59, v234, v62
	v_fma_f32 v63, -v56, v235, v63
	v_fma_f32 v62, -v57, v236, v62
	v_fma_f32 v63, -v54, v237, v63
	ds_read_b128 v[222:225], v137 offset:36176
	s_waitcnt lgkmcnt(8)
	v_fma_f32 v62, -v55, v238, v62
	v_fma_f32 v63, -v52, v239, v63
	v_fma_f32 v62, -v53, v240, v62
	v_fma_f32 v63, -v50, v241, v63
	ds_read_b128 v[226:229], v137 offset:36192
	s_waitcnt lgkmcnt(8)
	v_fma_f32 v62, -v51, v248, v62
	v_fma_f32 v63, -v48, v249, v63
	v_fma_f32 v62, -v49, v250, v62
	v_fma_f32 v63, -v46, v251, v63
	ds_read_b128 v[230:233], v137 offset:36208
	s_waitcnt lgkmcnt(8)
	v_fma_f32 v62, -v47, v252, v62
	v_fma_f32 v63, -v44, v253, v63
	v_fma_f32 v62, -v45, v254, v62
	v_fma_f32 v43, -v42, v255, v63
	v_add_f32_e32 v43, v62, v43
	s_nop 0
	ds_read_b128 v[234:237], v137 offset:36224
	s_waitcnt lgkmcnt(8)
	v_fma_f32 v62, -v81, v202, v115
	v_fma_f32 v63, -v0, v203, 0
	v_fma_f32 v62, -v1, v204, v62
	v_fma_f32 v63, -v2, v205, v63
	ds_read_b128 v[238:241], v137 offset:36352
	s_waitcnt lgkmcnt(8)
	v_fma_f32 v62, -v3, v206, v62
	v_fma_f32 v63, -v4, v207, v63
	v_fma_f32 v62, -v5, v208, v62
	v_fma_f32 v63, -v7, v209, v63
	ds_read_b128 v[248:251], v137 offset:36368
	s_waitcnt lgkmcnt(8)
	v_fma_f32 v62, -v6, v210, v62
	v_fma_f32 v63, -v8, v211, v63
	v_fma_f32 v62, -v9, v212, v62
	v_fma_f32 v63, -v10, v213, v63
	ds_read_b128 v[252:255], v137 offset:36384
	s_waitcnt lgkmcnt(8)
	v_fma_f32 v62, -v11, v214, v62
	v_fma_f32 v63, -v60, v215, v63
	v_fma_f32 v62, -v61, v216, v62
	v_fma_f32 v63, -v58, v217, v63
	ds_read_b128 v[202:205], v137 offset:36400
	s_waitcnt lgkmcnt(8)
	v_fma_f32 v62, -v59, v218, v62
	v_fma_f32 v63, -v56, v219, v63
	v_fma_f32 v62, -v57, v220, v62
	v_fma_f32 v63, -v54, v221, v63
	ds_read_b128 v[206:209], v137 offset:36416
	s_waitcnt lgkmcnt(8)
	v_fma_f32 v62, -v55, v222, v62
	v_fma_f32 v63, -v52, v223, v63
	v_fma_f32 v62, -v53, v224, v62
	v_fma_f32 v63, -v50, v225, v63
	ds_read_b128 v[210:213], v137 offset:36432
	s_waitcnt lgkmcnt(8)
	v_fma_f32 v62, -v51, v226, v62
	v_fma_f32 v63, -v48, v227, v63
	v_fma_f32 v62, -v49, v228, v62
	v_fma_f32 v63, -v46, v229, v63
	ds_read_b128 v[214:217], v137 offset:36448
	s_waitcnt lgkmcnt(8)
	v_fma_f32 v62, -v47, v230, v62
	v_fma_f32 v63, -v44, v231, v63
	v_fma_f32 v62, -v45, v232, v62
	v_fma_f32 v63, -v42, v233, v63
	ds_read_b128 v[218:221], v137 offset:36464
	s_waitcnt lgkmcnt(8)
	v_fma_f32 v40, -v43, v234, v62
	v_add_f32_e32 v40, v63, v40
	s_nop 0
	ds_read_b128 v[222:225], v137 offset:36480
	s_waitcnt lgkmcnt(8)
	v_fma_f32 v62, -v81, v238, v114
	v_fma_f32 v63, -v0, v239, 0
	v_fma_f32 v62, -v1, v240, v62
	v_fma_f32 v63, -v2, v241, v63
	ds_read_b128 v[226:229], v137 offset:36608
	s_waitcnt lgkmcnt(8)
	v_fma_f32 v62, -v3, v248, v62
	v_fma_f32 v63, -v4, v249, v63
	v_fma_f32 v62, -v5, v250, v62
	v_fma_f32 v63, -v7, v251, v63
	ds_read_b128 v[230:233], v137 offset:36624
	s_waitcnt lgkmcnt(8)
	v_fma_f32 v62, -v6, v252, v62
	v_fma_f32 v63, -v8, v253, v63
	v_fma_f32 v62, -v9, v254, v62
	v_fma_f32 v63, -v10, v255, v63
	ds_read_b128 v[234:237], v137 offset:36640
	s_waitcnt lgkmcnt(8)
	v_fma_f32 v62, -v11, v202, v62
	v_fma_f32 v63, -v60, v203, v63
	v_fma_f32 v62, -v61, v204, v62
	v_fma_f32 v63, -v58, v205, v63
	ds_read_b128 v[238:241], v137 offset:36656
	s_waitcnt lgkmcnt(8)
	v_fma_f32 v62, -v59, v206, v62
	v_fma_f32 v63, -v56, v207, v63
	v_fma_f32 v62, -v57, v208, v62
	v_fma_f32 v63, -v54, v209, v63
	ds_read_b128 v[248:251], v137 offset:36672
	s_waitcnt lgkmcnt(8)
	v_fma_f32 v62, -v55, v210, v62
	v_fma_f32 v63, -v52, v211, v63
	v_fma_f32 v62, -v53, v212, v62
	v_fma_f32 v63, -v50, v213, v63
	ds_read_b128 v[252:255], v137 offset:36688
	s_waitcnt lgkmcnt(8)
	v_fma_f32 v62, -v51, v214, v62
	v_fma_f32 v63, -v48, v215, v63
	v_fma_f32 v62, -v49, v216, v62
	v_fma_f32 v63, -v46, v217, v63
	ds_read_b128 v[202:205], v137 offset:36704
	s_waitcnt lgkmcnt(8)
	v_fma_f32 v62, -v47, v218, v62
	v_fma_f32 v63, -v44, v219, v63
	v_fma_f32 v62, -v45, v220, v62
	v_fma_f32 v63, -v42, v221, v63
	ds_read_b128 v[206:209], v137 offset:36720
	s_waitcnt lgkmcnt(8)
	v_fma_f32 v62, -v43, v222, v62
	v_fma_f32 v41, -v40, v223, v63
	v_add_f32_e32 v41, v62, v41
	s_nop 0
	ds_read_b128 v[210:213], v137 offset:36736
	s_waitcnt lgkmcnt(8)
	v_fma_f32 v62, -v81, v226, v111
	v_fma_f32 v63, -v0, v227, 0
	v_fma_f32 v62, -v1, v228, v62
	v_fma_f32 v63, -v2, v229, v63
	ds_read_b128 v[214:217], v137 offset:36864
	s_waitcnt lgkmcnt(8)
	v_fma_f32 v62, -v3, v230, v62
	v_fma_f32 v63, -v4, v231, v63
	v_fma_f32 v62, -v5, v232, v62
	v_fma_f32 v63, -v7, v233, v63
	ds_read_b128 v[218:221], v137 offset:36880
	s_waitcnt lgkmcnt(8)
	v_fma_f32 v62, -v6, v234, v62
	v_fma_f32 v63, -v8, v235, v63
	v_fma_f32 v62, -v9, v236, v62
	v_fma_f32 v63, -v10, v237, v63
	ds_read_b128 v[222:225], v137 offset:36896
	s_waitcnt lgkmcnt(8)
	v_fma_f32 v62, -v11, v238, v62
	v_fma_f32 v63, -v60, v239, v63
	v_fma_f32 v62, -v61, v240, v62
	v_fma_f32 v63, -v58, v241, v63
	ds_read_b128 v[226:229], v137 offset:36912
	s_waitcnt lgkmcnt(8)
	v_fma_f32 v62, -v59, v248, v62
	v_fma_f32 v63, -v56, v249, v63
	v_fma_f32 v62, -v57, v250, v62
	v_fma_f32 v63, -v54, v251, v63
	ds_read_b128 v[230:233], v137 offset:36928
	s_waitcnt lgkmcnt(8)
	v_fma_f32 v62, -v55, v252, v62
	v_fma_f32 v63, -v52, v253, v63
	v_fma_f32 v62, -v53, v254, v62
	v_fma_f32 v63, -v50, v255, v63
	ds_read_b128 v[234:237], v137 offset:36944
	s_waitcnt lgkmcnt(8)
	v_fma_f32 v62, -v51, v202, v62
	v_fma_f32 v63, -v48, v203, v63
	v_fma_f32 v62, -v49, v204, v62
	v_fma_f32 v63, -v46, v205, v63
	ds_read_b128 v[238:241], v137 offset:36960
	s_waitcnt lgkmcnt(8)
	v_fma_f32 v62, -v47, v206, v62
	v_fma_f32 v63, -v44, v207, v63
	v_fma_f32 v62, -v45, v208, v62
	v_fma_f32 v63, -v42, v209, v63
	ds_read_b128 v[248:251], v137 offset:36976
	s_waitcnt lgkmcnt(8)
	v_fma_f32 v62, -v43, v210, v62
	v_fma_f32 v63, -v40, v211, v63
	v_fma_f32 v38, -v41, v212, v62
	v_add_f32_e32 v38, v63, v38
	s_nop 0
	ds_read_b128 v[252:255], v137 offset:36992
	s_waitcnt lgkmcnt(8)
	v_fma_f32 v62, -v81, v214, v113
	v_fma_f32 v63, -v0, v215, 0
	v_fma_f32 v62, -v1, v216, v62
	v_fma_f32 v63, -v2, v217, v63
	ds_read_b128 v[202:205], v137 offset:37120
	s_waitcnt lgkmcnt(8)
	v_fma_f32 v62, -v3, v218, v62
	v_fma_f32 v63, -v4, v219, v63
	v_fma_f32 v62, -v5, v220, v62
	v_fma_f32 v63, -v7, v221, v63
	ds_read_b128 v[206:209], v137 offset:37136
	s_waitcnt lgkmcnt(8)
	v_fma_f32 v62, -v6, v222, v62
	v_fma_f32 v63, -v8, v223, v63
	v_fma_f32 v62, -v9, v224, v62
	v_fma_f32 v63, -v10, v225, v63
	ds_read_b128 v[210:213], v137 offset:37152
	s_waitcnt lgkmcnt(8)
	v_fma_f32 v62, -v11, v226, v62
	v_fma_f32 v63, -v60, v227, v63
	v_fma_f32 v62, -v61, v228, v62
	v_fma_f32 v63, -v58, v229, v63
	ds_read_b128 v[214:217], v137 offset:37168
	s_waitcnt lgkmcnt(8)
	v_fma_f32 v62, -v59, v230, v62
	v_fma_f32 v63, -v56, v231, v63
	v_fma_f32 v62, -v57, v232, v62
	v_fma_f32 v63, -v54, v233, v63
	ds_read_b128 v[218:221], v137 offset:37184
	s_waitcnt lgkmcnt(8)
	v_fma_f32 v62, -v55, v234, v62
	v_fma_f32 v63, -v52, v235, v63
	v_fma_f32 v62, -v53, v236, v62
	v_fma_f32 v63, -v50, v237, v63
	ds_read_b128 v[222:225], v137 offset:37200
	s_waitcnt lgkmcnt(8)
	v_fma_f32 v62, -v51, v238, v62
	v_fma_f32 v63, -v48, v239, v63
	v_fma_f32 v62, -v49, v240, v62
	v_fma_f32 v63, -v46, v241, v63
	ds_read_b128 v[226:229], v137 offset:37216
	s_waitcnt lgkmcnt(8)
	v_fma_f32 v62, -v47, v248, v62
	v_fma_f32 v63, -v44, v249, v63
	v_fma_f32 v62, -v45, v250, v62
	v_fma_f32 v63, -v42, v251, v63
	ds_read_b128 v[230:233], v137 offset:37232
	s_waitcnt lgkmcnt(8)
	v_fma_f32 v62, -v43, v252, v62
	v_fma_f32 v63, -v40, v253, v63
	v_fma_f32 v62, -v41, v254, v62
	v_fma_f32 v39, -v38, v255, v63
	v_add_f32_e32 v39, v62, v39
	s_nop 0
	ds_read_b128 v[234:237], v137 offset:37248
	s_waitcnt lgkmcnt(8)
	v_fma_f32 v62, -v81, v202, v112
	v_fma_f32 v63, -v0, v203, 0
	v_fma_f32 v62, -v1, v204, v62
	v_fma_f32 v63, -v2, v205, v63
	ds_read_b128 v[238:241], v137 offset:37264
	s_waitcnt lgkmcnt(8)
	v_fma_f32 v62, -v3, v206, v62
	v_fma_f32 v63, -v4, v207, v63
	v_fma_f32 v62, -v5, v208, v62
	v_fma_f32 v63, -v7, v209, v63
	ds_read_b128 v[248:251], v137 offset:37376
	s_waitcnt lgkmcnt(8)
	v_fma_f32 v62, -v6, v210, v62
	v_fma_f32 v63, -v8, v211, v63
	v_fma_f32 v62, -v9, v212, v62
	v_fma_f32 v63, -v10, v213, v63
	ds_read_b128 v[252:255], v137 offset:37392
	s_waitcnt lgkmcnt(8)
	v_fma_f32 v62, -v11, v214, v62
	v_fma_f32 v63, -v60, v215, v63
	v_fma_f32 v62, -v61, v216, v62
	v_fma_f32 v63, -v58, v217, v63
	ds_read_b128 v[202:205], v137 offset:37408
	s_waitcnt lgkmcnt(8)
	v_fma_f32 v62, -v59, v218, v62
	v_fma_f32 v63, -v56, v219, v63
	v_fma_f32 v62, -v57, v220, v62
	v_fma_f32 v63, -v54, v221, v63
	ds_read_b128 v[206:209], v137 offset:37424
	s_waitcnt lgkmcnt(8)
	v_fma_f32 v62, -v55, v222, v62
	v_fma_f32 v63, -v52, v223, v63
	v_fma_f32 v62, -v53, v224, v62
	v_fma_f32 v63, -v50, v225, v63
	ds_read_b128 v[210:213], v137 offset:37440
	s_waitcnt lgkmcnt(8)
	v_fma_f32 v62, -v51, v226, v62
	v_fma_f32 v63, -v48, v227, v63
	v_fma_f32 v62, -v49, v228, v62
	v_fma_f32 v63, -v46, v229, v63
	ds_read_b128 v[214:217], v137 offset:37456
	s_waitcnt lgkmcnt(8)
	v_fma_f32 v62, -v47, v230, v62
	v_fma_f32 v63, -v44, v231, v63
	v_fma_f32 v62, -v45, v232, v62
	v_fma_f32 v63, -v42, v233, v63
	ds_read_b128 v[218:221], v137 offset:37472
	s_waitcnt lgkmcnt(8)
	v_fma_f32 v62, -v43, v234, v62
	v_fma_f32 v63, -v40, v235, v63
	v_fma_f32 v62, -v41, v236, v62
	v_fma_f32 v63, -v38, v237, v63
	ds_read_b128 v[222:225], v137 offset:37488
	s_waitcnt lgkmcnt(8)
	v_fma_f32 v36, -v39, v238, v62
	v_add_f32_e32 v36, v63, v36
	s_nop 0
	ds_read_b128 v[226:229], v137 offset:37504
	s_waitcnt lgkmcnt(8)
	v_fma_f32 v62, -v81, v248, v108
	v_fma_f32 v63, -v0, v249, 0
	v_fma_f32 v62, -v1, v250, v62
	v_fma_f32 v63, -v2, v251, v63
	ds_read_b128 v[230:233], v137 offset:37520
	s_waitcnt lgkmcnt(8)
	v_fma_f32 v62, -v3, v252, v62
	v_fma_f32 v63, -v4, v253, v63
	v_fma_f32 v62, -v5, v254, v62
	v_fma_f32 v63, -v7, v255, v63
	ds_read_b128 v[234:237], v137 offset:37632
	s_waitcnt lgkmcnt(8)
	v_fma_f32 v62, -v6, v202, v62
	v_fma_f32 v63, -v8, v203, v63
	v_fma_f32 v62, -v9, v204, v62
	v_fma_f32 v63, -v10, v205, v63
	ds_read_b128 v[238:241], v137 offset:37648
	s_waitcnt lgkmcnt(8)
	v_fma_f32 v62, -v11, v206, v62
	v_fma_f32 v63, -v60, v207, v63
	v_fma_f32 v62, -v61, v208, v62
	v_fma_f32 v63, -v58, v209, v63
	ds_read_b128 v[248:251], v137 offset:37664
	s_waitcnt lgkmcnt(8)
	v_fma_f32 v62, -v59, v210, v62
	v_fma_f32 v63, -v56, v211, v63
	v_fma_f32 v62, -v57, v212, v62
	v_fma_f32 v63, -v54, v213, v63
	ds_read_b128 v[252:255], v137 offset:37680
	s_waitcnt lgkmcnt(8)
	v_fma_f32 v62, -v55, v214, v62
	v_fma_f32 v63, -v52, v215, v63
	v_fma_f32 v62, -v53, v216, v62
	v_fma_f32 v63, -v50, v217, v63
	ds_read_b128 v[202:205], v137 offset:37696
	s_waitcnt lgkmcnt(8)
	v_fma_f32 v62, -v51, v218, v62
	v_fma_f32 v63, -v48, v219, v63
	v_fma_f32 v62, -v49, v220, v62
	v_fma_f32 v63, -v46, v221, v63
	ds_read_b128 v[206:209], v137 offset:37712
	s_waitcnt lgkmcnt(8)
	v_fma_f32 v62, -v47, v222, v62
	v_fma_f32 v63, -v44, v223, v63
	v_fma_f32 v62, -v45, v224, v62
	v_fma_f32 v63, -v42, v225, v63
	ds_read_b128 v[210:213], v137 offset:37728
	s_waitcnt lgkmcnt(8)
	v_fma_f32 v62, -v43, v226, v62
	v_fma_f32 v63, -v40, v227, v63
	v_fma_f32 v62, -v41, v228, v62
	v_fma_f32 v63, -v38, v229, v63
	ds_read_b128 v[214:217], v137 offset:37744
	s_waitcnt lgkmcnt(8)
	v_fma_f32 v62, -v39, v230, v62
	v_fma_f32 v37, -v36, v231, v63
	v_add_f32_e32 v37, v62, v37
	s_nop 0
	ds_read_b128 v[218:221], v137 offset:37760
	s_waitcnt lgkmcnt(8)
	v_fma_f32 v62, -v81, v234, v110
	v_fma_f32 v63, -v0, v235, 0
	v_fma_f32 v62, -v1, v236, v62
	v_fma_f32 v63, -v2, v237, v63
	ds_read_b128 v[222:225], v137 offset:37776
	s_waitcnt lgkmcnt(8)
	v_fma_f32 v62, -v3, v238, v62
	v_fma_f32 v63, -v4, v239, v63
	v_fma_f32 v62, -v5, v240, v62
	v_fma_f32 v63, -v7, v241, v63
	ds_read_b128 v[226:229], v137 offset:37888
	s_waitcnt lgkmcnt(8)
	v_fma_f32 v62, -v6, v248, v62
	v_fma_f32 v63, -v8, v249, v63
	v_fma_f32 v62, -v9, v250, v62
	v_fma_f32 v63, -v10, v251, v63
	ds_read_b128 v[230:233], v137 offset:37904
	s_waitcnt lgkmcnt(8)
	v_fma_f32 v62, -v11, v252, v62
	v_fma_f32 v63, -v60, v253, v63
	v_fma_f32 v62, -v61, v254, v62
	v_fma_f32 v63, -v58, v255, v63
	ds_read_b128 v[234:237], v137 offset:37920
	s_waitcnt lgkmcnt(8)
	v_fma_f32 v62, -v59, v202, v62
	v_fma_f32 v63, -v56, v203, v63
	v_fma_f32 v62, -v57, v204, v62
	v_fma_f32 v63, -v54, v205, v63
	ds_read_b128 v[238:241], v137 offset:37936
	s_waitcnt lgkmcnt(8)
	v_fma_f32 v62, -v55, v206, v62
	v_fma_f32 v63, -v52, v207, v63
	v_fma_f32 v62, -v53, v208, v62
	v_fma_f32 v63, -v50, v209, v63
	ds_read_b128 v[248:251], v137 offset:37952
	s_waitcnt lgkmcnt(8)
	v_fma_f32 v62, -v51, v210, v62
	v_fma_f32 v63, -v48, v211, v63
	v_fma_f32 v62, -v49, v212, v62
	v_fma_f32 v63, -v46, v213, v63
	ds_read_b128 v[252:255], v137 offset:37968
	s_waitcnt lgkmcnt(8)
	v_fma_f32 v62, -v47, v214, v62
	v_fma_f32 v63, -v44, v215, v63
	v_fma_f32 v62, -v45, v216, v62
	v_fma_f32 v63, -v42, v217, v63
	ds_read_b128 v[202:205], v137 offset:37984
	s_waitcnt lgkmcnt(8)
	v_fma_f32 v62, -v43, v218, v62
	v_fma_f32 v63, -v40, v219, v63
	v_fma_f32 v62, -v41, v220, v62
	v_fma_f32 v63, -v38, v221, v63
	ds_read_b128 v[206:209], v137 offset:38000
	s_waitcnt lgkmcnt(8)
	v_fma_f32 v62, -v39, v222, v62
	v_fma_f32 v63, -v36, v223, v63
	v_fma_f32 v34, -v37, v224, v62
	v_add_f32_e32 v34, v63, v34
	s_nop 0
	ds_read_b128 v[210:213], v137 offset:38016
	s_waitcnt lgkmcnt(8)
	v_fma_f32 v62, -v81, v226, v107
	v_fma_f32 v63, -v0, v227, 0
	v_fma_f32 v62, -v1, v228, v62
	v_fma_f32 v63, -v2, v229, v63
	ds_read_b128 v[214:217], v137 offset:38032
	s_waitcnt lgkmcnt(8)
	v_fma_f32 v62, -v3, v230, v62
	v_fma_f32 v63, -v4, v231, v63
	v_fma_f32 v62, -v5, v232, v62
	v_fma_f32 v63, -v7, v233, v63
	ds_read_b128 v[218:221], v137 offset:38144
	s_waitcnt lgkmcnt(8)
	v_fma_f32 v62, -v6, v234, v62
	v_fma_f32 v63, -v8, v235, v63
	v_fma_f32 v62, -v9, v236, v62
	v_fma_f32 v63, -v10, v237, v63
	ds_read_b128 v[222:225], v137 offset:38160
	s_waitcnt lgkmcnt(8)
	v_fma_f32 v62, -v11, v238, v62
	v_fma_f32 v63, -v60, v239, v63
	v_fma_f32 v62, -v61, v240, v62
	v_fma_f32 v63, -v58, v241, v63
	ds_read_b128 v[226:229], v137 offset:38176
	s_waitcnt lgkmcnt(8)
	v_fma_f32 v62, -v59, v248, v62
	v_fma_f32 v63, -v56, v249, v63
	v_fma_f32 v62, -v57, v250, v62
	v_fma_f32 v63, -v54, v251, v63
	ds_read_b128 v[230:233], v137 offset:38192
	s_waitcnt lgkmcnt(8)
	v_fma_f32 v62, -v55, v252, v62
	v_fma_f32 v63, -v52, v253, v63
	v_fma_f32 v62, -v53, v254, v62
	v_fma_f32 v63, -v50, v255, v63
	ds_read_b128 v[234:237], v137 offset:38208
	s_waitcnt lgkmcnt(8)
	v_fma_f32 v62, -v51, v202, v62
	v_fma_f32 v63, -v48, v203, v63
	v_fma_f32 v62, -v49, v204, v62
	v_fma_f32 v63, -v46, v205, v63
	ds_read_b128 v[238:241], v137 offset:38224
	s_waitcnt lgkmcnt(8)
	v_fma_f32 v62, -v47, v206, v62
	v_fma_f32 v63, -v44, v207, v63
	v_fma_f32 v62, -v45, v208, v62
	v_fma_f32 v63, -v42, v209, v63
	ds_read_b128 v[248:251], v137 offset:38240
	s_waitcnt lgkmcnt(8)
	v_fma_f32 v62, -v43, v210, v62
	v_fma_f32 v63, -v40, v211, v63
	v_fma_f32 v62, -v41, v212, v62
	v_fma_f32 v63, -v38, v213, v63
	ds_read_b128 v[252:255], v137 offset:38256
	s_waitcnt lgkmcnt(8)
	v_fma_f32 v62, -v39, v214, v62
	v_fma_f32 v63, -v36, v215, v63
	v_fma_f32 v62, -v37, v216, v62
	v_fma_f32 v35, -v34, v217, v63
	v_add_f32_e32 v35, v62, v35
	s_nop 0
	ds_read_b128 v[202:205], v137 offset:38272
	s_waitcnt lgkmcnt(8)
	v_fma_f32 v62, -v81, v218, v104
	v_fma_f32 v63, -v0, v219, 0
	v_fma_f32 v62, -v1, v220, v62
	v_fma_f32 v63, -v2, v221, v63
	ds_read_b128 v[206:209], v137 offset:38288
	s_waitcnt lgkmcnt(8)
	v_fma_f32 v62, -v3, v222, v62
	v_fma_f32 v63, -v4, v223, v63
	v_fma_f32 v62, -v5, v224, v62
	v_fma_f32 v63, -v7, v225, v63
	ds_read_b128 v[210:213], v137 offset:38304
	s_waitcnt lgkmcnt(8)
	v_fma_f32 v62, -v6, v226, v62
	v_fma_f32 v63, -v8, v227, v63
	v_fma_f32 v62, -v9, v228, v62
	v_fma_f32 v63, -v10, v229, v63
	ds_read_b128 v[214:217], v137 offset:38400
	s_waitcnt lgkmcnt(8)
	v_fma_f32 v62, -v11, v230, v62
	v_fma_f32 v63, -v60, v231, v63
	v_fma_f32 v62, -v61, v232, v62
	v_fma_f32 v63, -v58, v233, v63
	ds_read_b128 v[218:221], v137 offset:38416
	s_waitcnt lgkmcnt(8)
	v_fma_f32 v62, -v59, v234, v62
	v_fma_f32 v63, -v56, v235, v63
	v_fma_f32 v62, -v57, v236, v62
	v_fma_f32 v63, -v54, v237, v63
	ds_read_b128 v[222:225], v137 offset:38432
	s_waitcnt lgkmcnt(8)
	v_fma_f32 v62, -v55, v238, v62
	v_fma_f32 v63, -v52, v239, v63
	v_fma_f32 v62, -v53, v240, v62
	v_fma_f32 v63, -v50, v241, v63
	ds_read_b128 v[226:229], v137 offset:38448
	s_waitcnt lgkmcnt(8)
	v_fma_f32 v62, -v51, v248, v62
	v_fma_f32 v63, -v48, v249, v63
	v_fma_f32 v62, -v49, v250, v62
	v_fma_f32 v63, -v46, v251, v63
	ds_read_b128 v[230:233], v137 offset:38464
	s_waitcnt lgkmcnt(8)
	v_fma_f32 v62, -v47, v252, v62
	v_fma_f32 v63, -v44, v253, v63
	v_fma_f32 v62, -v45, v254, v62
	v_fma_f32 v63, -v42, v255, v63
	ds_read_b128 v[234:237], v137 offset:38480
	s_waitcnt lgkmcnt(8)
	v_fma_f32 v62, -v43, v202, v62
	v_fma_f32 v63, -v40, v203, v63
	v_fma_f32 v62, -v41, v204, v62
	v_fma_f32 v63, -v38, v205, v63
	ds_read_b128 v[238:241], v137 offset:38496
	s_waitcnt lgkmcnt(8)
	v_fma_f32 v62, -v39, v206, v62
	v_fma_f32 v63, -v36, v207, v63
	v_fma_f32 v62, -v37, v208, v62
	v_fma_f32 v63, -v34, v209, v63
	ds_read_b128 v[248:251], v137 offset:38512
	s_waitcnt lgkmcnt(8)
	v_fma_f32 v32, -v35, v210, v62
	v_add_f32_e32 v32, v63, v32
	s_nop 0
	ds_read_b128 v[252:255], v137 offset:38528
	s_waitcnt lgkmcnt(8)
	v_fma_f32 v62, -v81, v214, v103
	v_fma_f32 v63, -v0, v215, 0
	v_fma_f32 v62, -v1, v216, v62
	v_fma_f32 v63, -v2, v217, v63
	ds_read_b128 v[202:205], v137 offset:38544
	s_waitcnt lgkmcnt(8)
	v_fma_f32 v62, -v3, v218, v62
	v_fma_f32 v63, -v4, v219, v63
	v_fma_f32 v62, -v5, v220, v62
	v_fma_f32 v63, -v7, v221, v63
	ds_read_b128 v[206:209], v137 offset:38560
	s_waitcnt lgkmcnt(8)
	v_fma_f32 v62, -v6, v222, v62
	v_fma_f32 v63, -v8, v223, v63
	v_fma_f32 v62, -v9, v224, v62
	v_fma_f32 v63, -v10, v225, v63
	ds_read_b128 v[210:213], v137 offset:38656
	s_waitcnt lgkmcnt(8)
	v_fma_f32 v62, -v11, v226, v62
	v_fma_f32 v63, -v60, v227, v63
	v_fma_f32 v62, -v61, v228, v62
	v_fma_f32 v63, -v58, v229, v63
	ds_read_b128 v[214:217], v137 offset:38672
	s_waitcnt lgkmcnt(8)
	v_fma_f32 v62, -v59, v230, v62
	v_fma_f32 v63, -v56, v231, v63
	v_fma_f32 v62, -v57, v232, v62
	v_fma_f32 v63, -v54, v233, v63
	ds_read_b128 v[218:221], v137 offset:38688
	s_waitcnt lgkmcnt(8)
	v_fma_f32 v62, -v55, v234, v62
	v_fma_f32 v63, -v52, v235, v63
	v_fma_f32 v62, -v53, v236, v62
	v_fma_f32 v63, -v50, v237, v63
	ds_read_b128 v[222:225], v137 offset:38704
	s_waitcnt lgkmcnt(8)
	v_fma_f32 v62, -v51, v238, v62
	v_fma_f32 v63, -v48, v239, v63
	v_fma_f32 v62, -v49, v240, v62
	v_fma_f32 v63, -v46, v241, v63
	ds_read_b128 v[226:229], v137 offset:38720
	s_waitcnt lgkmcnt(8)
	v_fma_f32 v62, -v47, v248, v62
	v_fma_f32 v63, -v44, v249, v63
	v_fma_f32 v62, -v45, v250, v62
	v_fma_f32 v63, -v42, v251, v63
	ds_read_b128 v[230:233], v137 offset:38736
	s_waitcnt lgkmcnt(8)
	v_fma_f32 v62, -v43, v252, v62
	v_fma_f32 v63, -v40, v253, v63
	v_fma_f32 v62, -v41, v254, v62
	v_fma_f32 v63, -v38, v255, v63
	ds_read_b128 v[234:237], v137 offset:38752
	s_waitcnt lgkmcnt(8)
	v_fma_f32 v62, -v39, v202, v62
	v_fma_f32 v63, -v36, v203, v63
	v_fma_f32 v62, -v37, v204, v62
	v_fma_f32 v63, -v34, v205, v63
	ds_read_b128 v[238:241], v137 offset:38768
	s_waitcnt lgkmcnt(8)
	v_fma_f32 v62, -v35, v206, v62
	v_fma_f32 v33, -v32, v207, v63
	v_add_f32_e32 v33, v62, v33
	s_nop 0
	ds_read_b128 v[248:251], v137 offset:38784
	s_waitcnt lgkmcnt(8)
	v_fma_f32 v62, -v81, v210, v101
	v_fma_f32 v63, -v0, v211, 0
	v_fma_f32 v62, -v1, v212, v62
	v_fma_f32 v63, -v2, v213, v63
	ds_read_b128 v[252:255], v137 offset:38800
	s_waitcnt lgkmcnt(8)
	v_fma_f32 v62, -v3, v214, v62
	v_fma_f32 v63, -v4, v215, v63
	v_fma_f32 v62, -v5, v216, v62
	v_fma_f32 v63, -v7, v217, v63
	ds_read_b128 v[202:205], v137 offset:38816
	s_waitcnt lgkmcnt(8)
	v_fma_f32 v62, -v6, v218, v62
	v_fma_f32 v63, -v8, v219, v63
	v_fma_f32 v62, -v9, v220, v62
	v_fma_f32 v63, -v10, v221, v63
	ds_read_b128 v[206:209], v137 offset:38912
	s_waitcnt lgkmcnt(8)
	v_fma_f32 v62, -v11, v222, v62
	v_fma_f32 v63, -v60, v223, v63
	v_fma_f32 v62, -v61, v224, v62
	v_fma_f32 v63, -v58, v225, v63
	ds_read_b128 v[210:213], v137 offset:38928
	s_waitcnt lgkmcnt(8)
	v_fma_f32 v62, -v59, v226, v62
	v_fma_f32 v63, -v56, v227, v63
	v_fma_f32 v62, -v57, v228, v62
	v_fma_f32 v63, -v54, v229, v63
	ds_read_b128 v[214:217], v137 offset:38944
	s_waitcnt lgkmcnt(8)
	v_fma_f32 v62, -v55, v230, v62
	v_fma_f32 v63, -v52, v231, v63
	v_fma_f32 v62, -v53, v232, v62
	v_fma_f32 v63, -v50, v233, v63
	ds_read_b128 v[218:221], v137 offset:38960
	s_waitcnt lgkmcnt(8)
	v_fma_f32 v62, -v51, v234, v62
	v_fma_f32 v63, -v48, v235, v63
	v_fma_f32 v62, -v49, v236, v62
	v_fma_f32 v63, -v46, v237, v63
	ds_read_b128 v[222:225], v137 offset:38976
	s_waitcnt lgkmcnt(8)
	v_fma_f32 v62, -v47, v238, v62
	v_fma_f32 v63, -v44, v239, v63
	v_fma_f32 v62, -v45, v240, v62
	v_fma_f32 v63, -v42, v241, v63
	ds_read_b128 v[226:229], v137 offset:38992
	s_waitcnt lgkmcnt(8)
	v_fma_f32 v62, -v43, v248, v62
	v_fma_f32 v63, -v40, v249, v63
	v_fma_f32 v62, -v41, v250, v62
	v_fma_f32 v63, -v38, v251, v63
	ds_read_b128 v[230:233], v137 offset:39008
	s_waitcnt lgkmcnt(8)
	v_fma_f32 v62, -v39, v252, v62
	v_fma_f32 v63, -v36, v253, v63
	v_fma_f32 v62, -v37, v254, v62
	v_fma_f32 v63, -v34, v255, v63
	ds_read_b128 v[234:237], v137 offset:39024
	s_waitcnt lgkmcnt(8)
	v_fma_f32 v62, -v35, v202, v62
	v_fma_f32 v63, -v32, v203, v63
	v_fma_f32 v30, -v33, v204, v62
	v_add_f32_e32 v30, v63, v30
	s_nop 0
	ds_read_b128 v[238:241], v137 offset:39040
	s_waitcnt lgkmcnt(8)
	v_fma_f32 v62, -v81, v206, v102
	v_fma_f32 v63, -v0, v207, 0
	v_fma_f32 v62, -v1, v208, v62
	v_fma_f32 v63, -v2, v209, v63
	ds_read_b128 v[248:251], v137 offset:39056
	s_waitcnt lgkmcnt(8)
	v_fma_f32 v62, -v3, v210, v62
	v_fma_f32 v63, -v4, v211, v63
	v_fma_f32 v62, -v5, v212, v62
	v_fma_f32 v63, -v7, v213, v63
	ds_read_b128 v[252:255], v137 offset:39072
	s_waitcnt lgkmcnt(8)
	v_fma_f32 v62, -v6, v214, v62
	v_fma_f32 v63, -v8, v215, v63
	v_fma_f32 v62, -v9, v216, v62
	v_fma_f32 v63, -v10, v217, v63
	ds_read_b128 v[202:205], v137 offset:39168
	s_waitcnt lgkmcnt(8)
	v_fma_f32 v62, -v11, v218, v62
	v_fma_f32 v63, -v60, v219, v63
	v_fma_f32 v62, -v61, v220, v62
	v_fma_f32 v63, -v58, v221, v63
	ds_read_b128 v[206:209], v137 offset:39184
	s_waitcnt lgkmcnt(8)
	v_fma_f32 v62, -v59, v222, v62
	v_fma_f32 v63, -v56, v223, v63
	v_fma_f32 v62, -v57, v224, v62
	v_fma_f32 v63, -v54, v225, v63
	ds_read_b128 v[210:213], v137 offset:39200
	s_waitcnt lgkmcnt(8)
	v_fma_f32 v62, -v55, v226, v62
	v_fma_f32 v63, -v52, v227, v63
	v_fma_f32 v62, -v53, v228, v62
	v_fma_f32 v63, -v50, v229, v63
	ds_read_b128 v[214:217], v137 offset:39216
	s_waitcnt lgkmcnt(8)
	v_fma_f32 v62, -v51, v230, v62
	v_fma_f32 v63, -v48, v231, v63
	v_fma_f32 v62, -v49, v232, v62
	v_fma_f32 v63, -v46, v233, v63
	ds_read_b128 v[218:221], v137 offset:39232
	s_waitcnt lgkmcnt(8)
	v_fma_f32 v62, -v47, v234, v62
	v_fma_f32 v63, -v44, v235, v63
	v_fma_f32 v62, -v45, v236, v62
	v_fma_f32 v63, -v42, v237, v63
	ds_read_b128 v[222:225], v137 offset:39248
	s_waitcnt lgkmcnt(8)
	v_fma_f32 v62, -v43, v238, v62
	v_fma_f32 v63, -v40, v239, v63
	v_fma_f32 v62, -v41, v240, v62
	v_fma_f32 v63, -v38, v241, v63
	ds_read_b128 v[226:229], v137 offset:39264
	s_waitcnt lgkmcnt(8)
	v_fma_f32 v62, -v39, v248, v62
	v_fma_f32 v63, -v36, v249, v63
	v_fma_f32 v62, -v37, v250, v62
	v_fma_f32 v63, -v34, v251, v63
	ds_read_b128 v[230:233], v137 offset:39280
	s_waitcnt lgkmcnt(8)
	v_fma_f32 v62, -v35, v252, v62
	v_fma_f32 v63, -v32, v253, v63
	v_fma_f32 v62, -v33, v254, v62
	v_fma_f32 v31, -v30, v255, v63
	v_add_f32_e32 v31, v62, v31
	s_nop 0
	ds_read_b128 v[234:237], v137 offset:39296
	s_waitcnt lgkmcnt(8)
	v_fma_f32 v62, -v81, v202, v100
	v_fma_f32 v63, -v0, v203, 0
	v_fma_f32 v62, -v1, v204, v62
	v_fma_f32 v63, -v2, v205, v63
	ds_read_b128 v[238:241], v137 offset:39312
	s_waitcnt lgkmcnt(8)
	v_fma_f32 v62, -v3, v206, v62
	v_fma_f32 v63, -v4, v207, v63
	v_fma_f32 v62, -v5, v208, v62
	v_fma_f32 v63, -v7, v209, v63
	ds_read_b128 v[248:251], v137 offset:39328
	s_waitcnt lgkmcnt(8)
	v_fma_f32 v62, -v6, v210, v62
	v_fma_f32 v63, -v8, v211, v63
	v_fma_f32 v62, -v9, v212, v62
	v_fma_f32 v63, -v10, v213, v63
	ds_read_b128 v[252:255], v137 offset:39344
	s_waitcnt lgkmcnt(8)
	v_fma_f32 v62, -v11, v214, v62
	v_fma_f32 v63, -v60, v215, v63
	v_fma_f32 v62, -v61, v216, v62
	v_fma_f32 v63, -v58, v217, v63
	ds_read_b128 v[202:205], v137 offset:39424
	s_waitcnt lgkmcnt(8)
	v_fma_f32 v62, -v59, v218, v62
	v_fma_f32 v63, -v56, v219, v63
	v_fma_f32 v62, -v57, v220, v62
	v_fma_f32 v63, -v54, v221, v63
	ds_read_b128 v[206:209], v137 offset:39440
	s_waitcnt lgkmcnt(8)
	v_fma_f32 v62, -v55, v222, v62
	v_fma_f32 v63, -v52, v223, v63
	v_fma_f32 v62, -v53, v224, v62
	v_fma_f32 v63, -v50, v225, v63
	ds_read_b128 v[210:213], v137 offset:39456
	s_waitcnt lgkmcnt(8)
	v_fma_f32 v62, -v51, v226, v62
	v_fma_f32 v63, -v48, v227, v63
	v_fma_f32 v62, -v49, v228, v62
	v_fma_f32 v63, -v46, v229, v63
	ds_read_b128 v[214:217], v137 offset:39472
	s_waitcnt lgkmcnt(8)
	v_fma_f32 v62, -v47, v230, v62
	v_fma_f32 v63, -v44, v231, v63
	v_fma_f32 v62, -v45, v232, v62
	v_fma_f32 v63, -v42, v233, v63
	ds_read_b128 v[218:221], v137 offset:39488
	s_waitcnt lgkmcnt(8)
	v_fma_f32 v62, -v43, v234, v62
	v_fma_f32 v63, -v40, v235, v63
	v_fma_f32 v62, -v41, v236, v62
	v_fma_f32 v63, -v38, v237, v63
	ds_read_b128 v[222:225], v137 offset:39504
	s_waitcnt lgkmcnt(8)
	v_fma_f32 v62, -v39, v238, v62
	v_fma_f32 v63, -v36, v239, v63
	v_fma_f32 v62, -v37, v240, v62
	v_fma_f32 v63, -v34, v241, v63
	ds_read_b128 v[226:229], v137 offset:39520
	s_waitcnt lgkmcnt(8)
	v_fma_f32 v62, -v35, v248, v62
	v_fma_f32 v63, -v32, v249, v63
	v_fma_f32 v62, -v33, v250, v62
	v_fma_f32 v63, -v30, v251, v63
	ds_read_b128 v[230:233], v137 offset:39536
	s_waitcnt lgkmcnt(8)
	v_fma_f32 v28, -v31, v252, v62
	v_add_f32_e32 v28, v63, v28
	s_nop 0
	ds_read_b128 v[234:237], v137 offset:39552
	s_waitcnt lgkmcnt(8)
	v_fma_f32 v62, -v81, v202, v98
	v_fma_f32 v63, -v0, v203, 0
	v_fma_f32 v62, -v1, v204, v62
	v_fma_f32 v63, -v2, v205, v63
	ds_read_b128 v[238:241], v137 offset:39568
	s_waitcnt lgkmcnt(8)
	v_fma_f32 v62, -v3, v206, v62
	v_fma_f32 v63, -v4, v207, v63
	v_fma_f32 v62, -v5, v208, v62
	v_fma_f32 v63, -v7, v209, v63
	ds_read_b128 v[248:251], v137 offset:39584
	s_waitcnt lgkmcnt(8)
	v_fma_f32 v62, -v6, v210, v62
	v_fma_f32 v63, -v8, v211, v63
	v_fma_f32 v62, -v9, v212, v62
	v_fma_f32 v63, -v10, v213, v63
	ds_read_b128 v[252:255], v137 offset:39600
	s_waitcnt lgkmcnt(8)
	v_fma_f32 v62, -v11, v214, v62
	v_fma_f32 v63, -v60, v215, v63
	v_fma_f32 v62, -v61, v216, v62
	v_fma_f32 v63, -v58, v217, v63
	ds_read_b128 v[202:205], v137 offset:39680
	s_waitcnt lgkmcnt(8)
	v_fma_f32 v62, -v59, v218, v62
	v_fma_f32 v63, -v56, v219, v63
	v_fma_f32 v62, -v57, v220, v62
	v_fma_f32 v63, -v54, v221, v63
	ds_read_b128 v[206:209], v137 offset:39696
	s_waitcnt lgkmcnt(8)
	v_fma_f32 v62, -v55, v222, v62
	v_fma_f32 v63, -v52, v223, v63
	v_fma_f32 v62, -v53, v224, v62
	v_fma_f32 v63, -v50, v225, v63
	ds_read_b128 v[210:213], v137 offset:39712
	s_waitcnt lgkmcnt(8)
	v_fma_f32 v62, -v51, v226, v62
	v_fma_f32 v63, -v48, v227, v63
	v_fma_f32 v62, -v49, v228, v62
	v_fma_f32 v63, -v46, v229, v63
	ds_read_b128 v[214:217], v137 offset:39728
	s_waitcnt lgkmcnt(8)
	v_fma_f32 v62, -v47, v230, v62
	v_fma_f32 v63, -v44, v231, v63
	v_fma_f32 v62, -v45, v232, v62
	v_fma_f32 v63, -v42, v233, v63
	ds_read_b128 v[218:221], v137 offset:39744
	s_waitcnt lgkmcnt(8)
	v_fma_f32 v62, -v43, v234, v62
	v_fma_f32 v63, -v40, v235, v63
	v_fma_f32 v62, -v41, v236, v62
	v_fma_f32 v63, -v38, v237, v63
	ds_read_b128 v[222:225], v137 offset:39760
	s_waitcnt lgkmcnt(8)
	v_fma_f32 v62, -v39, v238, v62
	v_fma_f32 v63, -v36, v239, v63
	v_fma_f32 v62, -v37, v240, v62
	v_fma_f32 v63, -v34, v241, v63
	ds_read_b128 v[226:229], v137 offset:39776
	s_waitcnt lgkmcnt(8)
	v_fma_f32 v62, -v35, v248, v62
	v_fma_f32 v63, -v32, v249, v63
	v_fma_f32 v62, -v33, v250, v62
	v_fma_f32 v63, -v30, v251, v63
	ds_read_b128 v[230:233], v137 offset:39792
	s_waitcnt lgkmcnt(8)
	v_fma_f32 v62, -v31, v252, v62
	v_fma_f32 v29, -v28, v253, v63
	v_add_f32_e32 v29, v62, v29
	s_nop 0
	ds_read_b128 v[234:237], v137 offset:39808
	s_waitcnt lgkmcnt(8)
	v_fma_f32 v62, -v81, v202, v99
	v_fma_f32 v63, -v0, v203, 0
	v_fma_f32 v62, -v1, v204, v62
	v_fma_f32 v63, -v2, v205, v63
	ds_read_b128 v[238:241], v137 offset:39824
	s_waitcnt lgkmcnt(8)
	v_fma_f32 v62, -v3, v206, v62
	v_fma_f32 v63, -v4, v207, v63
	v_fma_f32 v62, -v5, v208, v62
	v_fma_f32 v63, -v7, v209, v63
	ds_read_b128 v[248:251], v137 offset:39840
	s_waitcnt lgkmcnt(8)
	v_fma_f32 v62, -v6, v210, v62
	v_fma_f32 v63, -v8, v211, v63
	v_fma_f32 v62, -v9, v212, v62
	v_fma_f32 v63, -v10, v213, v63
	ds_read_b128 v[252:255], v137 offset:39856
	s_waitcnt lgkmcnt(8)
	v_fma_f32 v62, -v11, v214, v62
	v_fma_f32 v63, -v60, v215, v63
	v_fma_f32 v62, -v61, v216, v62
	v_fma_f32 v63, -v58, v217, v63
	ds_read_b128 v[202:205], v137 offset:39936
	s_waitcnt lgkmcnt(8)
	v_fma_f32 v62, -v59, v218, v62
	v_fma_f32 v63, -v56, v219, v63
	v_fma_f32 v62, -v57, v220, v62
	v_fma_f32 v63, -v54, v221, v63
	ds_read_b128 v[206:209], v137 offset:39952
	s_waitcnt lgkmcnt(8)
	v_fma_f32 v62, -v55, v222, v62
	v_fma_f32 v63, -v52, v223, v63
	v_fma_f32 v62, -v53, v224, v62
	v_fma_f32 v63, -v50, v225, v63
	ds_read_b128 v[210:213], v137 offset:39968
	s_waitcnt lgkmcnt(8)
	v_fma_f32 v62, -v51, v226, v62
	v_fma_f32 v63, -v48, v227, v63
	v_fma_f32 v62, -v49, v228, v62
	v_fma_f32 v63, -v46, v229, v63
	ds_read_b128 v[214:217], v137 offset:39984
	s_waitcnt lgkmcnt(8)
	v_fma_f32 v62, -v47, v230, v62
	v_fma_f32 v63, -v44, v231, v63
	v_fma_f32 v62, -v45, v232, v62
	v_fma_f32 v63, -v42, v233, v63
	ds_read_b128 v[218:221], v137 offset:40000
	s_waitcnt lgkmcnt(8)
	v_fma_f32 v62, -v43, v234, v62
	v_fma_f32 v63, -v40, v235, v63
	v_fma_f32 v62, -v41, v236, v62
	v_fma_f32 v63, -v38, v237, v63
	ds_read_b128 v[222:225], v137 offset:40016
	s_waitcnt lgkmcnt(8)
	v_fma_f32 v62, -v39, v238, v62
	v_fma_f32 v63, -v36, v239, v63
	v_fma_f32 v62, -v37, v240, v62
	v_fma_f32 v63, -v34, v241, v63
	ds_read_b128 v[226:229], v137 offset:40032
	s_waitcnt lgkmcnt(8)
	v_fma_f32 v62, -v35, v248, v62
	v_fma_f32 v63, -v32, v249, v63
	v_fma_f32 v62, -v33, v250, v62
	v_fma_f32 v63, -v30, v251, v63
	ds_read_b128 v[230:233], v137 offset:40048
	s_waitcnt lgkmcnt(8)
	v_fma_f32 v62, -v31, v252, v62
	v_fma_f32 v63, -v28, v253, v63
	v_fma_f32 v26, -v29, v254, v62
	v_add_f32_e32 v26, v63, v26
	s_nop 0
	ds_read_b128 v[234:237], v137 offset:40064
	s_waitcnt lgkmcnt(8)
	v_fma_f32 v62, -v81, v202, v97
	v_fma_f32 v63, -v0, v203, 0
	v_fma_f32 v62, -v1, v204, v62
	v_fma_f32 v63, -v2, v205, v63
	ds_read_b128 v[238:241], v137 offset:40080
	s_waitcnt lgkmcnt(8)
	v_fma_f32 v62, -v3, v206, v62
	v_fma_f32 v63, -v4, v207, v63
	v_fma_f32 v62, -v5, v208, v62
	v_fma_f32 v63, -v7, v209, v63
	ds_read_b128 v[248:251], v137 offset:40096
	s_waitcnt lgkmcnt(8)
	v_fma_f32 v62, -v6, v210, v62
	v_fma_f32 v63, -v8, v211, v63
	v_fma_f32 v62, -v9, v212, v62
	v_fma_f32 v63, -v10, v213, v63
	ds_read_b128 v[252:255], v137 offset:40112
	s_waitcnt lgkmcnt(8)
	v_fma_f32 v62, -v11, v214, v62
	v_fma_f32 v63, -v60, v215, v63
	v_fma_f32 v62, -v61, v216, v62
	v_fma_f32 v63, -v58, v217, v63
	ds_read_b128 v[202:205], v137 offset:40192
	s_waitcnt lgkmcnt(8)
	v_fma_f32 v62, -v59, v218, v62
	v_fma_f32 v63, -v56, v219, v63
	v_fma_f32 v62, -v57, v220, v62
	v_fma_f32 v63, -v54, v221, v63
	ds_read_b128 v[206:209], v137 offset:40208
	s_waitcnt lgkmcnt(8)
	v_fma_f32 v62, -v55, v222, v62
	v_fma_f32 v63, -v52, v223, v63
	v_fma_f32 v62, -v53, v224, v62
	v_fma_f32 v63, -v50, v225, v63
	ds_read_b128 v[210:213], v137 offset:40224
	s_waitcnt lgkmcnt(8)
	v_fma_f32 v62, -v51, v226, v62
	v_fma_f32 v63, -v48, v227, v63
	v_fma_f32 v62, -v49, v228, v62
	v_fma_f32 v63, -v46, v229, v63
	ds_read_b128 v[214:217], v137 offset:40240
	s_waitcnt lgkmcnt(8)
	v_fma_f32 v62, -v47, v230, v62
	v_fma_f32 v63, -v44, v231, v63
	v_fma_f32 v62, -v45, v232, v62
	v_fma_f32 v63, -v42, v233, v63
	ds_read_b128 v[218:221], v137 offset:40256
	s_waitcnt lgkmcnt(8)
	v_fma_f32 v62, -v43, v234, v62
	v_fma_f32 v63, -v40, v235, v63
	v_fma_f32 v62, -v41, v236, v62
	v_fma_f32 v63, -v38, v237, v63
	ds_read_b128 v[222:225], v137 offset:40272
	s_waitcnt lgkmcnt(8)
	v_fma_f32 v62, -v39, v238, v62
	v_fma_f32 v63, -v36, v239, v63
	v_fma_f32 v62, -v37, v240, v62
	v_fma_f32 v63, -v34, v241, v63
	ds_read_b128 v[226:229], v137 offset:40288
	s_waitcnt lgkmcnt(8)
	v_fma_f32 v62, -v35, v248, v62
	v_fma_f32 v63, -v32, v249, v63
	v_fma_f32 v62, -v33, v250, v62
	v_fma_f32 v63, -v30, v251, v63
	ds_read_b128 v[230:233], v137 offset:40304
	s_waitcnt lgkmcnt(8)
	v_fma_f32 v62, -v31, v252, v62
	v_fma_f32 v63, -v28, v253, v63
	v_fma_f32 v62, -v29, v254, v62
	v_fma_f32 v27, -v26, v255, v63
	v_add_f32_e32 v27, v62, v27
	s_nop 0
	ds_read_b128 v[234:237], v137 offset:40320
	s_waitcnt lgkmcnt(8)
	v_fma_f32 v62, -v81, v202, v96
	v_fma_f32 v63, -v0, v203, 0
	v_fma_f32 v62, -v1, v204, v62
	v_fma_f32 v63, -v2, v205, v63
	ds_read_b128 v[238:241], v137 offset:40336
	s_waitcnt lgkmcnt(8)
	v_fma_f32 v62, -v3, v206, v62
	v_fma_f32 v63, -v4, v207, v63
	v_fma_f32 v62, -v5, v208, v62
	v_fma_f32 v63, -v7, v209, v63
	ds_read_b128 v[248:251], v137 offset:40352
	s_waitcnt lgkmcnt(8)
	v_fma_f32 v62, -v6, v210, v62
	v_fma_f32 v63, -v8, v211, v63
	v_fma_f32 v62, -v9, v212, v62
	v_fma_f32 v63, -v10, v213, v63
	ds_read_b128 v[252:255], v137 offset:40368
	s_waitcnt lgkmcnt(8)
	v_fma_f32 v62, -v11, v214, v62
	v_fma_f32 v63, -v60, v215, v63
	v_fma_f32 v62, -v61, v216, v62
	v_fma_f32 v63, -v58, v217, v63
	ds_read_b128 v[202:205], v137 offset:40384
	s_waitcnt lgkmcnt(8)
	v_fma_f32 v62, -v59, v218, v62
	v_fma_f32 v63, -v56, v219, v63
	v_fma_f32 v62, -v57, v220, v62
	v_fma_f32 v63, -v54, v221, v63
	ds_read_b128 v[206:209], v137 offset:40448
	s_waitcnt lgkmcnt(8)
	v_fma_f32 v62, -v55, v222, v62
	v_fma_f32 v63, -v52, v223, v63
	v_fma_f32 v62, -v53, v224, v62
	v_fma_f32 v63, -v50, v225, v63
	ds_read_b128 v[210:213], v137 offset:40464
	s_waitcnt lgkmcnt(8)
	v_fma_f32 v62, -v51, v226, v62
	v_fma_f32 v63, -v48, v227, v63
	v_fma_f32 v62, -v49, v228, v62
	v_fma_f32 v63, -v46, v229, v63
	ds_read_b128 v[214:217], v137 offset:40480
	s_waitcnt lgkmcnt(8)
	v_fma_f32 v62, -v47, v230, v62
	v_fma_f32 v63, -v44, v231, v63
	v_fma_f32 v62, -v45, v232, v62
	v_fma_f32 v63, -v42, v233, v63
	ds_read_b128 v[218:221], v137 offset:40496
	s_waitcnt lgkmcnt(8)
	v_fma_f32 v62, -v43, v234, v62
	v_fma_f32 v63, -v40, v235, v63
	v_fma_f32 v62, -v41, v236, v62
	v_fma_f32 v63, -v38, v237, v63
	ds_read_b128 v[222:225], v137 offset:40512
	s_waitcnt lgkmcnt(8)
	v_fma_f32 v62, -v39, v238, v62
	v_fma_f32 v63, -v36, v239, v63
	v_fma_f32 v62, -v37, v240, v62
	v_fma_f32 v63, -v34, v241, v63
	ds_read_b128 v[226:229], v137 offset:40528
	s_waitcnt lgkmcnt(8)
	v_fma_f32 v62, -v35, v248, v62
	v_fma_f32 v63, -v32, v249, v63
	v_fma_f32 v62, -v33, v250, v62
	v_fma_f32 v63, -v30, v251, v63
	ds_read_b128 v[230:233], v137 offset:40544
	s_waitcnt lgkmcnt(8)
	v_fma_f32 v62, -v31, v252, v62
	v_fma_f32 v63, -v28, v253, v63
	v_fma_f32 v62, -v29, v254, v62
	v_fma_f32 v63, -v26, v255, v63
	ds_read_b128 v[234:237], v137 offset:40560
	s_waitcnt lgkmcnt(8)
	v_fma_f32 v24, -v27, v202, v62
	v_add_f32_e32 v24, v63, v24
	s_nop 0
	ds_read_b128 v[238:241], v137 offset:40576
	s_waitcnt lgkmcnt(8)
	v_fma_f32 v62, -v81, v206, v95
	v_fma_f32 v63, -v0, v207, 0
	v_fma_f32 v62, -v1, v208, v62
	v_fma_f32 v63, -v2, v209, v63
	ds_read_b128 v[248:251], v137 offset:40592
	s_waitcnt lgkmcnt(8)
	v_fma_f32 v62, -v3, v210, v62
	v_fma_f32 v63, -v4, v211, v63
	v_fma_f32 v62, -v5, v212, v62
	v_fma_f32 v63, -v7, v213, v63
	ds_read_b128 v[252:255], v137 offset:40608
	s_waitcnt lgkmcnt(8)
	v_fma_f32 v62, -v6, v214, v62
	v_fma_f32 v63, -v8, v215, v63
	v_fma_f32 v62, -v9, v216, v62
	v_fma_f32 v63, -v10, v217, v63
	ds_read_b128 v[202:205], v137 offset:40624
	s_waitcnt lgkmcnt(8)
	v_fma_f32 v62, -v11, v218, v62
	v_fma_f32 v63, -v60, v219, v63
	v_fma_f32 v62, -v61, v220, v62
	v_fma_f32 v63, -v58, v221, v63
	ds_read_b128 v[206:209], v137 offset:40640
	s_waitcnt lgkmcnt(8)
	v_fma_f32 v62, -v59, v222, v62
	v_fma_f32 v63, -v56, v223, v63
	v_fma_f32 v62, -v57, v224, v62
	v_fma_f32 v63, -v54, v225, v63
	ds_read_b128 v[210:213], v137 offset:40704
	s_waitcnt lgkmcnt(8)
	v_fma_f32 v62, -v55, v226, v62
	v_fma_f32 v63, -v52, v227, v63
	v_fma_f32 v62, -v53, v228, v62
	v_fma_f32 v63, -v50, v229, v63
	ds_read_b128 v[214:217], v137 offset:40720
	s_waitcnt lgkmcnt(8)
	v_fma_f32 v62, -v51, v230, v62
	v_fma_f32 v63, -v48, v231, v63
	v_fma_f32 v62, -v49, v232, v62
	v_fma_f32 v63, -v46, v233, v63
	ds_read_b128 v[218:221], v137 offset:40736
	s_waitcnt lgkmcnt(8)
	v_fma_f32 v62, -v47, v234, v62
	v_fma_f32 v63, -v44, v235, v63
	v_fma_f32 v62, -v45, v236, v62
	v_fma_f32 v63, -v42, v237, v63
	ds_read_b128 v[222:225], v137 offset:40752
	s_waitcnt lgkmcnt(8)
	v_fma_f32 v62, -v43, v238, v62
	v_fma_f32 v63, -v40, v239, v63
	v_fma_f32 v62, -v41, v240, v62
	v_fma_f32 v63, -v38, v241, v63
	ds_read_b128 v[226:229], v137 offset:40768
	s_waitcnt lgkmcnt(8)
	v_fma_f32 v62, -v39, v248, v62
	v_fma_f32 v63, -v36, v249, v63
	v_fma_f32 v62, -v37, v250, v62
	v_fma_f32 v63, -v34, v251, v63
	ds_read_b128 v[230:233], v137 offset:40784
	s_waitcnt lgkmcnt(8)
	v_fma_f32 v62, -v35, v252, v62
	v_fma_f32 v63, -v32, v253, v63
	v_fma_f32 v62, -v33, v254, v62
	v_fma_f32 v63, -v30, v255, v63
	ds_read_b128 v[234:237], v137 offset:40800
	s_waitcnt lgkmcnt(8)
	v_fma_f32 v62, -v31, v202, v62
	v_fma_f32 v63, -v28, v203, v63
	v_fma_f32 v62, -v29, v204, v62
	v_fma_f32 v63, -v26, v205, v63
	ds_read_b128 v[238:241], v137 offset:40816
	s_waitcnt lgkmcnt(8)
	v_fma_f32 v62, -v27, v206, v62
	v_fma_f32 v25, -v24, v207, v63
	v_add_f32_e32 v25, v62, v25
	s_nop 0
	ds_read_b128 v[248:251], v137 offset:40832
	s_waitcnt lgkmcnt(8)
	v_fma_f32 v62, -v81, v210, v93
	v_fma_f32 v63, -v0, v211, 0
	v_fma_f32 v62, -v1, v212, v62
	v_fma_f32 v63, -v2, v213, v63
	ds_read_b128 v[252:255], v137 offset:40848
	s_waitcnt lgkmcnt(8)
	v_fma_f32 v62, -v3, v214, v62
	v_fma_f32 v63, -v4, v215, v63
	v_fma_f32 v62, -v5, v216, v62
	v_fma_f32 v63, -v7, v217, v63
	ds_read_b128 v[202:205], v137 offset:40864
	s_waitcnt lgkmcnt(8)
	v_fma_f32 v62, -v6, v218, v62
	v_fma_f32 v63, -v8, v219, v63
	v_fma_f32 v62, -v9, v220, v62
	v_fma_f32 v63, -v10, v221, v63
	ds_read_b128 v[206:209], v137 offset:40880
	s_waitcnt lgkmcnt(8)
	v_fma_f32 v62, -v11, v222, v62
	v_fma_f32 v63, -v60, v223, v63
	v_fma_f32 v62, -v61, v224, v62
	v_fma_f32 v63, -v58, v225, v63
	ds_read_b128 v[210:213], v137 offset:40896
	s_waitcnt lgkmcnt(8)
	v_fma_f32 v62, -v59, v226, v62
	v_fma_f32 v63, -v56, v227, v63
	v_fma_f32 v62, -v57, v228, v62
	v_fma_f32 v63, -v54, v229, v63
	ds_read_b128 v[214:217], v137 offset:40960
	s_waitcnt lgkmcnt(8)
	v_fma_f32 v62, -v55, v230, v62
	v_fma_f32 v63, -v52, v231, v63
	v_fma_f32 v62, -v53, v232, v62
	v_fma_f32 v63, -v50, v233, v63
	ds_read_b128 v[218:221], v137 offset:40976
	s_waitcnt lgkmcnt(8)
	v_fma_f32 v62, -v51, v234, v62
	v_fma_f32 v63, -v48, v235, v63
	v_fma_f32 v62, -v49, v236, v62
	v_fma_f32 v63, -v46, v237, v63
	ds_read_b128 v[222:225], v137 offset:40992
	s_waitcnt lgkmcnt(8)
	v_fma_f32 v62, -v47, v238, v62
	v_fma_f32 v63, -v44, v239, v63
	v_fma_f32 v62, -v45, v240, v62
	v_fma_f32 v63, -v42, v241, v63
	ds_read_b128 v[226:229], v137 offset:41008
	s_waitcnt lgkmcnt(8)
	v_fma_f32 v62, -v43, v248, v62
	v_fma_f32 v63, -v40, v249, v63
	v_fma_f32 v62, -v41, v250, v62
	v_fma_f32 v63, -v38, v251, v63
	ds_read_b128 v[230:233], v137 offset:41024
	s_waitcnt lgkmcnt(8)
	v_fma_f32 v62, -v39, v252, v62
	v_fma_f32 v63, -v36, v253, v63
	v_fma_f32 v62, -v37, v254, v62
	v_fma_f32 v63, -v34, v255, v63
	ds_read_b128 v[234:237], v137 offset:41040
	s_waitcnt lgkmcnt(8)
	v_fma_f32 v62, -v35, v202, v62
	v_fma_f32 v63, -v32, v203, v63
	v_fma_f32 v62, -v33, v204, v62
	v_fma_f32 v63, -v30, v205, v63
	ds_read_b128 v[238:241], v137 offset:41056
	s_waitcnt lgkmcnt(8)
	v_fma_f32 v62, -v31, v206, v62
	v_fma_f32 v63, -v28, v207, v63
	v_fma_f32 v62, -v29, v208, v62
	v_fma_f32 v63, -v26, v209, v63
	ds_read_b128 v[248:251], v137 offset:41072
	s_waitcnt lgkmcnt(8)
	v_fma_f32 v62, -v27, v210, v62
	v_fma_f32 v63, -v24, v211, v63
	v_fma_f32 v22, -v25, v212, v62
	v_add_f32_e32 v22, v63, v22
	s_nop 0
	ds_read_b128 v[252:255], v137 offset:41088
	s_waitcnt lgkmcnt(8)
	v_fma_f32 v62, -v81, v214, v94
	v_fma_f32 v63, -v0, v215, 0
	v_fma_f32 v62, -v1, v216, v62
	v_fma_f32 v63, -v2, v217, v63
	ds_read_b128 v[202:205], v137 offset:41104
	s_waitcnt lgkmcnt(8)
	v_fma_f32 v62, -v3, v218, v62
	v_fma_f32 v63, -v4, v219, v63
	v_fma_f32 v62, -v5, v220, v62
	v_fma_f32 v63, -v7, v221, v63
	ds_read_b128 v[206:209], v137 offset:41120
	s_waitcnt lgkmcnt(8)
	v_fma_f32 v62, -v6, v222, v62
	v_fma_f32 v63, -v8, v223, v63
	v_fma_f32 v62, -v9, v224, v62
	v_fma_f32 v63, -v10, v225, v63
	ds_read_b128 v[210:213], v137 offset:41136
	s_waitcnt lgkmcnt(8)
	v_fma_f32 v62, -v11, v226, v62
	v_fma_f32 v63, -v60, v227, v63
	v_fma_f32 v62, -v61, v228, v62
	v_fma_f32 v63, -v58, v229, v63
	ds_read_b128 v[214:217], v137 offset:41152
	s_waitcnt lgkmcnt(8)
	v_fma_f32 v62, -v59, v230, v62
	v_fma_f32 v63, -v56, v231, v63
	v_fma_f32 v62, -v57, v232, v62
	v_fma_f32 v63, -v54, v233, v63
	ds_read_b128 v[218:221], v137 offset:41216
	s_waitcnt lgkmcnt(8)
	v_fma_f32 v62, -v55, v234, v62
	v_fma_f32 v63, -v52, v235, v63
	v_fma_f32 v62, -v53, v236, v62
	v_fma_f32 v63, -v50, v237, v63
	ds_read_b128 v[222:225], v137 offset:41232
	s_waitcnt lgkmcnt(8)
	v_fma_f32 v62, -v51, v238, v62
	v_fma_f32 v63, -v48, v239, v63
	v_fma_f32 v62, -v49, v240, v62
	v_fma_f32 v63, -v46, v241, v63
	ds_read_b128 v[226:229], v137 offset:41248
	s_waitcnt lgkmcnt(8)
	v_fma_f32 v62, -v47, v248, v62
	v_fma_f32 v63, -v44, v249, v63
	v_fma_f32 v62, -v45, v250, v62
	v_fma_f32 v63, -v42, v251, v63
	ds_read_b128 v[230:233], v137 offset:41264
	s_waitcnt lgkmcnt(8)
	v_fma_f32 v62, -v43, v252, v62
	v_fma_f32 v63, -v40, v253, v63
	v_fma_f32 v62, -v41, v254, v62
	v_fma_f32 v63, -v38, v255, v63
	ds_read_b128 v[234:237], v137 offset:41280
	s_waitcnt lgkmcnt(8)
	v_fma_f32 v62, -v39, v202, v62
	v_fma_f32 v63, -v36, v203, v63
	v_fma_f32 v62, -v37, v204, v62
	v_fma_f32 v63, -v34, v205, v63
	ds_read_b128 v[238:241], v137 offset:41296
	s_waitcnt lgkmcnt(8)
	v_fma_f32 v62, -v35, v206, v62
	v_fma_f32 v63, -v32, v207, v63
	v_fma_f32 v62, -v33, v208, v62
	v_fma_f32 v63, -v30, v209, v63
	ds_read_b128 v[248:251], v137 offset:41312
	s_waitcnt lgkmcnt(8)
	v_fma_f32 v62, -v31, v210, v62
	v_fma_f32 v63, -v28, v211, v63
	v_fma_f32 v62, -v29, v212, v62
	v_fma_f32 v63, -v26, v213, v63
	ds_read_b128 v[252:255], v137 offset:41328
	s_waitcnt lgkmcnt(8)
	v_fma_f32 v62, -v27, v214, v62
	v_fma_f32 v63, -v24, v215, v63
	v_fma_f32 v62, -v25, v216, v62
	v_fma_f32 v23, -v22, v217, v63
	v_add_f32_e32 v23, v62, v23
	s_nop 0
	ds_read_b128 v[202:205], v137 offset:41344
	s_waitcnt lgkmcnt(8)
	v_fma_f32 v62, -v81, v218, v92
	v_fma_f32 v63, -v0, v219, 0
	v_fma_f32 v62, -v1, v220, v62
	v_fma_f32 v63, -v2, v221, v63
	ds_read_b128 v[206:209], v137 offset:41360
	s_waitcnt lgkmcnt(8)
	v_fma_f32 v62, -v3, v222, v62
	v_fma_f32 v63, -v4, v223, v63
	v_fma_f32 v62, -v5, v224, v62
	v_fma_f32 v63, -v7, v225, v63
	ds_read_b128 v[210:213], v137 offset:41376
	s_waitcnt lgkmcnt(8)
	v_fma_f32 v62, -v6, v226, v62
	v_fma_f32 v63, -v8, v227, v63
	v_fma_f32 v62, -v9, v228, v62
	v_fma_f32 v63, -v10, v229, v63
	ds_read_b128 v[214:217], v137 offset:41392
	s_waitcnt lgkmcnt(8)
	v_fma_f32 v62, -v11, v230, v62
	v_fma_f32 v63, -v60, v231, v63
	v_fma_f32 v62, -v61, v232, v62
	v_fma_f32 v63, -v58, v233, v63
	ds_read_b128 v[218:221], v137 offset:41408
	s_waitcnt lgkmcnt(8)
	v_fma_f32 v62, -v59, v234, v62
	v_fma_f32 v63, -v56, v235, v63
	v_fma_f32 v62, -v57, v236, v62
	v_fma_f32 v63, -v54, v237, v63
	ds_read_b128 v[222:225], v137 offset:41424
	s_waitcnt lgkmcnt(8)
	v_fma_f32 v62, -v55, v238, v62
	v_fma_f32 v63, -v52, v239, v63
	v_fma_f32 v62, -v53, v240, v62
	v_fma_f32 v63, -v50, v241, v63
	ds_read_b128 v[226:229], v137 offset:41472
	s_waitcnt lgkmcnt(8)
	v_fma_f32 v62, -v51, v248, v62
	v_fma_f32 v63, -v48, v249, v63
	v_fma_f32 v62, -v49, v250, v62
	v_fma_f32 v63, -v46, v251, v63
	ds_read_b128 v[230:233], v137 offset:41488
	s_waitcnt lgkmcnt(8)
	v_fma_f32 v62, -v47, v252, v62
	v_fma_f32 v63, -v44, v253, v63
	v_fma_f32 v62, -v45, v254, v62
	v_fma_f32 v63, -v42, v255, v63
	ds_read_b128 v[234:237], v137 offset:41504
	s_waitcnt lgkmcnt(8)
	v_fma_f32 v62, -v43, v202, v62
	v_fma_f32 v63, -v40, v203, v63
	v_fma_f32 v62, -v41, v204, v62
	v_fma_f32 v63, -v38, v205, v63
	ds_read_b128 v[238:241], v137 offset:41520
	s_waitcnt lgkmcnt(8)
	v_fma_f32 v62, -v39, v206, v62
	v_fma_f32 v63, -v36, v207, v63
	v_fma_f32 v62, -v37, v208, v62
	v_fma_f32 v63, -v34, v209, v63
	ds_read_b128 v[248:251], v137 offset:41536
	s_waitcnt lgkmcnt(8)
	v_fma_f32 v62, -v35, v210, v62
	v_fma_f32 v63, -v32, v211, v63
	v_fma_f32 v62, -v33, v212, v62
	v_fma_f32 v63, -v30, v213, v63
	ds_read_b128 v[252:255], v137 offset:41552
	s_waitcnt lgkmcnt(8)
	v_fma_f32 v62, -v31, v214, v62
	v_fma_f32 v63, -v28, v215, v63
	v_fma_f32 v62, -v29, v216, v62
	v_fma_f32 v63, -v26, v217, v63
	ds_read_b128 v[202:205], v137 offset:41568
	s_waitcnt lgkmcnt(8)
	v_fma_f32 v62, -v27, v218, v62
	v_fma_f32 v63, -v24, v219, v63
	v_fma_f32 v62, -v25, v220, v62
	v_fma_f32 v63, -v22, v221, v63
	ds_read_b128 v[206:209], v137 offset:41584
	s_waitcnt lgkmcnt(8)
	v_fma_f32 v20, -v23, v222, v62
	v_add_f32_e32 v20, v63, v20
	s_nop 0
	ds_read_b128 v[210:213], v137 offset:41600
	s_waitcnt lgkmcnt(8)
	v_fma_f32 v62, -v81, v226, v90
	v_fma_f32 v63, -v0, v227, 0
	v_fma_f32 v62, -v1, v228, v62
	v_fma_f32 v63, -v2, v229, v63
	ds_read_b128 v[214:217], v137 offset:41616
	s_waitcnt lgkmcnt(8)
	v_fma_f32 v62, -v3, v230, v62
	v_fma_f32 v63, -v4, v231, v63
	v_fma_f32 v62, -v5, v232, v62
	v_fma_f32 v63, -v7, v233, v63
	ds_read_b128 v[218:221], v137 offset:41632
	s_waitcnt lgkmcnt(8)
	v_fma_f32 v62, -v6, v234, v62
	v_fma_f32 v63, -v8, v235, v63
	v_fma_f32 v62, -v9, v236, v62
	v_fma_f32 v63, -v10, v237, v63
	ds_read_b128 v[222:225], v137 offset:41648
	s_waitcnt lgkmcnt(8)
	v_fma_f32 v62, -v11, v238, v62
	v_fma_f32 v63, -v60, v239, v63
	v_fma_f32 v62, -v61, v240, v62
	v_fma_f32 v63, -v58, v241, v63
	ds_read_b128 v[226:229], v137 offset:41664
	s_waitcnt lgkmcnt(8)
	v_fma_f32 v62, -v59, v248, v62
	v_fma_f32 v63, -v56, v249, v63
	v_fma_f32 v62, -v57, v250, v62
	v_fma_f32 v63, -v54, v251, v63
	ds_read_b128 v[230:233], v137 offset:41680
	s_waitcnt lgkmcnt(8)
	v_fma_f32 v62, -v55, v252, v62
	v_fma_f32 v63, -v52, v253, v63
	v_fma_f32 v62, -v53, v254, v62
	v_fma_f32 v63, -v50, v255, v63
	ds_read_b128 v[234:237], v137 offset:41728
	s_waitcnt lgkmcnt(8)
	v_fma_f32 v62, -v51, v202, v62
	v_fma_f32 v63, -v48, v203, v63
	v_fma_f32 v62, -v49, v204, v62
	v_fma_f32 v63, -v46, v205, v63
	ds_read_b128 v[238:241], v137 offset:41744
	s_waitcnt lgkmcnt(8)
	v_fma_f32 v62, -v47, v206, v62
	v_fma_f32 v63, -v44, v207, v63
	v_fma_f32 v62, -v45, v208, v62
	v_fma_f32 v63, -v42, v209, v63
	ds_read_b128 v[248:251], v137 offset:41760
	s_waitcnt lgkmcnt(8)
	v_fma_f32 v62, -v43, v210, v62
	v_fma_f32 v63, -v40, v211, v63
	v_fma_f32 v62, -v41, v212, v62
	v_fma_f32 v63, -v38, v213, v63
	ds_read_b128 v[252:255], v137 offset:41776
	s_waitcnt lgkmcnt(8)
	v_fma_f32 v62, -v39, v214, v62
	v_fma_f32 v63, -v36, v215, v63
	v_fma_f32 v62, -v37, v216, v62
	v_fma_f32 v63, -v34, v217, v63
	ds_read_b128 v[202:205], v137 offset:41792
	s_waitcnt lgkmcnt(8)
	v_fma_f32 v62, -v35, v218, v62
	v_fma_f32 v63, -v32, v219, v63
	v_fma_f32 v62, -v33, v220, v62
	v_fma_f32 v63, -v30, v221, v63
	ds_read_b128 v[206:209], v137 offset:41808
	s_waitcnt lgkmcnt(8)
	v_fma_f32 v62, -v31, v222, v62
	v_fma_f32 v63, -v28, v223, v63
	v_fma_f32 v62, -v29, v224, v62
	v_fma_f32 v63, -v26, v225, v63
	ds_read_b128 v[210:213], v137 offset:41824
	s_waitcnt lgkmcnt(8)
	v_fma_f32 v62, -v27, v226, v62
	v_fma_f32 v63, -v24, v227, v63
	v_fma_f32 v62, -v25, v228, v62
	v_fma_f32 v63, -v22, v229, v63
	ds_read_b128 v[214:217], v137 offset:41840
	s_waitcnt lgkmcnt(8)
	v_fma_f32 v62, -v23, v230, v62
	v_fma_f32 v21, -v20, v231, v63
	v_add_f32_e32 v21, v62, v21
	s_nop 0
	ds_read_b128 v[218:221], v137 offset:41856
	s_waitcnt lgkmcnt(8)
	v_fma_f32 v62, -v81, v234, v91
	v_fma_f32 v63, -v0, v235, 0
	v_fma_f32 v62, -v1, v236, v62
	v_fma_f32 v63, -v2, v237, v63
	ds_read_b128 v[222:225], v137 offset:41872
	s_waitcnt lgkmcnt(8)
	v_fma_f32 v62, -v3, v238, v62
	v_fma_f32 v63, -v4, v239, v63
	v_fma_f32 v62, -v5, v240, v62
	v_fma_f32 v63, -v7, v241, v63
	ds_read_b128 v[226:229], v137 offset:41888
	s_waitcnt lgkmcnt(8)
	v_fma_f32 v62, -v6, v248, v62
	v_fma_f32 v63, -v8, v249, v63
	v_fma_f32 v62, -v9, v250, v62
	v_fma_f32 v63, -v10, v251, v63
	ds_read_b128 v[230:233], v137 offset:41904
	s_waitcnt lgkmcnt(8)
	v_fma_f32 v62, -v11, v252, v62
	v_fma_f32 v63, -v60, v253, v63
	v_fma_f32 v62, -v61, v254, v62
	v_fma_f32 v63, -v58, v255, v63
	ds_read_b128 v[234:237], v137 offset:41920
	s_waitcnt lgkmcnt(8)
	v_fma_f32 v62, -v59, v202, v62
	v_fma_f32 v63, -v56, v203, v63
	v_fma_f32 v62, -v57, v204, v62
	v_fma_f32 v63, -v54, v205, v63
	ds_read_b128 v[238:241], v137 offset:41936
	s_waitcnt lgkmcnt(8)
	v_fma_f32 v62, -v55, v206, v62
	v_fma_f32 v63, -v52, v207, v63
	v_fma_f32 v62, -v53, v208, v62
	v_fma_f32 v63, -v50, v209, v63
	ds_read_b128 v[248:251], v137 offset:41984
	s_waitcnt lgkmcnt(8)
	v_fma_f32 v62, -v51, v210, v62
	v_fma_f32 v63, -v48, v211, v63
	v_fma_f32 v62, -v49, v212, v62
	v_fma_f32 v63, -v46, v213, v63
	ds_read_b128 v[252:255], v137 offset:42000
	s_waitcnt lgkmcnt(8)
	v_fma_f32 v62, -v47, v214, v62
	v_fma_f32 v63, -v44, v215, v63
	v_fma_f32 v62, -v45, v216, v62
	v_fma_f32 v63, -v42, v217, v63
	ds_read_b128 v[202:205], v137 offset:42016
	s_waitcnt lgkmcnt(8)
	v_fma_f32 v62, -v43, v218, v62
	v_fma_f32 v63, -v40, v219, v63
	v_fma_f32 v62, -v41, v220, v62
	v_fma_f32 v63, -v38, v221, v63
	ds_read_b128 v[206:209], v137 offset:42032
	s_waitcnt lgkmcnt(8)
	v_fma_f32 v62, -v39, v222, v62
	v_fma_f32 v63, -v36, v223, v63
	v_fma_f32 v62, -v37, v224, v62
	v_fma_f32 v63, -v34, v225, v63
	ds_read_b128 v[210:213], v137 offset:42048
	s_waitcnt lgkmcnt(8)
	v_fma_f32 v62, -v35, v226, v62
	v_fma_f32 v63, -v32, v227, v63
	v_fma_f32 v62, -v33, v228, v62
	v_fma_f32 v63, -v30, v229, v63
	ds_read_b128 v[214:217], v137 offset:42064
	s_waitcnt lgkmcnt(8)
	v_fma_f32 v62, -v31, v230, v62
	v_fma_f32 v63, -v28, v231, v63
	v_fma_f32 v62, -v29, v232, v62
	v_fma_f32 v63, -v26, v233, v63
	ds_read_b128 v[218:221], v137 offset:42080
	s_waitcnt lgkmcnt(8)
	v_fma_f32 v62, -v27, v234, v62
	v_fma_f32 v63, -v24, v235, v63
	v_fma_f32 v62, -v25, v236, v62
	v_fma_f32 v63, -v22, v237, v63
	ds_read_b128 v[222:225], v137 offset:42096
	s_waitcnt lgkmcnt(8)
	v_fma_f32 v62, -v23, v238, v62
	v_fma_f32 v63, -v20, v239, v63
	v_fma_f32 v18, -v21, v240, v62
	v_add_f32_e32 v18, v63, v18
	s_nop 0
	ds_read_b128 v[226:229], v137 offset:42112
	s_waitcnt lgkmcnt(8)
	v_fma_f32 v62, -v81, v248, v89
	v_fma_f32 v63, -v0, v249, 0
	v_fma_f32 v62, -v1, v250, v62
	v_fma_f32 v63, -v2, v251, v63
	ds_read_b128 v[230:233], v137 offset:42128
	s_waitcnt lgkmcnt(8)
	v_fma_f32 v62, -v3, v252, v62
	v_fma_f32 v63, -v4, v253, v63
	v_fma_f32 v62, -v5, v254, v62
	v_fma_f32 v63, -v7, v255, v63
	ds_read_b128 v[234:237], v137 offset:42144
	s_waitcnt lgkmcnt(8)
	v_fma_f32 v62, -v6, v202, v62
	v_fma_f32 v63, -v8, v203, v63
	v_fma_f32 v62, -v9, v204, v62
	v_fma_f32 v63, -v10, v205, v63
	ds_read_b128 v[238:241], v137 offset:42160
	s_waitcnt lgkmcnt(8)
	v_fma_f32 v62, -v11, v206, v62
	v_fma_f32 v63, -v60, v207, v63
	v_fma_f32 v62, -v61, v208, v62
	v_fma_f32 v63, -v58, v209, v63
	ds_read_b128 v[248:251], v137 offset:42176
	s_waitcnt lgkmcnt(8)
	v_fma_f32 v62, -v59, v210, v62
	v_fma_f32 v63, -v56, v211, v63
	v_fma_f32 v62, -v57, v212, v62
	v_fma_f32 v63, -v54, v213, v63
	ds_read_b128 v[252:255], v137 offset:42192
	s_waitcnt lgkmcnt(8)
	v_fma_f32 v62, -v55, v214, v62
	v_fma_f32 v63, -v52, v215, v63
	v_fma_f32 v62, -v53, v216, v62
	v_fma_f32 v63, -v50, v217, v63
	ds_read_b128 v[202:205], v137 offset:42240
	s_waitcnt lgkmcnt(8)
	v_fma_f32 v62, -v51, v218, v62
	v_fma_f32 v63, -v48, v219, v63
	v_fma_f32 v62, -v49, v220, v62
	v_fma_f32 v63, -v46, v221, v63
	ds_read_b128 v[206:209], v137 offset:42256
	s_waitcnt lgkmcnt(8)
	v_fma_f32 v62, -v47, v222, v62
	v_fma_f32 v63, -v44, v223, v63
	v_fma_f32 v62, -v45, v224, v62
	v_fma_f32 v63, -v42, v225, v63
	ds_read_b128 v[210:213], v137 offset:42272
	s_waitcnt lgkmcnt(8)
	v_fma_f32 v62, -v43, v226, v62
	v_fma_f32 v63, -v40, v227, v63
	v_fma_f32 v62, -v41, v228, v62
	v_fma_f32 v63, -v38, v229, v63
	ds_read_b128 v[214:217], v137 offset:42288
	s_waitcnt lgkmcnt(8)
	v_fma_f32 v62, -v39, v230, v62
	v_fma_f32 v63, -v36, v231, v63
	v_fma_f32 v62, -v37, v232, v62
	v_fma_f32 v63, -v34, v233, v63
	ds_read_b128 v[218:221], v137 offset:42304
	s_waitcnt lgkmcnt(8)
	v_fma_f32 v62, -v35, v234, v62
	v_fma_f32 v63, -v32, v235, v63
	v_fma_f32 v62, -v33, v236, v62
	v_fma_f32 v63, -v30, v237, v63
	ds_read_b128 v[222:225], v137 offset:42320
	s_waitcnt lgkmcnt(8)
	v_fma_f32 v62, -v31, v238, v62
	v_fma_f32 v63, -v28, v239, v63
	v_fma_f32 v62, -v29, v240, v62
	v_fma_f32 v63, -v26, v241, v63
	ds_read_b128 v[226:229], v137 offset:42336
	s_waitcnt lgkmcnt(8)
	v_fma_f32 v62, -v27, v248, v62
	v_fma_f32 v63, -v24, v249, v63
	v_fma_f32 v62, -v25, v250, v62
	v_fma_f32 v63, -v22, v251, v63
	ds_read_b128 v[230:233], v137 offset:42352
	s_waitcnt lgkmcnt(8)
	v_fma_f32 v62, -v23, v252, v62
	v_fma_f32 v63, -v20, v253, v63
	v_fma_f32 v62, -v21, v254, v62
	v_fma_f32 v19, -v18, v255, v63
	v_add_f32_e32 v19, v62, v19
	s_nop 0
	ds_read_b128 v[234:237], v137 offset:42368
	s_waitcnt lgkmcnt(8)
	v_fma_f32 v62, -v81, v202, v88
	v_fma_f32 v63, -v0, v203, 0
	v_fma_f32 v62, -v1, v204, v62
	v_fma_f32 v63, -v2, v205, v63
	ds_read_b128 v[238:241], v137 offset:42384
	s_waitcnt lgkmcnt(8)
	v_fma_f32 v62, -v3, v206, v62
	v_fma_f32 v63, -v4, v207, v63
	v_fma_f32 v62, -v5, v208, v62
	v_fma_f32 v63, -v7, v209, v63
	ds_read_b128 v[248:251], v137 offset:42400
	s_waitcnt lgkmcnt(8)
	v_fma_f32 v62, -v6, v210, v62
	v_fma_f32 v63, -v8, v211, v63
	v_fma_f32 v62, -v9, v212, v62
	v_fma_f32 v63, -v10, v213, v63
	ds_read_b128 v[252:255], v137 offset:42416
	s_waitcnt lgkmcnt(8)
	v_fma_f32 v62, -v11, v214, v62
	v_fma_f32 v63, -v60, v215, v63
	v_fma_f32 v62, -v61, v216, v62
	v_fma_f32 v63, -v58, v217, v63
	ds_read_b128 v[202:205], v137 offset:42432
	s_waitcnt lgkmcnt(8)
	v_fma_f32 v62, -v59, v218, v62
	v_fma_f32 v63, -v56, v219, v63
	v_fma_f32 v62, -v57, v220, v62
	v_fma_f32 v63, -v54, v221, v63
	ds_read_b128 v[206:209], v137 offset:42448
	s_waitcnt lgkmcnt(8)
	v_fma_f32 v62, -v55, v222, v62
	v_fma_f32 v63, -v52, v223, v63
	v_fma_f32 v62, -v53, v224, v62
	v_fma_f32 v63, -v50, v225, v63
	ds_read_b128 v[210:213], v137 offset:42464
	s_waitcnt lgkmcnt(8)
	v_fma_f32 v62, -v51, v226, v62
	v_fma_f32 v63, -v48, v227, v63
	v_fma_f32 v62, -v49, v228, v62
	v_fma_f32 v63, -v46, v229, v63
	ds_read_b128 v[214:217], v137 offset:42496
	s_waitcnt lgkmcnt(8)
	v_fma_f32 v62, -v47, v230, v62
	v_fma_f32 v63, -v44, v231, v63
	v_fma_f32 v62, -v45, v232, v62
	v_fma_f32 v63, -v42, v233, v63
	ds_read_b128 v[218:221], v137 offset:42512
	s_waitcnt lgkmcnt(8)
	v_fma_f32 v62, -v43, v234, v62
	v_fma_f32 v63, -v40, v235, v63
	v_fma_f32 v62, -v41, v236, v62
	v_fma_f32 v63, -v38, v237, v63
	ds_read_b128 v[222:225], v137 offset:42528
	s_waitcnt lgkmcnt(8)
	v_fma_f32 v62, -v39, v238, v62
	v_fma_f32 v63, -v36, v239, v63
	v_fma_f32 v62, -v37, v240, v62
	v_fma_f32 v63, -v34, v241, v63
	ds_read_b128 v[226:229], v137 offset:42544
	s_waitcnt lgkmcnt(8)
	v_fma_f32 v62, -v35, v248, v62
	v_fma_f32 v63, -v32, v249, v63
	v_fma_f32 v62, -v33, v250, v62
	v_fma_f32 v63, -v30, v251, v63
	ds_read_b128 v[230:233], v137 offset:42560
	s_waitcnt lgkmcnt(8)
	v_fma_f32 v62, -v31, v252, v62
	v_fma_f32 v63, -v28, v253, v63
	v_fma_f32 v62, -v29, v254, v62
	v_fma_f32 v63, -v26, v255, v63
	ds_read_b128 v[234:237], v137 offset:42576
	s_waitcnt lgkmcnt(8)
	v_fma_f32 v62, -v27, v202, v62
	v_fma_f32 v63, -v24, v203, v63
	v_fma_f32 v62, -v25, v204, v62
	v_fma_f32 v63, -v22, v205, v63
	ds_read_b128 v[238:241], v137 offset:42592
	s_waitcnt lgkmcnt(8)
	v_fma_f32 v62, -v23, v206, v62
	v_fma_f32 v63, -v20, v207, v63
	v_fma_f32 v62, -v21, v208, v62
	v_fma_f32 v63, -v18, v209, v63
	ds_read_b128 v[248:251], v137 offset:42608
	s_waitcnt lgkmcnt(8)
	v_fma_f32 v16, -v19, v210, v62
	v_add_f32_e32 v16, v63, v16
	s_nop 0
	ds_read_b128 v[252:255], v137 offset:42624
	s_waitcnt lgkmcnt(8)
	v_fma_f32 v62, -v81, v214, v87
	v_fma_f32 v63, -v0, v215, 0
	v_fma_f32 v62, -v1, v216, v62
	v_fma_f32 v63, -v2, v217, v63
	ds_read_b128 v[202:205], v137 offset:42640
	s_waitcnt lgkmcnt(8)
	v_fma_f32 v62, -v3, v218, v62
	v_fma_f32 v63, -v4, v219, v63
	v_fma_f32 v62, -v5, v220, v62
	v_fma_f32 v63, -v7, v221, v63
	ds_read_b128 v[206:209], v137 offset:42656
	s_waitcnt lgkmcnt(8)
	v_fma_f32 v62, -v6, v222, v62
	v_fma_f32 v63, -v8, v223, v63
	v_fma_f32 v62, -v9, v224, v62
	v_fma_f32 v63, -v10, v225, v63
	ds_read_b128 v[210:213], v137 offset:42672
	s_waitcnt lgkmcnt(8)
	v_fma_f32 v62, -v11, v226, v62
	v_fma_f32 v63, -v60, v227, v63
	v_fma_f32 v62, -v61, v228, v62
	v_fma_f32 v63, -v58, v229, v63
	ds_read_b128 v[214:217], v137 offset:42688
	s_waitcnt lgkmcnt(8)
	v_fma_f32 v62, -v59, v230, v62
	v_fma_f32 v63, -v56, v231, v63
	v_fma_f32 v62, -v57, v232, v62
	v_fma_f32 v63, -v54, v233, v63
	ds_read_b128 v[218:221], v137 offset:42704
	s_waitcnt lgkmcnt(8)
	v_fma_f32 v62, -v55, v234, v62
	v_fma_f32 v63, -v52, v235, v63
	v_fma_f32 v62, -v53, v236, v62
	v_fma_f32 v63, -v50, v237, v63
	ds_read_b128 v[222:225], v137 offset:42720
	s_waitcnt lgkmcnt(8)
	v_fma_f32 v62, -v51, v238, v62
	v_fma_f32 v63, -v48, v239, v63
	v_fma_f32 v62, -v49, v240, v62
	v_fma_f32 v63, -v46, v241, v63
	ds_read_b128 v[226:229], v137 offset:42752
	s_waitcnt lgkmcnt(8)
	v_fma_f32 v62, -v47, v248, v62
	v_fma_f32 v63, -v44, v249, v63
	v_fma_f32 v62, -v45, v250, v62
	v_fma_f32 v63, -v42, v251, v63
	ds_read_b128 v[230:233], v137 offset:42768
	s_waitcnt lgkmcnt(8)
	v_fma_f32 v62, -v43, v252, v62
	v_fma_f32 v63, -v40, v253, v63
	v_fma_f32 v62, -v41, v254, v62
	v_fma_f32 v63, -v38, v255, v63
	ds_read_b128 v[234:237], v137 offset:42784
	s_waitcnt lgkmcnt(8)
	v_fma_f32 v62, -v39, v202, v62
	v_fma_f32 v63, -v36, v203, v63
	v_fma_f32 v62, -v37, v204, v62
	v_fma_f32 v63, -v34, v205, v63
	ds_read_b128 v[238:241], v137 offset:42800
	s_waitcnt lgkmcnt(8)
	v_fma_f32 v62, -v35, v206, v62
	v_fma_f32 v63, -v32, v207, v63
	v_fma_f32 v62, -v33, v208, v62
	v_fma_f32 v63, -v30, v209, v63
	ds_read_b128 v[248:251], v137 offset:42816
	s_waitcnt lgkmcnt(8)
	v_fma_f32 v62, -v31, v210, v62
	v_fma_f32 v63, -v28, v211, v63
	v_fma_f32 v62, -v29, v212, v62
	v_fma_f32 v63, -v26, v213, v63
	ds_read_b128 v[252:255], v137 offset:42832
	s_waitcnt lgkmcnt(8)
	v_fma_f32 v62, -v27, v214, v62
	v_fma_f32 v63, -v24, v215, v63
	v_fma_f32 v62, -v25, v216, v62
	v_fma_f32 v63, -v22, v217, v63
	ds_read_b128 v[202:205], v137 offset:42848
	s_waitcnt lgkmcnt(8)
	v_fma_f32 v62, -v23, v218, v62
	v_fma_f32 v63, -v20, v219, v63
	v_fma_f32 v62, -v21, v220, v62
	v_fma_f32 v63, -v18, v221, v63
	ds_read_b128 v[206:209], v137 offset:42864
	s_waitcnt lgkmcnt(8)
	v_fma_f32 v62, -v19, v222, v62
	v_fma_f32 v17, -v16, v223, v63
	v_add_f32_e32 v17, v62, v17
	s_nop 0
	ds_read_b128 v[210:213], v137 offset:42880
	s_waitcnt lgkmcnt(8)
	v_fma_f32 v62, -v81, v226, v86
	v_fma_f32 v63, -v0, v227, 0
	v_fma_f32 v62, -v1, v228, v62
	v_fma_f32 v63, -v2, v229, v63
	ds_read_b128 v[214:217], v137 offset:42896
	s_waitcnt lgkmcnt(8)
	v_fma_f32 v62, -v3, v230, v62
	v_fma_f32 v63, -v4, v231, v63
	v_fma_f32 v62, -v5, v232, v62
	v_fma_f32 v63, -v7, v233, v63
	ds_read_b128 v[218:221], v137 offset:42912
	s_waitcnt lgkmcnt(8)
	v_fma_f32 v62, -v6, v234, v62
	v_fma_f32 v63, -v8, v235, v63
	v_fma_f32 v62, -v9, v236, v62
	v_fma_f32 v63, -v10, v237, v63
	ds_read_b128 v[222:225], v137 offset:42928
	s_waitcnt lgkmcnt(8)
	v_fma_f32 v62, -v11, v238, v62
	v_fma_f32 v63, -v60, v239, v63
	v_fma_f32 v62, -v61, v240, v62
	v_fma_f32 v63, -v58, v241, v63
	ds_read_b128 v[226:229], v137 offset:42944
	s_waitcnt lgkmcnt(8)
	v_fma_f32 v62, -v59, v248, v62
	v_fma_f32 v63, -v56, v249, v63
	v_fma_f32 v62, -v57, v250, v62
	v_fma_f32 v63, -v54, v251, v63
	ds_read_b128 v[230:233], v137 offset:42960
	s_waitcnt lgkmcnt(8)
	v_fma_f32 v62, -v55, v252, v62
	v_fma_f32 v63, -v52, v253, v63
	v_fma_f32 v62, -v53, v254, v62
	v_fma_f32 v63, -v50, v255, v63
	ds_read_b128 v[234:237], v137 offset:42976
	s_waitcnt lgkmcnt(8)
	v_fma_f32 v62, -v51, v202, v62
	v_fma_f32 v63, -v48, v203, v63
	v_fma_f32 v62, -v49, v204, v62
	v_fma_f32 v63, -v46, v205, v63
	ds_read_b128 v[238:241], v137 offset:43008
	s_waitcnt lgkmcnt(8)
	v_fma_f32 v62, -v47, v206, v62
	v_fma_f32 v63, -v44, v207, v63
	v_fma_f32 v62, -v45, v208, v62
	v_fma_f32 v63, -v42, v209, v63
	ds_read_b128 v[248:251], v137 offset:43024
	s_waitcnt lgkmcnt(8)
	v_fma_f32 v62, -v43, v210, v62
	v_fma_f32 v63, -v40, v211, v63
	v_fma_f32 v62, -v41, v212, v62
	v_fma_f32 v63, -v38, v213, v63
	ds_read_b128 v[252:255], v137 offset:43040
	s_waitcnt lgkmcnt(8)
	v_fma_f32 v62, -v39, v214, v62
	v_fma_f32 v63, -v36, v215, v63
	v_fma_f32 v62, -v37, v216, v62
	v_fma_f32 v63, -v34, v217, v63
	ds_read_b128 v[202:205], v137 offset:43056
	s_waitcnt lgkmcnt(8)
	v_fma_f32 v62, -v35, v218, v62
	v_fma_f32 v63, -v32, v219, v63
	v_fma_f32 v62, -v33, v220, v62
	v_fma_f32 v63, -v30, v221, v63
	ds_read_b128 v[206:209], v137 offset:43072
	s_waitcnt lgkmcnt(8)
	v_fma_f32 v62, -v31, v222, v62
	v_fma_f32 v63, -v28, v223, v63
	v_fma_f32 v62, -v29, v224, v62
	v_fma_f32 v63, -v26, v225, v63
	ds_read_b128 v[210:213], v137 offset:43088
	s_waitcnt lgkmcnt(8)
	v_fma_f32 v62, -v27, v226, v62
	v_fma_f32 v63, -v24, v227, v63
	v_fma_f32 v62, -v25, v228, v62
	v_fma_f32 v63, -v22, v229, v63
	ds_read_b128 v[214:217], v137 offset:43104
	s_waitcnt lgkmcnt(8)
	v_fma_f32 v62, -v23, v230, v62
	v_fma_f32 v63, -v20, v231, v63
	v_fma_f32 v62, -v21, v232, v62
	v_fma_f32 v63, -v18, v233, v63
	ds_read_b128 v[218:221], v137 offset:43120
	s_waitcnt lgkmcnt(8)
	v_fma_f32 v62, -v19, v234, v62
	v_fma_f32 v63, -v16, v235, v63
	v_fma_f32 v14, -v17, v236, v62
	v_add_f32_e32 v14, v63, v14
	s_nop 0
	ds_read_b128 v[222:225], v137 offset:43136
	s_waitcnt lgkmcnt(8)
	v_fma_f32 v62, -v81, v238, v85
	v_fma_f32 v63, -v0, v239, 0
	v_fma_f32 v62, -v1, v240, v62
	v_fma_f32 v63, -v2, v241, v63
	ds_read_b128 v[226:229], v137 offset:43152
	s_waitcnt lgkmcnt(8)
	v_fma_f32 v62, -v3, v248, v62
	v_fma_f32 v63, -v4, v249, v63
	v_fma_f32 v62, -v5, v250, v62
	v_fma_f32 v63, -v7, v251, v63
	ds_read_b128 v[230:233], v137 offset:43168
	s_waitcnt lgkmcnt(8)
	v_fma_f32 v62, -v6, v252, v62
	v_fma_f32 v63, -v8, v253, v63
	v_fma_f32 v62, -v9, v254, v62
	v_fma_f32 v63, -v10, v255, v63
	ds_read_b128 v[234:237], v137 offset:43184
	s_waitcnt lgkmcnt(8)
	v_fma_f32 v62, -v11, v202, v62
	v_fma_f32 v63, -v60, v203, v63
	v_fma_f32 v62, -v61, v204, v62
	v_fma_f32 v63, -v58, v205, v63
	ds_read_b128 v[238:241], v137 offset:43200
	s_waitcnt lgkmcnt(8)
	v_fma_f32 v62, -v59, v206, v62
	v_fma_f32 v63, -v56, v207, v63
	v_fma_f32 v62, -v57, v208, v62
	v_fma_f32 v63, -v54, v209, v63
	ds_read_b128 v[248:251], v137 offset:43216
	s_waitcnt lgkmcnt(8)
	v_fma_f32 v62, -v55, v210, v62
	v_fma_f32 v63, -v52, v211, v63
	v_fma_f32 v62, -v53, v212, v62
	v_fma_f32 v63, -v50, v213, v63
	ds_read_b128 v[252:255], v137 offset:43232
	s_waitcnt lgkmcnt(8)
	v_fma_f32 v62, -v51, v214, v62
	v_fma_f32 v63, -v48, v215, v63
	v_fma_f32 v62, -v49, v216, v62
	v_fma_f32 v63, -v46, v217, v63
	ds_read_b128 v[202:205], v137 offset:43264
	s_waitcnt lgkmcnt(8)
	v_fma_f32 v62, -v47, v218, v62
	v_fma_f32 v63, -v44, v219, v63
	v_fma_f32 v62, -v45, v220, v62
	v_fma_f32 v63, -v42, v221, v63
	ds_read_b128 v[206:209], v137 offset:43280
	s_waitcnt lgkmcnt(8)
	v_fma_f32 v62, -v43, v222, v62
	v_fma_f32 v63, -v40, v223, v63
	v_fma_f32 v62, -v41, v224, v62
	v_fma_f32 v63, -v38, v225, v63
	ds_read_b128 v[210:213], v137 offset:43296
	s_waitcnt lgkmcnt(8)
	v_fma_f32 v62, -v39, v226, v62
	v_fma_f32 v63, -v36, v227, v63
	v_fma_f32 v62, -v37, v228, v62
	v_fma_f32 v63, -v34, v229, v63
	ds_read_b128 v[214:217], v137 offset:43312
	s_waitcnt lgkmcnt(8)
	v_fma_f32 v62, -v35, v230, v62
	v_fma_f32 v63, -v32, v231, v63
	v_fma_f32 v62, -v33, v232, v62
	v_fma_f32 v63, -v30, v233, v63
	ds_read_b128 v[218:221], v137 offset:43328
	s_waitcnt lgkmcnt(8)
	v_fma_f32 v62, -v31, v234, v62
	v_fma_f32 v63, -v28, v235, v63
	v_fma_f32 v62, -v29, v236, v62
	v_fma_f32 v63, -v26, v237, v63
	ds_read_b128 v[222:225], v137 offset:43344
	s_waitcnt lgkmcnt(8)
	v_fma_f32 v62, -v27, v238, v62
	v_fma_f32 v63, -v24, v239, v63
	v_fma_f32 v62, -v25, v240, v62
	v_fma_f32 v63, -v22, v241, v63
	ds_read_b128 v[226:229], v137 offset:43360
	s_waitcnt lgkmcnt(8)
	v_fma_f32 v62, -v23, v248, v62
	v_fma_f32 v63, -v20, v249, v63
	v_fma_f32 v62, -v21, v250, v62
	v_fma_f32 v63, -v18, v251, v63
	ds_read_b128 v[230:233], v137 offset:43376
	s_waitcnt lgkmcnt(8)
	v_fma_f32 v62, -v19, v252, v62
	v_fma_f32 v63, -v16, v253, v63
	v_fma_f32 v62, -v17, v254, v62
	v_fma_f32 v15, -v14, v255, v63
	v_add_f32_e32 v15, v62, v15
	s_nop 0
	ds_read_b128 v[234:237], v137 offset:43392
	s_waitcnt lgkmcnt(8)
	v_fma_f32 v62, -v81, v202, v84
	v_fma_f32 v63, -v0, v203, 0
	v_fma_f32 v62, -v1, v204, v62
	v_fma_f32 v63, -v2, v205, v63
	ds_read_b128 v[238:241], v137 offset:43408
	s_waitcnt lgkmcnt(8)
	v_fma_f32 v62, -v3, v206, v62
	v_fma_f32 v63, -v4, v207, v63
	v_fma_f32 v62, -v5, v208, v62
	v_fma_f32 v63, -v7, v209, v63
	ds_read_b128 v[248:251], v137 offset:43424
	s_waitcnt lgkmcnt(8)
	v_fma_f32 v62, -v6, v210, v62
	v_fma_f32 v63, -v8, v211, v63
	v_fma_f32 v62, -v9, v212, v62
	v_fma_f32 v63, -v10, v213, v63
	ds_read_b128 v[252:255], v137 offset:43440
	s_waitcnt lgkmcnt(8)
	v_fma_f32 v62, -v11, v214, v62
	v_fma_f32 v63, -v60, v215, v63
	v_fma_f32 v62, -v61, v216, v62
	v_fma_f32 v63, -v58, v217, v63
	ds_read_b128 v[202:205], v137 offset:43456
	s_waitcnt lgkmcnt(8)
	v_fma_f32 v62, -v59, v218, v62
	v_fma_f32 v63, -v56, v219, v63
	v_fma_f32 v62, -v57, v220, v62
	v_fma_f32 v63, -v54, v221, v63
	ds_read_b128 v[206:209], v137 offset:43472
	s_waitcnt lgkmcnt(8)
	v_fma_f32 v62, -v55, v222, v62
	v_fma_f32 v63, -v52, v223, v63
	v_fma_f32 v62, -v53, v224, v62
	v_fma_f32 v63, -v50, v225, v63
	ds_read_b128 v[210:213], v137 offset:43488
	s_waitcnt lgkmcnt(8)
	v_fma_f32 v62, -v51, v226, v62
	v_fma_f32 v63, -v48, v227, v63
	v_fma_f32 v62, -v49, v228, v62
	v_fma_f32 v63, -v46, v229, v63
	ds_read_b128 v[214:217], v137 offset:43504
	s_waitcnt lgkmcnt(8)
	v_fma_f32 v62, -v47, v230, v62
	v_fma_f32 v63, -v44, v231, v63
	v_fma_f32 v62, -v45, v232, v62
	v_fma_f32 v63, -v42, v233, v63
	ds_read_b128 v[218:221], v137 offset:43520
	s_waitcnt lgkmcnt(8)
	v_fma_f32 v62, -v43, v234, v62
	v_fma_f32 v63, -v40, v235, v63
	v_fma_f32 v62, -v41, v236, v62
	v_fma_f32 v63, -v38, v237, v63
	ds_read_b128 v[222:225], v137 offset:43536
	s_waitcnt lgkmcnt(8)
	v_fma_f32 v62, -v39, v238, v62
	v_fma_f32 v63, -v36, v239, v63
	v_fma_f32 v62, -v37, v240, v62
	v_fma_f32 v63, -v34, v241, v63
	ds_read_b128 v[226:229], v137 offset:43552
	s_waitcnt lgkmcnt(8)
	v_fma_f32 v62, -v35, v248, v62
	v_fma_f32 v63, -v32, v249, v63
	v_fma_f32 v62, -v33, v250, v62
	v_fma_f32 v63, -v30, v251, v63
	ds_read_b128 v[230:233], v137 offset:43568
	s_waitcnt lgkmcnt(8)
	v_fma_f32 v62, -v31, v252, v62
	v_fma_f32 v63, -v28, v253, v63
	v_fma_f32 v62, -v29, v254, v62
	v_fma_f32 v63, -v26, v255, v63
	ds_read_b128 v[234:237], v137 offset:43584
	s_waitcnt lgkmcnt(8)
	v_fma_f32 v62, -v27, v202, v62
	v_fma_f32 v63, -v24, v203, v63
	v_fma_f32 v62, -v25, v204, v62
	v_fma_f32 v63, -v22, v205, v63
	ds_read_b128 v[238:241], v137 offset:43600
	s_waitcnt lgkmcnt(8)
	v_fma_f32 v62, -v23, v206, v62
	v_fma_f32 v63, -v20, v207, v63
	v_fma_f32 v62, -v21, v208, v62
	v_fma_f32 v63, -v18, v209, v63
	ds_read_b128 v[248:251], v137 offset:43616
	s_waitcnt lgkmcnt(8)
	v_fma_f32 v62, -v19, v210, v62
	v_fma_f32 v63, -v16, v211, v63
	v_fma_f32 v62, -v17, v212, v62
	v_fma_f32 v63, -v14, v213, v63
	ds_read_b128 v[252:255], v137 offset:43632
	s_waitcnt lgkmcnt(8)
	v_fma_f32 v12, -v15, v214, v62
	v_add_f32_e32 v12, v63, v12
	s_nop 0
	ds_read_b128 v[202:205], v137 offset:43648
	s_waitcnt lgkmcnt(8)
	v_fma_f32 v62, -v81, v218, v83
	v_fma_f32 v63, -v0, v219, 0
	v_fma_f32 v62, -v1, v220, v62
	v_fma_f32 v63, -v2, v221, v63
	ds_read_b128 v[206:209], v137 offset:43664
	s_waitcnt lgkmcnt(8)
	v_fma_f32 v62, -v3, v222, v62
	v_fma_f32 v63, -v4, v223, v63
	v_fma_f32 v62, -v5, v224, v62
	v_fma_f32 v63, -v7, v225, v63
	ds_read_b128 v[210:213], v137 offset:43680
	s_waitcnt lgkmcnt(8)
	v_fma_f32 v62, -v6, v226, v62
	v_fma_f32 v63, -v8, v227, v63
	v_fma_f32 v62, -v9, v228, v62
	v_fma_f32 v63, -v10, v229, v63
	ds_read_b128 v[214:217], v137 offset:43696
	s_waitcnt lgkmcnt(8)
	v_fma_f32 v62, -v11, v230, v62
	v_fma_f32 v63, -v60, v231, v63
	v_fma_f32 v62, -v61, v232, v62
	v_fma_f32 v63, -v58, v233, v63
	ds_read_b128 v[218:221], v137 offset:43712
	s_waitcnt lgkmcnt(8)
	v_fma_f32 v62, -v59, v234, v62
	v_fma_f32 v63, -v56, v235, v63
	v_fma_f32 v62, -v57, v236, v62
	v_fma_f32 v63, -v54, v237, v63
	ds_read_b128 v[222:225], v137 offset:43728
	s_waitcnt lgkmcnt(8)
	v_fma_f32 v62, -v55, v238, v62
	v_fma_f32 v63, -v52, v239, v63
	v_fma_f32 v62, -v53, v240, v62
	v_fma_f32 v63, -v50, v241, v63
	ds_read_b128 v[226:229], v137 offset:43744
	s_waitcnt lgkmcnt(8)
	v_fma_f32 v62, -v51, v248, v62
	v_fma_f32 v63, -v48, v249, v63
	v_fma_f32 v62, -v49, v250, v62
	v_fma_f32 v63, -v46, v251, v63
	ds_read_b128 v[230:233], v137 offset:43760
	s_waitcnt lgkmcnt(8)
	v_fma_f32 v62, -v47, v252, v62
	v_fma_f32 v63, -v44, v253, v63
	v_fma_f32 v62, -v45, v254, v62
	v_fma_f32 v63, -v42, v255, v63
	ds_read_b128 v[234:237], v137 offset:43776
	s_waitcnt lgkmcnt(8)
	v_fma_f32 v62, -v43, v202, v62
	v_fma_f32 v63, -v40, v203, v63
	v_fma_f32 v62, -v41, v204, v62
	v_fma_f32 v63, -v38, v205, v63
	ds_read_b128 v[238:241], v137 offset:43792
	s_waitcnt lgkmcnt(8)
	v_fma_f32 v62, -v39, v206, v62
	v_fma_f32 v63, -v36, v207, v63
	v_fma_f32 v62, -v37, v208, v62
	v_fma_f32 v63, -v34, v209, v63
	ds_read_b128 v[248:251], v137 offset:43808
	s_waitcnt lgkmcnt(8)
	v_fma_f32 v62, -v35, v210, v62
	v_fma_f32 v63, -v32, v211, v63
	v_fma_f32 v62, -v33, v212, v62
	v_fma_f32 v63, -v30, v213, v63
	ds_read_b128 v[252:255], v137 offset:43824
	s_waitcnt lgkmcnt(8)
	v_fma_f32 v62, -v31, v214, v62
	v_fma_f32 v63, -v28, v215, v63
	v_fma_f32 v62, -v29, v216, v62
	v_fma_f32 v63, -v26, v217, v63
	ds_read_b128 v[202:205], v137 offset:43840
	s_waitcnt lgkmcnt(8)
	v_fma_f32 v62, -v27, v218, v62
	v_fma_f32 v63, -v24, v219, v63
	v_fma_f32 v62, -v25, v220, v62
	v_fma_f32 v63, -v22, v221, v63
	ds_read_b128 v[206:209], v137 offset:43856
	s_waitcnt lgkmcnt(8)
	v_fma_f32 v62, -v23, v222, v62
	v_fma_f32 v63, -v20, v223, v63
	v_fma_f32 v62, -v21, v224, v62
	v_fma_f32 v63, -v18, v225, v63
	ds_read_b128 v[210:213], v137 offset:43872
	s_waitcnt lgkmcnt(8)
	v_fma_f32 v62, -v19, v226, v62
	v_fma_f32 v63, -v16, v227, v63
	v_fma_f32 v62, -v17, v228, v62
	v_fma_f32 v63, -v14, v229, v63
	ds_read_b128 v[214:217], v137 offset:43888
	s_waitcnt lgkmcnt(8)
	v_fma_f32 v62, -v15, v230, v62
	v_fma_f32 v13, -v12, v231, v63
	v_add_f32_e32 v13, v62, v13
	s_nop 0
	ds_read_b128 v[218:221], v137 offset:43904
	s_waitcnt lgkmcnt(8)
	v_fma_f32 v62, -v81, v234, v82
	v_fma_f32 v63, -v0, v235, 0
	v_fma_f32 v62, -v1, v236, v62
	v_fma_f32 v63, -v2, v237, v63
	ds_read_b128 v[222:225], v137 offset:43920
	s_waitcnt lgkmcnt(8)
	v_fma_f32 v62, -v3, v238, v62
	v_fma_f32 v63, -v4, v239, v63
	v_fma_f32 v62, -v5, v240, v62
	v_fma_f32 v63, -v7, v241, v63
	ds_read_b128 v[226:229], v137 offset:43936
	s_waitcnt lgkmcnt(8)
	v_fma_f32 v62, -v6, v248, v62
	v_fma_f32 v63, -v8, v249, v63
	v_fma_f32 v62, -v9, v250, v62
	v_fma_f32 v63, -v10, v251, v63
	ds_read_b128 v[230:233], v137 offset:43952
	s_waitcnt lgkmcnt(8)
	v_fma_f32 v62, -v11, v252, v62
	v_fma_f32 v63, -v60, v253, v63
	v_fma_f32 v62, -v61, v254, v62
	v_fma_f32 v63, -v58, v255, v63
	ds_read_b128 v[234:237], v137 offset:43968
	s_waitcnt lgkmcnt(8)
	v_fma_f32 v62, -v59, v202, v62
	v_fma_f32 v63, -v56, v203, v63
	v_fma_f32 v62, -v57, v204, v62
	v_fma_f32 v63, -v54, v205, v63
	ds_read_b128 v[238:241], v137 offset:43984
	s_waitcnt lgkmcnt(8)
	v_fma_f32 v62, -v55, v206, v62
	v_fma_f32 v63, -v52, v207, v63
	v_fma_f32 v62, -v53, v208, v62
	v_fma_f32 v63, -v50, v209, v63
	ds_read_b128 v[248:251], v137 offset:44000
	s_waitcnt lgkmcnt(8)
	v_fma_f32 v62, -v51, v210, v62
	v_fma_f32 v63, -v48, v211, v63
	v_fma_f32 v62, -v49, v212, v62
	v_fma_f32 v63, -v46, v213, v63
	ds_read_b128 v[252:255], v137 offset:44016
	s_waitcnt lgkmcnt(8)
	v_fma_f32 v62, -v47, v214, v62
	v_fma_f32 v63, -v44, v215, v63
	v_fma_f32 v62, -v45, v216, v62
	v_fma_f32 v63, -v42, v217, v63
	s_waitcnt lgkmcnt(7)
	v_fma_f32 v62, -v43, v218, v62
	v_fma_f32 v63, -v40, v219, v63
	v_fma_f32 v62, -v41, v220, v62
	v_fma_f32 v63, -v38, v221, v63
	s_waitcnt lgkmcnt(6)
	v_fma_f32 v62, -v39, v222, v62
	v_fma_f32 v63, -v36, v223, v63
	v_fma_f32 v62, -v37, v224, v62
	v_fma_f32 v63, -v34, v225, v63
	s_waitcnt lgkmcnt(5)
	v_fma_f32 v62, -v35, v226, v62
	v_fma_f32 v63, -v32, v227, v63
	v_fma_f32 v62, -v33, v228, v62
	v_fma_f32 v63, -v30, v229, v63
	s_waitcnt lgkmcnt(4)
	v_fma_f32 v62, -v31, v230, v62
	v_fma_f32 v63, -v28, v231, v63
	v_fma_f32 v62, -v29, v232, v62
	v_fma_f32 v63, -v26, v233, v63
	s_waitcnt lgkmcnt(3)
	v_fma_f32 v62, -v27, v234, v62
	v_fma_f32 v63, -v24, v235, v63
	v_fma_f32 v62, -v25, v236, v62
	v_fma_f32 v63, -v22, v237, v63
	s_waitcnt lgkmcnt(2)
	v_fma_f32 v62, -v23, v238, v62
	v_fma_f32 v63, -v20, v239, v63
	v_fma_f32 v62, -v21, v240, v62
	v_fma_f32 v63, -v18, v241, v63
	s_waitcnt lgkmcnt(1)
	v_fma_f32 v62, -v19, v248, v62
	v_fma_f32 v63, -v16, v249, v63
	v_fma_f32 v62, -v17, v250, v62
	v_fma_f32 v63, -v14, v251, v63
	s_waitcnt lgkmcnt(0)
	v_fma_f32 v62, -v15, v252, v62
	v_fma_f32 v63, -v12, v253, v63
	v_fma_f32 v62, -v13, v254, v62
	v_add_f32_e32 v62, v63, v62
	s_and_saveexec_b64 s[2:3], s[38:39]
	s_xor_b64 s[2:3], exec, s[2:3]
	s_cbranch_execz .LBB0_657
	v_readlane_b32 s44, v246, 41
	s_lshl_b64 s[4:5], s[42:43], 1
	v_readlane_b32 s52, v246, 49
	v_readlane_b32 s53, v246, 50
	s_add_u32 s4, s52, s4
	v_cvt_pk_bf16_f32 v0, v79, v0
	v_cvt_pk_bf16_f32 v1, v1, v2
	v_cvt_pk_bf16_f32 v2, v3, v4
	v_cvt_pk_bf16_f32 v3, v5, v7
	s_addc_u32 s5, s53, s5
	v_lshlrev_b32_e32 v4, 7, v75
	global_store_dwordx4 v4, v[0:3], s[4:5]
	v_readlane_b32 s45, v246, 42
	v_readlane_b32 s46, v246, 43
	v_cvt_pk_bf16_f32 v0, v6, v8
	v_cvt_pk_bf16_f32 v1, v9, v10
	v_cvt_pk_bf16_f32 v2, v11, v60
	v_cvt_pk_bf16_f32 v3, v61, v58
	global_store_dwordx4 v4, v[0:3], s[4:5] offset:16
	v_readlane_b32 s47, v246, 44
	v_readlane_b32 s48, v246, 45
	v_cvt_pk_bf16_f32 v0, v59, v56
	v_cvt_pk_bf16_f32 v1, v57, v54
	v_cvt_pk_bf16_f32 v2, v55, v52
	v_cvt_pk_bf16_f32 v3, v53, v50
	global_store_dwordx4 v4, v[0:3], s[4:5] offset:32
	v_readlane_b32 s49, v246, 46
	v_readlane_b32 s50, v246, 47
	v_cvt_pk_bf16_f32 v0, v51, v48
	v_cvt_pk_bf16_f32 v1, v49, v46
	v_cvt_pk_bf16_f32 v2, v47, v44
	v_cvt_pk_bf16_f32 v3, v45, v42
	global_store_dwordx4 v4, v[0:3], s[4:5] offset:48
	v_readlane_b32 s51, v246, 48
	v_readlane_b32 s54, v246, 51
	v_cvt_pk_bf16_f32 v0, v43, v40
	v_cvt_pk_bf16_f32 v1, v41, v38
	v_cvt_pk_bf16_f32 v2, v39, v36
	v_cvt_pk_bf16_f32 v3, v37, v34
	global_store_dwordx4 v4, v[0:3], s[4:5] offset:64
	v_readlane_b32 s55, v246, 52
	v_readlane_b32 s56, v246, 53
	v_cvt_pk_bf16_f32 v0, v35, v32
	v_cvt_pk_bf16_f32 v1, v33, v30
	v_cvt_pk_bf16_f32 v2, v31, v28
	v_cvt_pk_bf16_f32 v3, v29, v26
	global_store_dwordx4 v4, v[0:3], s[4:5] offset:80
	v_readlane_b32 s57, v246, 54
	v_readlane_b32 s58, v246, 55
	v_cvt_pk_bf16_f32 v0, v27, v24
	v_cvt_pk_bf16_f32 v1, v25, v22
	v_cvt_pk_bf16_f32 v2, v23, v20
	v_cvt_pk_bf16_f32 v3, v21, v18
	global_store_dwordx4 v4, v[0:3], s[4:5] offset:96
	v_readlane_b32 s59, v246, 56
	s_nop 0
	v_cvt_pk_bf16_f32 v0, v19, v16
	v_cvt_pk_bf16_f32 v1, v17, v14
	v_cvt_pk_bf16_f32 v2, v15, v12
	v_cvt_pk_bf16_f32 v3, v13, v62
	global_store_dwordx4 v4, v[0:3], s[4:5] offset:112
